# static priority strategy step 1: removed the 160 per-segment s_setprio 1/0 toggles in all GEMM phases (all waves at equal priority there)
# baseline (speedup 1.0000x reference)
.LBB0_135:
	s_add_i32 s58, s26, 2
	s_add_u32 s27, s24, 0xfff80080
	s_addc_u32 s28, s25, -1
	s_add_i32 s59, 0, 0x10000
	s_cmp_eq_u32 s43, s26
	s_cselect_b32 s29, s17, s28
	s_cselect_b32 s28, s19, s27
	v_add_u32_e32 v161, s59, v140
	s_cselect_b32 s27, s49, s57
	s_cselect_b32 s26, s50, s56
	s_add_i32 s67, 0, 0x14000
	ds_read_b128 v[142:145], v161
	ds_read_b128 v[146:149], v161 offset:1024
	ds_read_b128 v[150:153], v161 offset:2048
	ds_read_b128 v[162:165], v161 offset:3072
	v_add_u32_e32 v161, s67, v140
	ds_read_b128 v[166:169], v161
	ds_read_b128 v[170:173], v161 offset:1024
	ds_read_b128 v[174:177], v161 offset:2048
	ds_read_b128 v[178:181], v161 offset:3072
	v_lshl_add_u64 v[190:191], s[24:25], 0, v[136:137]
	s_add_i32 m0, s15, 0xc000
	ds_read_b128 v[182:185], v141
	ds_read_b128 v[186:189], v141 offset:1024
	ds_read_b128 v[220:223], v141 offset:2048
	ds_read_b128 v[224:227], v141 offset:3072
	ds_read_b128 v[228:231], v141 offset:4096
	ds_read_b128 v[232:235], v141 offset:5120
	ds_read_b128 v[236:239], v141 offset:6144
	ds_read_b128 v[240:243], v141 offset:7168
	global_load_lds_dwordx4 v[190:191], off
	v_lshl_add_u64 v[190:191], s[24:25], 0, v[138:139]
	s_add_i32 m0, s15, 0xe000
	s_nop 0
	global_load_lds_dwordx4 v[190:191], off
	s_waitcnt vmcnt(8)
	s_waitcnt lgkmcnt(0)
	s_barrier
	s_waitcnt lgkmcnt(0)
	v_mfma_f32_16x16x32_bf16 v[122:125], v[142:145], v[182:185], v[122:125]
	v_mfma_f32_16x16x32_bf16 v[126:129], v[150:153], v[182:185], v[126:129]
	v_mfma_f32_16x16x32_bf16 v[110:113], v[142:145], v[220:223], v[110:113]
	v_mfma_f32_16x16x32_bf16 v[106:109], v[150:153], v[220:223], v[106:109]
	v_mfma_f32_16x16x32_bf16 v[94:97], v[142:145], v[228:231], v[94:97]
	v_mfma_f32_16x16x32_bf16 v[90:93], v[150:153], v[228:231], v[90:93]
	v_mfma_f32_16x16x32_bf16 v[78:81], v[142:145], v[236:239], v[78:81]
	v_mfma_f32_16x16x32_bf16 v[74:77], v[150:153], v[236:239], v[74:77]
	v_mfma_f32_16x16x32_bf16 v[122:125], v[146:149], v[186:189], v[122:125]
	v_mfma_f32_16x16x32_bf16 v[126:129], v[162:165], v[186:189], v[126:129]
	v_mfma_f32_16x16x32_bf16 v[110:113], v[146:149], v[224:227], v[110:113]
	v_mfma_f32_16x16x32_bf16 v[106:109], v[162:165], v[224:227], v[106:109]
	v_mfma_f32_16x16x32_bf16 v[94:97], v[146:149], v[232:235], v[94:97]
	v_mfma_f32_16x16x32_bf16 v[90:93], v[162:165], v[232:235], v[90:93]
	v_mfma_f32_16x16x32_bf16 v[78:81], v[146:149], v[240:243], v[78:81]
	v_mfma_f32_16x16x32_bf16 v[74:77], v[162:165], v[240:243], v[74:77]
	v_mfma_f32_16x16x32_bf16 v[118:121], v[166:169], v[182:185], v[118:121]
	v_mfma_f32_16x16x32_bf16 v[114:117], v[174:177], v[182:185], v[114:117]
	v_mfma_f32_16x16x32_bf16 v[102:105], v[166:169], v[220:223], v[102:105]
	v_mfma_f32_16x16x32_bf16 v[98:101], v[174:177], v[220:223], v[98:101]
	v_mfma_f32_16x16x32_bf16 v[86:89], v[166:169], v[228:231], v[86:89]
	v_mfma_f32_16x16x32_bf16 v[82:85], v[174:177], v[228:231], v[82:85]
	v_mfma_f32_16x16x32_bf16 v[70:73], v[166:169], v[236:239], v[70:73]
	v_mfma_f32_16x16x32_bf16 v[66:69], v[174:177], v[236:239], v[66:69]
	v_mfma_f32_16x16x32_bf16 v[118:121], v[170:173], v[186:189], v[118:121]
	v_mfma_f32_16x16x32_bf16 v[114:117], v[178:181], v[186:189], v[114:117]
	v_mfma_f32_16x16x32_bf16 v[102:105], v[170:173], v[224:227], v[102:105]
	v_mfma_f32_16x16x32_bf16 v[98:101], v[178:181], v[224:227], v[98:101]
	v_mfma_f32_16x16x32_bf16 v[86:89], v[170:173], v[232:235], v[86:89]
	v_mfma_f32_16x16x32_bf16 v[82:85], v[178:181], v[232:235], v[82:85]
	v_mfma_f32_16x16x32_bf16 v[70:73], v[170:173], v[240:243], v[70:73]
	v_mfma_f32_16x16x32_bf16 v[66:69], v[178:181], v[240:243], v[66:69]
	s_barrier
	s_add_i32 s59, s59, s34
	v_lshl_add_u64 v[190:191], s[26:27], 0, v[0:1]
	s_mov_b32 m0, s59
	ds_read_b128 v[182:185], v141 offset:16384
	ds_read_b128 v[186:189], v141 offset:17408
	ds_read_b128 v[220:223], v141 offset:18432
	ds_read_b128 v[224:227], v141 offset:19456
	ds_read_b128 v[228:231], v141 offset:20480
	ds_read_b128 v[232:235], v141 offset:21504
	ds_read_b128 v[236:239], v141 offset:22528
	ds_read_b128 v[240:243], v141 offset:23552
	global_load_lds_dwordx4 v[190:191], off
	s_add_i32 m0, s59, 0x2000
	s_add_u32 s62, s26, 0x80000
	v_lshl_add_u64 v[244:245], s[26:27], 0, v[134:135]
	s_addc_u32 s63, s27, 0
	s_add_i32 s59, s67, s34
	global_load_lds_dwordx4 v[244:245], off
	v_lshl_add_u64 v[246:247], s[62:63], 0, v[0:1]
	s_mov_b32 m0, s59
	v_lshl_add_u64 v[248:249], s[28:29], 0, v[132:133]
	global_load_lds_dwordx4 v[246:247], off
	v_lshl_add_u64 v[246:247], s[62:63], 0, v[134:135]
	s_add_i32 m0, s59, 0x2000
	s_nop 0
	global_load_lds_dwordx4 v[246:247], off
	v_lshl_add_u64 v[246:247], s[28:29], 0, v[130:131]
	s_mov_b32 m0, s15
	s_nop 0
	global_load_lds_dwordx4 v[246:247], off
	s_mov_b32 m0, s35
	s_nop 0
	global_load_lds_dwordx4 v[248:249], off
	s_waitcnt vmcnt(8)
	s_waitcnt lgkmcnt(0)
	s_barrier
	s_waitcnt lgkmcnt(0)
	v_mfma_f32_16x16x32_bf16 v[62:65], v[142:145], v[182:185], v[62:65]
	v_mfma_f32_16x16x32_bf16 v[58:61], v[150:153], v[182:185], v[58:61]
	v_mfma_f32_16x16x32_bf16 v[46:49], v[142:145], v[220:223], v[46:49]
	v_mfma_f32_16x16x32_bf16 v[42:45], v[150:153], v[220:223], v[42:45]
	v_mfma_f32_16x16x32_bf16 v[30:33], v[142:145], v[228:231], v[30:33]
	v_mfma_f32_16x16x32_bf16 v[26:29], v[150:153], v[228:231], v[26:29]
	v_mfma_f32_16x16x32_bf16 v[14:17], v[142:145], v[236:239], v[14:17]
	v_mfma_f32_16x16x32_bf16 v[10:13], v[150:153], v[236:239], v[10:13]
	v_mfma_f32_16x16x32_bf16 v[62:65], v[146:149], v[186:189], v[62:65]
	v_mfma_f32_16x16x32_bf16 v[58:61], v[162:165], v[186:189], v[58:61]
	v_mfma_f32_16x16x32_bf16 v[46:49], v[146:149], v[224:227], v[46:49]
	v_mfma_f32_16x16x32_bf16 v[42:45], v[162:165], v[224:227], v[42:45]
	v_mfma_f32_16x16x32_bf16 v[30:33], v[146:149], v[232:235], v[30:33]
	v_mfma_f32_16x16x32_bf16 v[26:29], v[162:165], v[232:235], v[26:29]
	v_mfma_f32_16x16x32_bf16 v[14:17], v[146:149], v[240:243], v[14:17]
	v_mfma_f32_16x16x32_bf16 v[10:13], v[162:165], v[240:243], v[10:13]
	v_mfma_f32_16x16x32_bf16 v[54:57], v[166:169], v[182:185], v[54:57]
	v_mfma_f32_16x16x32_bf16 v[50:53], v[174:177], v[182:185], v[50:53]
	v_mfma_f32_16x16x32_bf16 v[38:41], v[166:169], v[220:223], v[38:41]
	v_mfma_f32_16x16x32_bf16 v[34:37], v[174:177], v[220:223], v[34:37]
	v_mfma_f32_16x16x32_bf16 v[22:25], v[166:169], v[228:231], v[22:25]
	v_mfma_f32_16x16x32_bf16 v[18:21], v[174:177], v[228:231], v[18:21]
	v_mfma_f32_16x16x32_bf16 v[6:9], v[166:169], v[236:239], v[6:9]
	v_mfma_f32_16x16x32_bf16 v[2:5], v[174:177], v[236:239], v[2:5]
	v_mfma_f32_16x16x32_bf16 v[54:57], v[170:173], v[186:189], v[54:57]
	v_mfma_f32_16x16x32_bf16 v[50:53], v[178:181], v[186:189], v[50:53]
	v_mfma_f32_16x16x32_bf16 v[38:41], v[170:173], v[224:227], v[38:41]
	v_mfma_f32_16x16x32_bf16 v[34:37], v[178:181], v[224:227], v[34:37]
	v_mfma_f32_16x16x32_bf16 v[22:25], v[170:173], v[232:235], v[22:25]
	v_mfma_f32_16x16x32_bf16 v[18:21], v[178:181], v[232:235], v[18:21]
	v_mfma_f32_16x16x32_bf16 v[6:9], v[170:173], v[240:243], v[6:9]
	v_mfma_f32_16x16x32_bf16 v[2:5], v[178:181], v[240:243], v[2:5]
	s_barrier
	s_add_i32 s59, 0, 0x18000
	v_add_u32_e32 v161, s59, v140
	s_add_i32 s62, 0, 0x1c000
	ds_read_b128 v[142:145], v161
	ds_read_b128 v[146:149], v161 offset:1024
	ds_read_b128 v[150:153], v161 offset:2048
	ds_read_b128 v[162:165], v161 offset:3072
	v_add_u32_e32 v161, s62, v140
	ds_read_b128 v[166:169], v161
	ds_read_b128 v[170:173], v161 offset:1024
	ds_read_b128 v[174:177], v161 offset:2048
	ds_read_b128 v[178:181], v161 offset:3072
	s_add_u32 s28, s28, 0x80000
	s_addc_u32 s29, s29, 0
	s_mov_b32 m0, s36
	v_lshl_add_u64 v[250:251], s[28:29], 0, v[130:131]
	ds_read_b128 v[182:185], v141 offset:32768
	ds_read_b128 v[186:189], v141 offset:33792
	ds_read_b128 v[220:223], v141 offset:34816
	ds_read_b128 v[224:227], v141 offset:35840
	ds_read_b128 v[228:231], v141 offset:36864
	ds_read_b128 v[232:235], v141 offset:37888
	ds_read_b128 v[236:239], v141 offset:38912
	ds_read_b128 v[240:243], v141 offset:39936
	global_load_lds_dwordx4 v[250:251], off
	v_lshl_add_u64 v[250:251], s[28:29], 0, v[132:133]
	s_mov_b32 m0, s37
	s_nop 0
	global_load_lds_dwordx4 v[250:251], off
	s_waitcnt vmcnt(8)
	s_waitcnt lgkmcnt(0)
	s_barrier
	s_waitcnt lgkmcnt(0)
	v_mfma_f32_16x16x32_bf16 v[122:125], v[142:145], v[182:185], v[122:125]
	v_mfma_f32_16x16x32_bf16 v[126:129], v[150:153], v[182:185], v[126:129]
	v_mfma_f32_16x16x32_bf16 v[110:113], v[142:145], v[220:223], v[110:113]
	v_mfma_f32_16x16x32_bf16 v[106:109], v[150:153], v[220:223], v[106:109]
	v_mfma_f32_16x16x32_bf16 v[94:97], v[142:145], v[228:231], v[94:97]
	v_mfma_f32_16x16x32_bf16 v[90:93], v[150:153], v[228:231], v[90:93]
	v_mfma_f32_16x16x32_bf16 v[78:81], v[142:145], v[236:239], v[78:81]
	v_mfma_f32_16x16x32_bf16 v[74:77], v[150:153], v[236:239], v[74:77]
	v_mfma_f32_16x16x32_bf16 v[122:125], v[146:149], v[186:189], v[122:125]
	v_mfma_f32_16x16x32_bf16 v[126:129], v[162:165], v[186:189], v[126:129]
	v_mfma_f32_16x16x32_bf16 v[110:113], v[146:149], v[224:227], v[110:113]
	v_mfma_f32_16x16x32_bf16 v[106:109], v[162:165], v[224:227], v[106:109]
	v_mfma_f32_16x16x32_bf16 v[94:97], v[146:149], v[232:235], v[94:97]
	v_mfma_f32_16x16x32_bf16 v[90:93], v[162:165], v[232:235], v[90:93]
	v_mfma_f32_16x16x32_bf16 v[78:81], v[146:149], v[240:243], v[78:81]
	v_mfma_f32_16x16x32_bf16 v[74:77], v[162:165], v[240:243], v[74:77]
	v_mfma_f32_16x16x32_bf16 v[118:121], v[166:169], v[182:185], v[118:121]
	v_mfma_f32_16x16x32_bf16 v[114:117], v[174:177], v[182:185], v[114:117]
	v_mfma_f32_16x16x32_bf16 v[102:105], v[166:169], v[220:223], v[102:105]
	v_mfma_f32_16x16x32_bf16 v[98:101], v[174:177], v[220:223], v[98:101]
	v_mfma_f32_16x16x32_bf16 v[86:89], v[166:169], v[228:231], v[86:89]
	v_mfma_f32_16x16x32_bf16 v[82:85], v[174:177], v[228:231], v[82:85]
	v_mfma_f32_16x16x32_bf16 v[70:73], v[166:169], v[236:239], v[70:73]
	v_mfma_f32_16x16x32_bf16 v[66:69], v[174:177], v[236:239], v[66:69]
	v_mfma_f32_16x16x32_bf16 v[118:121], v[170:173], v[186:189], v[118:121]
	v_mfma_f32_16x16x32_bf16 v[114:117], v[178:181], v[186:189], v[114:117]
	v_mfma_f32_16x16x32_bf16 v[102:105], v[170:173], v[224:227], v[102:105]
	v_mfma_f32_16x16x32_bf16 v[98:101], v[178:181], v[224:227], v[98:101]
	v_mfma_f32_16x16x32_bf16 v[86:89], v[170:173], v[232:235], v[86:89]
	v_mfma_f32_16x16x32_bf16 v[82:85], v[178:181], v[232:235], v[82:85]
	v_mfma_f32_16x16x32_bf16 v[70:73], v[170:173], v[240:243], v[70:73]
	v_mfma_f32_16x16x32_bf16 v[66:69], v[178:181], v[240:243], v[66:69]
	s_barrier
	s_add_i32 s28, s59, s34
	v_lshl_add_u64 v[190:191], v[190:191], 0, s[72:73]
	s_mov_b32 m0, s28
	ds_read_b128 v[182:185], v141 offset:49152
	ds_read_b128 v[186:189], v141 offset:50176
	ds_read_b128 v[220:223], v141 offset:51200
	ds_read_b128 v[224:227], v141 offset:52224
	ds_read_b128 v[228:231], v141 offset:53248
	ds_read_b128 v[232:235], v141 offset:54272
	ds_read_b128 v[236:239], v141 offset:55296
	ds_read_b128 v[240:243], v141 offset:56320
	global_load_lds_dwordx4 v[190:191], off
	s_add_i32 m0, s28, 0x2000
	s_add_u32 s26, s26, 0x80080
	v_lshl_add_u64 v[190:191], v[244:245], 0, s[72:73]
	s_addc_u32 s27, s27, 0
	s_add_i32 s28, s62, s34
	global_load_lds_dwordx4 v[190:191], off
	v_lshl_add_u64 v[190:191], s[26:27], 0, v[0:1]
	s_mov_b32 m0, s28
	s_nop 0
	global_load_lds_dwordx4 v[190:191], off
	v_lshl_add_u64 v[190:191], s[26:27], 0, v[134:135]
	s_add_i32 m0, s28, 0x2000
	s_nop 0
	global_load_lds_dwordx4 v[190:191], off
	v_lshl_add_u64 v[190:191], v[246:247], 0, s[72:73]
	s_mov_b32 m0, s41
	s_nop 0
	global_load_lds_dwordx4 v[190:191], off
	v_lshl_add_u64 v[190:191], v[248:249], 0, s[72:73]
	s_mov_b32 m0, s42
	s_nop 0
	global_load_lds_dwordx4 v[190:191], off
	s_waitcnt vmcnt(8)
	s_waitcnt lgkmcnt(0)
	s_barrier
	s_waitcnt lgkmcnt(0)
	v_mfma_f32_16x16x32_bf16 v[62:65], v[142:145], v[182:185], v[62:65]
	v_mfma_f32_16x16x32_bf16 v[58:61], v[150:153], v[182:185], v[58:61]
	v_mfma_f32_16x16x32_bf16 v[46:49], v[142:145], v[220:223], v[46:49]
	v_mfma_f32_16x16x32_bf16 v[42:45], v[150:153], v[220:223], v[42:45]
	v_mfma_f32_16x16x32_bf16 v[30:33], v[142:145], v[228:231], v[30:33]
	v_mfma_f32_16x16x32_bf16 v[26:29], v[150:153], v[228:231], v[26:29]
	v_mfma_f32_16x16x32_bf16 v[14:17], v[142:145], v[236:239], v[14:17]
	v_mfma_f32_16x16x32_bf16 v[10:13], v[150:153], v[236:239], v[10:13]
	v_mfma_f32_16x16x32_bf16 v[62:65], v[146:149], v[186:189], v[62:65]
	v_mfma_f32_16x16x32_bf16 v[58:61], v[162:165], v[186:189], v[58:61]
	v_mfma_f32_16x16x32_bf16 v[46:49], v[146:149], v[224:227], v[46:49]
	v_mfma_f32_16x16x32_bf16 v[42:45], v[162:165], v[224:227], v[42:45]
	v_mfma_f32_16x16x32_bf16 v[30:33], v[146:149], v[232:235], v[30:33]
	v_mfma_f32_16x16x32_bf16 v[26:29], v[162:165], v[232:235], v[26:29]
	v_mfma_f32_16x16x32_bf16 v[14:17], v[146:149], v[240:243], v[14:17]
	v_mfma_f32_16x16x32_bf16 v[10:13], v[162:165], v[240:243], v[10:13]
	v_mfma_f32_16x16x32_bf16 v[54:57], v[166:169], v[182:185], v[54:57]
	v_mfma_f32_16x16x32_bf16 v[50:53], v[174:177], v[182:185], v[50:53]
	v_mfma_f32_16x16x32_bf16 v[38:41], v[166:169], v[220:223], v[38:41]
	v_mfma_f32_16x16x32_bf16 v[34:37], v[174:177], v[220:223], v[34:37]
	v_mfma_f32_16x16x32_bf16 v[22:25], v[166:169], v[228:231], v[22:25]
	v_mfma_f32_16x16x32_bf16 v[18:21], v[174:177], v[228:231], v[18:21]
	v_mfma_f32_16x16x32_bf16 v[6:9], v[166:169], v[236:239], v[6:9]
	v_mfma_f32_16x16x32_bf16 v[2:5], v[174:177], v[236:239], v[2:5]
	v_mfma_f32_16x16x32_bf16 v[54:57], v[170:173], v[186:189], v[54:57]
	v_mfma_f32_16x16x32_bf16 v[50:53], v[178:181], v[186:189], v[50:53]
	v_mfma_f32_16x16x32_bf16 v[38:41], v[170:173], v[224:227], v[38:41]
	v_mfma_f32_16x16x32_bf16 v[34:37], v[178:181], v[224:227], v[34:37]
	v_mfma_f32_16x16x32_bf16 v[22:25], v[170:173], v[232:235], v[22:25]
	v_mfma_f32_16x16x32_bf16 v[18:21], v[178:181], v[232:235], v[18:21]
	v_mfma_f32_16x16x32_bf16 v[6:9], v[170:173], v[240:243], v[6:9]
	v_mfma_f32_16x16x32_bf16 v[2:5], v[178:181], v[240:243], v[2:5]
	s_barrier
	s_add_u32 s24, s24, 0x100
	s_addc_u32 s25, s25, 0
	s_add_u32 s56, s56, 0x100
	s_addc_u32 s57, s57, 0
	s_cmp_ge_i32 s58, s38
	s_mov_b32 s26, s58
	s_cbranch_scc0 .LBB0_135
	s_mov_b32 s63, 0x8000
	s_movk_i32 s67, 0x1800

.LBB0_267:
	s_add_i32 s49, s34, 2
	s_add_u32 s35, s30, 0xfffc0080
	s_addc_u32 s36, s31, -1
	s_add_i32 s50, 0, 0x10000
	s_cmp_eq_u32 s70, s34
	s_cselect_b32 s37, s3, s36
	s_cselect_b32 s36, s7, s35
	v_add_u32_e32 v0, s50, v161
	s_cselect_b32 s35, s9, s48
	s_cselect_b32 s34, s23, s25
	s_add_i32 s62, 0, 0x14000
	ds_read_b128 v[130:133], v0
	ds_read_b128 v[146:149], v0 offset:1024
	ds_read_b128 v[150:153], v0 offset:2048
	ds_read_b128 v[162:165], v0 offset:3072
	v_add_u32_e32 v0, s62, v161
	ds_read_b128 v[166:169], v0
	ds_read_b128 v[170:173], v0 offset:1024
	ds_read_b128 v[174:177], v0 offset:2048
	ds_read_b128 v[178:181], v0 offset:3072
	v_lshl_add_u64 v[246:247], s[30:31], 0, v[142:143]
	s_add_i32 m0, s40, 0xc000
	ds_read_b128 v[182:185], v220
	ds_read_b128 v[186:189], v220 offset:1024
	ds_read_b128 v[222:225], v220 offset:2048
	ds_read_b128 v[226:229], v220 offset:3072
	ds_read_b128 v[230:233], v220 offset:4096
	ds_read_b128 v[234:237], v220 offset:5120
	ds_read_b128 v[238:241], v220 offset:6144
	ds_read_b128 v[242:245], v220 offset:7168
	global_load_lds_dwordx4 v[246:247], off
	v_lshl_add_u64 v[246:247], s[30:31], 0, v[144:145]
	s_add_i32 m0, s40, 0xe000
	s_nop 0
	global_load_lds_dwordx4 v[246:247], off
	s_waitcnt vmcnt(8)
	s_waitcnt lgkmcnt(0)
	s_barrier
	s_waitcnt lgkmcnt(0)
	v_mfma_f32_16x16x32_bf16 v[126:129], v[130:133], v[182:185], v[126:129]
	v_mfma_f32_16x16x32_bf16 v[122:125], v[150:153], v[182:185], v[122:125]
	v_mfma_f32_16x16x32_bf16 v[110:113], v[130:133], v[222:225], v[110:113]
	v_mfma_f32_16x16x32_bf16 v[106:109], v[150:153], v[222:225], v[106:109]
	v_mfma_f32_16x16x32_bf16 v[94:97], v[130:133], v[230:233], v[94:97]
	v_mfma_f32_16x16x32_bf16 v[90:93], v[150:153], v[230:233], v[90:93]
	v_mfma_f32_16x16x32_bf16 v[78:81], v[130:133], v[238:241], v[78:81]
	v_mfma_f32_16x16x32_bf16 v[74:77], v[150:153], v[238:241], v[74:77]
	v_mfma_f32_16x16x32_bf16 v[126:129], v[146:149], v[186:189], v[126:129]
	v_mfma_f32_16x16x32_bf16 v[122:125], v[162:165], v[186:189], v[122:125]
	v_mfma_f32_16x16x32_bf16 v[110:113], v[146:149], v[226:229], v[110:113]
	v_mfma_f32_16x16x32_bf16 v[106:109], v[162:165], v[226:229], v[106:109]
	v_mfma_f32_16x16x32_bf16 v[94:97], v[146:149], v[234:237], v[94:97]
	v_mfma_f32_16x16x32_bf16 v[90:93], v[162:165], v[234:237], v[90:93]
	v_mfma_f32_16x16x32_bf16 v[78:81], v[146:149], v[242:245], v[78:81]
	v_mfma_f32_16x16x32_bf16 v[74:77], v[162:165], v[242:245], v[74:77]
	v_mfma_f32_16x16x32_bf16 v[118:121], v[166:169], v[182:185], v[118:121]
	v_mfma_f32_16x16x32_bf16 v[114:117], v[174:177], v[182:185], v[114:117]
	v_mfma_f32_16x16x32_bf16 v[102:105], v[166:169], v[222:225], v[102:105]
	v_mfma_f32_16x16x32_bf16 v[98:101], v[174:177], v[222:225], v[98:101]
	v_mfma_f32_16x16x32_bf16 v[86:89], v[166:169], v[230:233], v[86:89]
	v_mfma_f32_16x16x32_bf16 v[82:85], v[174:177], v[230:233], v[82:85]
	v_mfma_f32_16x16x32_bf16 v[70:73], v[166:169], v[238:241], v[70:73]
	v_mfma_f32_16x16x32_bf16 v[66:69], v[174:177], v[238:241], v[66:69]
	v_mfma_f32_16x16x32_bf16 v[118:121], v[170:173], v[186:189], v[118:121]
	v_mfma_f32_16x16x32_bf16 v[114:117], v[178:181], v[186:189], v[114:117]
	v_mfma_f32_16x16x32_bf16 v[102:105], v[170:173], v[226:229], v[102:105]
	v_mfma_f32_16x16x32_bf16 v[98:101], v[178:181], v[226:229], v[98:101]
	v_mfma_f32_16x16x32_bf16 v[86:89], v[170:173], v[234:237], v[86:89]
	v_mfma_f32_16x16x32_bf16 v[82:85], v[178:181], v[234:237], v[82:85]
	v_mfma_f32_16x16x32_bf16 v[70:73], v[170:173], v[242:245], v[70:73]
	v_mfma_f32_16x16x32_bf16 v[66:69], v[178:181], v[242:245], v[66:69]
	s_barrier
	s_add_i32 s50, s50, s39
	v_lshl_add_u64 v[246:247], s[34:35], 0, v[136:137]
	s_mov_b32 m0, s50
	ds_read_b128 v[182:185], v220 offset:16384
	ds_read_b128 v[186:189], v220 offset:17408
	ds_read_b128 v[222:225], v220 offset:18432
	ds_read_b128 v[226:229], v220 offset:19456
	ds_read_b128 v[230:233], v220 offset:20480
	ds_read_b128 v[234:237], v220 offset:21504
	ds_read_b128 v[238:241], v220 offset:22528
	ds_read_b128 v[242:245], v220 offset:23552
	global_load_lds_dwordx4 v[246:247], off
	s_add_i32 m0, s50, 0x2000
	s_add_u32 s78, s34, 0x40000
	v_lshl_add_u64 v[248:249], s[34:35], 0, v[140:141]
	s_addc_u32 s79, s35, 0
	s_add_i32 s50, s62, s39
	global_load_lds_dwordx4 v[248:249], off
	v_lshl_add_u64 v[250:251], s[78:79], 0, v[136:137]
	s_mov_b32 m0, s50
	v_lshl_add_u64 v[252:253], s[36:37], 0, v[138:139]
	global_load_lds_dwordx4 v[250:251], off
	v_lshl_add_u64 v[250:251], s[78:79], 0, v[140:141]
	s_add_i32 m0, s50, 0x2000
	s_nop 0
	global_load_lds_dwordx4 v[250:251], off
	v_lshl_add_u64 v[250:251], s[36:37], 0, v[134:135]
	s_mov_b32 m0, s40
	s_nop 0
	global_load_lds_dwordx4 v[250:251], off
	s_mov_b32 m0, s41
	s_nop 0
	global_load_lds_dwordx4 v[252:253], off
	s_waitcnt vmcnt(8)
	s_waitcnt lgkmcnt(0)
	s_barrier
	s_waitcnt lgkmcnt(0)
	v_mfma_f32_16x16x32_bf16 v[62:65], v[130:133], v[182:185], v[62:65]
	v_mfma_f32_16x16x32_bf16 v[58:61], v[150:153], v[182:185], v[58:61]
	v_mfma_f32_16x16x32_bf16 v[46:49], v[130:133], v[222:225], v[46:49]
	v_mfma_f32_16x16x32_bf16 v[42:45], v[150:153], v[222:225], v[42:45]
	v_mfma_f32_16x16x32_bf16 v[30:33], v[130:133], v[230:233], v[30:33]
	v_mfma_f32_16x16x32_bf16 v[26:29], v[150:153], v[230:233], v[26:29]
	v_mfma_f32_16x16x32_bf16 v[14:17], v[130:133], v[238:241], v[14:17]
	v_mfma_f32_16x16x32_bf16 v[10:13], v[150:153], v[238:241], v[10:13]
	v_mfma_f32_16x16x32_bf16 v[62:65], v[146:149], v[186:189], v[62:65]
	v_mfma_f32_16x16x32_bf16 v[58:61], v[162:165], v[186:189], v[58:61]
	v_mfma_f32_16x16x32_bf16 v[46:49], v[146:149], v[226:229], v[46:49]
	v_mfma_f32_16x16x32_bf16 v[42:45], v[162:165], v[226:229], v[42:45]
	v_mfma_f32_16x16x32_bf16 v[30:33], v[146:149], v[234:237], v[30:33]
	v_mfma_f32_16x16x32_bf16 v[26:29], v[162:165], v[234:237], v[26:29]
	v_mfma_f32_16x16x32_bf16 v[14:17], v[146:149], v[242:245], v[14:17]
	v_mfma_f32_16x16x32_bf16 v[10:13], v[162:165], v[242:245], v[10:13]
	v_mfma_f32_16x16x32_bf16 v[54:57], v[166:169], v[182:185], v[54:57]
	v_mfma_f32_16x16x32_bf16 v[50:53], v[174:177], v[182:185], v[50:53]
	v_mfma_f32_16x16x32_bf16 v[38:41], v[166:169], v[222:225], v[38:41]
	v_mfma_f32_16x16x32_bf16 v[34:37], v[174:177], v[222:225], v[34:37]
	v_mfma_f32_16x16x32_bf16 v[22:25], v[166:169], v[230:233], v[22:25]
	v_mfma_f32_16x16x32_bf16 v[18:21], v[174:177], v[230:233], v[18:21]
	v_mfma_f32_16x16x32_bf16 v[6:9], v[166:169], v[238:241], v[6:9]
	v_mfma_f32_16x16x32_bf16 v[2:5], v[174:177], v[238:241], v[2:5]
	v_mfma_f32_16x16x32_bf16 v[54:57], v[170:173], v[186:189], v[54:57]
	v_mfma_f32_16x16x32_bf16 v[50:53], v[178:181], v[186:189], v[50:53]
	v_mfma_f32_16x16x32_bf16 v[38:41], v[170:173], v[226:229], v[38:41]
	v_mfma_f32_16x16x32_bf16 v[34:37], v[178:181], v[226:229], v[34:37]
	v_mfma_f32_16x16x32_bf16 v[22:25], v[170:173], v[234:237], v[22:25]
	v_mfma_f32_16x16x32_bf16 v[18:21], v[178:181], v[234:237], v[18:21]
	v_mfma_f32_16x16x32_bf16 v[6:9], v[170:173], v[242:245], v[6:9]
	v_mfma_f32_16x16x32_bf16 v[2:5], v[178:181], v[242:245], v[2:5]
	s_barrier
	s_add_i32 s50, 0, 0x18000
	v_add_u32_e32 v0, s50, v161
	s_add_i32 s62, 0, 0x1c000
	ds_read_b128 v[130:133], v0
	ds_read_b128 v[146:149], v0 offset:1024
	ds_read_b128 v[150:153], v0 offset:2048
	ds_read_b128 v[162:165], v0 offset:3072
	v_add_u32_e32 v0, s62, v161
	ds_read_b128 v[166:169], v0
	ds_read_b128 v[170:173], v0 offset:1024
	ds_read_b128 v[174:177], v0 offset:2048
	ds_read_b128 v[178:181], v0 offset:3072
	s_add_u32 s36, s36, 0x40000
	s_addc_u32 s37, s37, 0
	s_mov_b32 m0, s42
	v_lshl_add_u64 v[190:191], s[36:37], 0, v[134:135]
	ds_read_b128 v[182:185], v220 offset:32768
	ds_read_b128 v[186:189], v220 offset:33792
	ds_read_b128 v[222:225], v220 offset:34816
	ds_read_b128 v[226:229], v220 offset:35840
	ds_read_b128 v[230:233], v220 offset:36864
	ds_read_b128 v[234:237], v220 offset:37888
	ds_read_b128 v[238:241], v220 offset:38912
	ds_read_b128 v[242:245], v220 offset:39936
	global_load_lds_dwordx4 v[190:191], off
	v_lshl_add_u64 v[190:191], s[36:37], 0, v[138:139]
	s_mov_b32 m0, s43
	s_nop 0
	global_load_lds_dwordx4 v[190:191], off
	s_waitcnt vmcnt(8)
	s_waitcnt lgkmcnt(0)
	s_barrier
	s_waitcnt lgkmcnt(0)
	v_mfma_f32_16x16x32_bf16 v[126:129], v[130:133], v[182:185], v[126:129]
	v_mfma_f32_16x16x32_bf16 v[122:125], v[150:153], v[182:185], v[122:125]
	v_mfma_f32_16x16x32_bf16 v[110:113], v[130:133], v[222:225], v[110:113]
	v_mfma_f32_16x16x32_bf16 v[106:109], v[150:153], v[222:225], v[106:109]
	v_mfma_f32_16x16x32_bf16 v[94:97], v[130:133], v[230:233], v[94:97]
	v_mfma_f32_16x16x32_bf16 v[90:93], v[150:153], v[230:233], v[90:93]
	v_mfma_f32_16x16x32_bf16 v[78:81], v[130:133], v[238:241], v[78:81]
	v_mfma_f32_16x16x32_bf16 v[74:77], v[150:153], v[238:241], v[74:77]
	v_mfma_f32_16x16x32_bf16 v[126:129], v[146:149], v[186:189], v[126:129]
	v_mfma_f32_16x16x32_bf16 v[122:125], v[162:165], v[186:189], v[122:125]
	v_mfma_f32_16x16x32_bf16 v[110:113], v[146:149], v[226:229], v[110:113]
	v_mfma_f32_16x16x32_bf16 v[106:109], v[162:165], v[226:229], v[106:109]
	v_mfma_f32_16x16x32_bf16 v[94:97], v[146:149], v[234:237], v[94:97]
	v_mfma_f32_16x16x32_bf16 v[90:93], v[162:165], v[234:237], v[90:93]
	v_mfma_f32_16x16x32_bf16 v[78:81], v[146:149], v[242:245], v[78:81]
	v_mfma_f32_16x16x32_bf16 v[74:77], v[162:165], v[242:245], v[74:77]
	v_mfma_f32_16x16x32_bf16 v[118:121], v[166:169], v[182:185], v[118:121]
	v_mfma_f32_16x16x32_bf16 v[114:117], v[174:177], v[182:185], v[114:117]
	v_mfma_f32_16x16x32_bf16 v[102:105], v[166:169], v[222:225], v[102:105]
	v_mfma_f32_16x16x32_bf16 v[98:101], v[174:177], v[222:225], v[98:101]
	v_mfma_f32_16x16x32_bf16 v[86:89], v[166:169], v[230:233], v[86:89]
	v_mfma_f32_16x16x32_bf16 v[82:85], v[174:177], v[230:233], v[82:85]
	v_mfma_f32_16x16x32_bf16 v[70:73], v[166:169], v[238:241], v[70:73]
	v_mfma_f32_16x16x32_bf16 v[66:69], v[174:177], v[238:241], v[66:69]
	v_mfma_f32_16x16x32_bf16 v[118:121], v[170:173], v[186:189], v[118:121]
	v_mfma_f32_16x16x32_bf16 v[114:117], v[178:181], v[186:189], v[114:117]
	v_mfma_f32_16x16x32_bf16 v[102:105], v[170:173], v[226:229], v[102:105]
	v_mfma_f32_16x16x32_bf16 v[98:101], v[178:181], v[226:229], v[98:101]
	v_mfma_f32_16x16x32_bf16 v[86:89], v[170:173], v[234:237], v[86:89]
	v_mfma_f32_16x16x32_bf16 v[82:85], v[178:181], v[234:237], v[82:85]
	v_mfma_f32_16x16x32_bf16 v[70:73], v[170:173], v[242:245], v[70:73]
	v_mfma_f32_16x16x32_bf16 v[66:69], v[178:181], v[242:245], v[66:69]
	s_barrier
	s_add_i32 s36, s50, s39
	v_lshl_add_u64 v[190:191], v[246:247], 0, s[72:73]
	s_mov_b32 m0, s36
	ds_read_b128 v[182:185], v220 offset:49152
	ds_read_b128 v[186:189], v220 offset:50176
	ds_read_b128 v[222:225], v220 offset:51200
	ds_read_b128 v[226:229], v220 offset:52224
	ds_read_b128 v[230:233], v220 offset:53248
	ds_read_b128 v[234:237], v220 offset:54272
	ds_read_b128 v[238:241], v220 offset:55296
	ds_read_b128 v[242:245], v220 offset:56320
	global_load_lds_dwordx4 v[190:191], off
	s_add_i32 m0, s36, 0x2000
	s_add_u32 s34, s34, 0x40080
	v_lshl_add_u64 v[190:191], v[248:249], 0, s[72:73]
	s_addc_u32 s35, s35, 0
	s_add_i32 s36, s62, s39
	global_load_lds_dwordx4 v[190:191], off
	v_lshl_add_u64 v[190:191], s[34:35], 0, v[136:137]
	s_mov_b32 m0, s36
	s_nop 0
	global_load_lds_dwordx4 v[190:191], off
	v_lshl_add_u64 v[190:191], s[34:35], 0, v[140:141]
	s_add_i32 m0, s36, 0x2000
	s_nop 0
	global_load_lds_dwordx4 v[190:191], off
	v_lshl_add_u64 v[190:191], v[250:251], 0, s[72:73]
	s_mov_b32 m0, s59
	s_nop 0
	global_load_lds_dwordx4 v[190:191], off
	v_lshl_add_u64 v[190:191], v[252:253], 0, s[72:73]
	s_mov_b32 m0, s67
	s_nop 0
	global_load_lds_dwordx4 v[190:191], off
	s_waitcnt vmcnt(8)
	s_waitcnt lgkmcnt(0)
	s_barrier
	s_waitcnt lgkmcnt(0)
	v_mfma_f32_16x16x32_bf16 v[62:65], v[130:133], v[182:185], v[62:65]
	v_mfma_f32_16x16x32_bf16 v[58:61], v[150:153], v[182:185], v[58:61]
	v_mfma_f32_16x16x32_bf16 v[46:49], v[130:133], v[222:225], v[46:49]
	v_mfma_f32_16x16x32_bf16 v[42:45], v[150:153], v[222:225], v[42:45]
	v_mfma_f32_16x16x32_bf16 v[30:33], v[130:133], v[230:233], v[30:33]
	v_mfma_f32_16x16x32_bf16 v[26:29], v[150:153], v[230:233], v[26:29]
	v_mfma_f32_16x16x32_bf16 v[14:17], v[130:133], v[238:241], v[14:17]
	v_mfma_f32_16x16x32_bf16 v[10:13], v[150:153], v[238:241], v[10:13]
	v_mfma_f32_16x16x32_bf16 v[62:65], v[146:149], v[186:189], v[62:65]
	v_mfma_f32_16x16x32_bf16 v[58:61], v[162:165], v[186:189], v[58:61]
	v_mfma_f32_16x16x32_bf16 v[46:49], v[146:149], v[226:229], v[46:49]
	v_mfma_f32_16x16x32_bf16 v[42:45], v[162:165], v[226:229], v[42:45]
	v_mfma_f32_16x16x32_bf16 v[30:33], v[146:149], v[234:237], v[30:33]
	v_mfma_f32_16x16x32_bf16 v[26:29], v[162:165], v[234:237], v[26:29]
	v_mfma_f32_16x16x32_bf16 v[14:17], v[146:149], v[242:245], v[14:17]
	v_mfma_f32_16x16x32_bf16 v[10:13], v[162:165], v[242:245], v[10:13]
	v_mfma_f32_16x16x32_bf16 v[54:57], v[166:169], v[182:185], v[54:57]
	v_mfma_f32_16x16x32_bf16 v[50:53], v[174:177], v[182:185], v[50:53]
	v_mfma_f32_16x16x32_bf16 v[38:41], v[166:169], v[222:225], v[38:41]
	v_mfma_f32_16x16x32_bf16 v[34:37], v[174:177], v[222:225], v[34:37]
	v_mfma_f32_16x16x32_bf16 v[22:25], v[166:169], v[230:233], v[22:25]
	v_mfma_f32_16x16x32_bf16 v[18:21], v[174:177], v[230:233], v[18:21]
	v_mfma_f32_16x16x32_bf16 v[6:9], v[166:169], v[238:241], v[6:9]
	v_mfma_f32_16x16x32_bf16 v[2:5], v[174:177], v[238:241], v[2:5]
	v_mfma_f32_16x16x32_bf16 v[54:57], v[170:173], v[186:189], v[54:57]
	v_mfma_f32_16x16x32_bf16 v[50:53], v[178:181], v[186:189], v[50:53]
	v_mfma_f32_16x16x32_bf16 v[38:41], v[170:173], v[226:229], v[38:41]
	v_mfma_f32_16x16x32_bf16 v[34:37], v[178:181], v[226:229], v[34:37]
	v_mfma_f32_16x16x32_bf16 v[22:25], v[170:173], v[234:237], v[22:25]
	v_mfma_f32_16x16x32_bf16 v[18:21], v[178:181], v[234:237], v[18:21]
	v_mfma_f32_16x16x32_bf16 v[6:9], v[170:173], v[242:245], v[6:9]
	v_mfma_f32_16x16x32_bf16 v[2:5], v[178:181], v[242:245], v[2:5]
	s_barrier
	s_add_u32 s30, s30, 0x100
	s_addc_u32 s31, s31, 0
	s_add_u32 s25, s25, 0x100
	s_addc_u32 s48, s48, 0
	s_cmp_ge_i32 s49, s56
	s_mov_b32 s34, s49
	s_cbranch_scc0 .LBB0_267

.LBB0_347:
	s_add_i32 s77, s34, 2
	s_add_u32 s35, s30, 0xfff80080
	s_addc_u32 s36, s31, -1
	s_add_i32 s63, 0, 0x10000
	s_cmp_eq_u32 s58, s34
	s_cselect_b32 s37, s23, s36
	s_cselect_b32 s36, s25, s35
	v_add_u32_e32 v161, s63, v140
	s_cselect_b32 s35, s70, s75
	s_cselect_b32 s34, s71, s74
	s_add_i32 s84, 0, 0x14000
	ds_read_b128 v[142:145], v161
	ds_read_b128 v[146:149], v161 offset:1024
	ds_read_b128 v[150:153], v161 offset:2048
	ds_read_b128 v[162:165], v161 offset:3072
	v_add_u32_e32 v161, s84, v140
	ds_read_b128 v[166:169], v161
	ds_read_b128 v[170:173], v161 offset:1024
	ds_read_b128 v[174:177], v161 offset:2048
	ds_read_b128 v[178:181], v161 offset:3072
	v_lshl_add_u64 v[190:191], s[30:31], 0, v[136:137]
	s_add_i32 m0, s21, 0xc000
	ds_read_b128 v[182:185], v141
	ds_read_b128 v[186:189], v141 offset:1024
	ds_read_b128 v[220:223], v141 offset:2048
	ds_read_b128 v[224:227], v141 offset:3072
	ds_read_b128 v[228:231], v141 offset:4096
	ds_read_b128 v[232:235], v141 offset:5120
	ds_read_b128 v[236:239], v141 offset:6144
	ds_read_b128 v[240:243], v141 offset:7168
	global_load_lds_dwordx4 v[190:191], off
	v_lshl_add_u64 v[190:191], s[30:31], 0, v[138:139]
	s_add_i32 m0, s21, 0xe000
	s_nop 0
	global_load_lds_dwordx4 v[190:191], off
	s_waitcnt vmcnt(8)
	s_waitcnt lgkmcnt(0)
	s_barrier
	s_waitcnt lgkmcnt(0)
	v_mfma_f32_16x16x32_bf16 v[122:125], v[142:145], v[182:185], v[122:125]
	v_mfma_f32_16x16x32_bf16 v[126:129], v[150:153], v[182:185], v[126:129]
	v_mfma_f32_16x16x32_bf16 v[110:113], v[142:145], v[220:223], v[110:113]
	v_mfma_f32_16x16x32_bf16 v[106:109], v[150:153], v[220:223], v[106:109]
	v_mfma_f32_16x16x32_bf16 v[94:97], v[142:145], v[228:231], v[94:97]
	v_mfma_f32_16x16x32_bf16 v[90:93], v[150:153], v[228:231], v[90:93]
	v_mfma_f32_16x16x32_bf16 v[78:81], v[142:145], v[236:239], v[78:81]
	v_mfma_f32_16x16x32_bf16 v[74:77], v[150:153], v[236:239], v[74:77]
	v_mfma_f32_16x16x32_bf16 v[122:125], v[146:149], v[186:189], v[122:125]
	v_mfma_f32_16x16x32_bf16 v[126:129], v[162:165], v[186:189], v[126:129]
	v_mfma_f32_16x16x32_bf16 v[110:113], v[146:149], v[224:227], v[110:113]
	v_mfma_f32_16x16x32_bf16 v[106:109], v[162:165], v[224:227], v[106:109]
	v_mfma_f32_16x16x32_bf16 v[94:97], v[146:149], v[232:235], v[94:97]
	v_mfma_f32_16x16x32_bf16 v[90:93], v[162:165], v[232:235], v[90:93]
	v_mfma_f32_16x16x32_bf16 v[78:81], v[146:149], v[240:243], v[78:81]
	v_mfma_f32_16x16x32_bf16 v[74:77], v[162:165], v[240:243], v[74:77]
	v_mfma_f32_16x16x32_bf16 v[118:121], v[166:169], v[182:185], v[118:121]
	v_mfma_f32_16x16x32_bf16 v[114:117], v[174:177], v[182:185], v[114:117]
	v_mfma_f32_16x16x32_bf16 v[102:105], v[166:169], v[220:223], v[102:105]
	v_mfma_f32_16x16x32_bf16 v[98:101], v[174:177], v[220:223], v[98:101]
	v_mfma_f32_16x16x32_bf16 v[86:89], v[166:169], v[228:231], v[86:89]
	v_mfma_f32_16x16x32_bf16 v[82:85], v[174:177], v[228:231], v[82:85]
	v_mfma_f32_16x16x32_bf16 v[70:73], v[166:169], v[236:239], v[70:73]
	v_mfma_f32_16x16x32_bf16 v[66:69], v[174:177], v[236:239], v[66:69]
	v_mfma_f32_16x16x32_bf16 v[118:121], v[170:173], v[186:189], v[118:121]
	v_mfma_f32_16x16x32_bf16 v[114:117], v[178:181], v[186:189], v[114:117]
	v_mfma_f32_16x16x32_bf16 v[102:105], v[170:173], v[224:227], v[102:105]
	v_mfma_f32_16x16x32_bf16 v[98:101], v[178:181], v[224:227], v[98:101]
	v_mfma_f32_16x16x32_bf16 v[86:89], v[170:173], v[232:235], v[86:89]
	v_mfma_f32_16x16x32_bf16 v[82:85], v[178:181], v[232:235], v[82:85]
	v_mfma_f32_16x16x32_bf16 v[70:73], v[170:173], v[240:243], v[70:73]
	v_mfma_f32_16x16x32_bf16 v[66:69], v[178:181], v[240:243], v[66:69]
	s_barrier
	s_add_i32 s63, s63, s42
	v_lshl_add_u64 v[190:191], s[34:35], 0, v[0:1]
	s_mov_b32 m0, s63
	ds_read_b128 v[182:185], v141 offset:16384
	ds_read_b128 v[186:189], v141 offset:17408
	ds_read_b128 v[220:223], v141 offset:18432
	ds_read_b128 v[224:227], v141 offset:19456
	ds_read_b128 v[228:231], v141 offset:20480
	ds_read_b128 v[232:235], v141 offset:21504
	ds_read_b128 v[236:239], v141 offset:22528
	ds_read_b128 v[240:243], v141 offset:23552
	global_load_lds_dwordx4 v[190:191], off
	s_add_i32 m0, s63, 0x2000
	s_add_u32 s78, s34, 0x80000
	v_lshl_add_u64 v[244:245], s[34:35], 0, v[134:135]
	s_addc_u32 s79, s35, 0
	s_add_i32 s63, s84, s42
	global_load_lds_dwordx4 v[244:245], off
	v_lshl_add_u64 v[246:247], s[78:79], 0, v[0:1]
	s_mov_b32 m0, s63
	v_lshl_add_u64 v[248:249], s[36:37], 0, v[132:133]
	global_load_lds_dwordx4 v[246:247], off
	v_lshl_add_u64 v[246:247], s[78:79], 0, v[134:135]
	s_add_i32 m0, s63, 0x2000
	s_nop 0
	global_load_lds_dwordx4 v[246:247], off
	v_lshl_add_u64 v[246:247], s[36:37], 0, v[130:131]
	s_mov_b32 m0, s21
	s_nop 0
	global_load_lds_dwordx4 v[246:247], off
	s_mov_b32 m0, s43
	s_nop 0
	global_load_lds_dwordx4 v[248:249], off
	s_waitcnt vmcnt(8)
	s_waitcnt lgkmcnt(0)
	s_barrier
	s_waitcnt lgkmcnt(0)
	v_mfma_f32_16x16x32_bf16 v[62:65], v[142:145], v[182:185], v[62:65]
	v_mfma_f32_16x16x32_bf16 v[58:61], v[150:153], v[182:185], v[58:61]
	v_mfma_f32_16x16x32_bf16 v[46:49], v[142:145], v[220:223], v[46:49]
	v_mfma_f32_16x16x32_bf16 v[42:45], v[150:153], v[220:223], v[42:45]
	v_mfma_f32_16x16x32_bf16 v[30:33], v[142:145], v[228:231], v[30:33]
	v_mfma_f32_16x16x32_bf16 v[26:29], v[150:153], v[228:231], v[26:29]
	v_mfma_f32_16x16x32_bf16 v[14:17], v[142:145], v[236:239], v[14:17]
	v_mfma_f32_16x16x32_bf16 v[10:13], v[150:153], v[236:239], v[10:13]
	v_mfma_f32_16x16x32_bf16 v[62:65], v[146:149], v[186:189], v[62:65]
	v_mfma_f32_16x16x32_bf16 v[58:61], v[162:165], v[186:189], v[58:61]
	v_mfma_f32_16x16x32_bf16 v[46:49], v[146:149], v[224:227], v[46:49]
	v_mfma_f32_16x16x32_bf16 v[42:45], v[162:165], v[224:227], v[42:45]
	v_mfma_f32_16x16x32_bf16 v[30:33], v[146:149], v[232:235], v[30:33]
	v_mfma_f32_16x16x32_bf16 v[26:29], v[162:165], v[232:235], v[26:29]
	v_mfma_f32_16x16x32_bf16 v[14:17], v[146:149], v[240:243], v[14:17]
	v_mfma_f32_16x16x32_bf16 v[10:13], v[162:165], v[240:243], v[10:13]
	v_mfma_f32_16x16x32_bf16 v[54:57], v[166:169], v[182:185], v[54:57]
	v_mfma_f32_16x16x32_bf16 v[50:53], v[174:177], v[182:185], v[50:53]
	v_mfma_f32_16x16x32_bf16 v[38:41], v[166:169], v[220:223], v[38:41]
	v_mfma_f32_16x16x32_bf16 v[34:37], v[174:177], v[220:223], v[34:37]
	v_mfma_f32_16x16x32_bf16 v[22:25], v[166:169], v[228:231], v[22:25]
	v_mfma_f32_16x16x32_bf16 v[18:21], v[174:177], v[228:231], v[18:21]
	v_mfma_f32_16x16x32_bf16 v[6:9], v[166:169], v[236:239], v[6:9]
	v_mfma_f32_16x16x32_bf16 v[2:5], v[174:177], v[236:239], v[2:5]
	v_mfma_f32_16x16x32_bf16 v[54:57], v[170:173], v[186:189], v[54:57]
	v_mfma_f32_16x16x32_bf16 v[50:53], v[178:181], v[186:189], v[50:53]
	v_mfma_f32_16x16x32_bf16 v[38:41], v[170:173], v[224:227], v[38:41]
	v_mfma_f32_16x16x32_bf16 v[34:37], v[178:181], v[224:227], v[34:37]
	v_mfma_f32_16x16x32_bf16 v[22:25], v[170:173], v[232:235], v[22:25]
	v_mfma_f32_16x16x32_bf16 v[18:21], v[178:181], v[232:235], v[18:21]
	v_mfma_f32_16x16x32_bf16 v[6:9], v[170:173], v[240:243], v[6:9]
	v_mfma_f32_16x16x32_bf16 v[2:5], v[178:181], v[240:243], v[2:5]
	s_barrier
	s_add_i32 s63, 0, 0x18000
	v_add_u32_e32 v161, s63, v140
	s_add_i32 s78, 0, 0x1c000
	ds_read_b128 v[142:145], v161
	ds_read_b128 v[146:149], v161 offset:1024
	ds_read_b128 v[150:153], v161 offset:2048
	ds_read_b128 v[162:165], v161 offset:3072
	v_add_u32_e32 v161, s78, v140
	ds_read_b128 v[166:169], v161
	ds_read_b128 v[170:173], v161 offset:1024
	ds_read_b128 v[174:177], v161 offset:2048
	ds_read_b128 v[178:181], v161 offset:3072
	s_add_u32 s36, s36, 0x80000
	s_addc_u32 s37, s37, 0
	s_mov_b32 m0, s46
	v_lshl_add_u64 v[250:251], s[36:37], 0, v[130:131]
	ds_read_b128 v[182:185], v141 offset:32768
	ds_read_b128 v[186:189], v141 offset:33792
	ds_read_b128 v[220:223], v141 offset:34816
	ds_read_b128 v[224:227], v141 offset:35840
	ds_read_b128 v[228:231], v141 offset:36864
	ds_read_b128 v[232:235], v141 offset:37888
	ds_read_b128 v[236:239], v141 offset:38912
	ds_read_b128 v[240:243], v141 offset:39936
	global_load_lds_dwordx4 v[250:251], off
	v_lshl_add_u64 v[250:251], s[36:37], 0, v[132:133]
	s_mov_b32 m0, s47
	s_nop 0
	global_load_lds_dwordx4 v[250:251], off
	s_waitcnt vmcnt(8)
	s_waitcnt lgkmcnt(0)
	s_barrier
	s_waitcnt lgkmcnt(0)
	v_mfma_f32_16x16x32_bf16 v[122:125], v[142:145], v[182:185], v[122:125]
	v_mfma_f32_16x16x32_bf16 v[126:129], v[150:153], v[182:185], v[126:129]
	v_mfma_f32_16x16x32_bf16 v[110:113], v[142:145], v[220:223], v[110:113]
	v_mfma_f32_16x16x32_bf16 v[106:109], v[150:153], v[220:223], v[106:109]
	v_mfma_f32_16x16x32_bf16 v[94:97], v[142:145], v[228:231], v[94:97]
	v_mfma_f32_16x16x32_bf16 v[90:93], v[150:153], v[228:231], v[90:93]
	v_mfma_f32_16x16x32_bf16 v[78:81], v[142:145], v[236:239], v[78:81]
	v_mfma_f32_16x16x32_bf16 v[74:77], v[150:153], v[236:239], v[74:77]
	v_mfma_f32_16x16x32_bf16 v[122:125], v[146:149], v[186:189], v[122:125]
	v_mfma_f32_16x16x32_bf16 v[126:129], v[162:165], v[186:189], v[126:129]
	v_mfma_f32_16x16x32_bf16 v[110:113], v[146:149], v[224:227], v[110:113]
	v_mfma_f32_16x16x32_bf16 v[106:109], v[162:165], v[224:227], v[106:109]
	v_mfma_f32_16x16x32_bf16 v[94:97], v[146:149], v[232:235], v[94:97]
	v_mfma_f32_16x16x32_bf16 v[90:93], v[162:165], v[232:235], v[90:93]
	v_mfma_f32_16x16x32_bf16 v[78:81], v[146:149], v[240:243], v[78:81]
	v_mfma_f32_16x16x32_bf16 v[74:77], v[162:165], v[240:243], v[74:77]
	v_mfma_f32_16x16x32_bf16 v[118:121], v[166:169], v[182:185], v[118:121]
	v_mfma_f32_16x16x32_bf16 v[114:117], v[174:177], v[182:185], v[114:117]
	v_mfma_f32_16x16x32_bf16 v[102:105], v[166:169], v[220:223], v[102:105]
	v_mfma_f32_16x16x32_bf16 v[98:101], v[174:177], v[220:223], v[98:101]
	v_mfma_f32_16x16x32_bf16 v[86:89], v[166:169], v[228:231], v[86:89]
	v_mfma_f32_16x16x32_bf16 v[82:85], v[174:177], v[228:231], v[82:85]
	v_mfma_f32_16x16x32_bf16 v[70:73], v[166:169], v[236:239], v[70:73]
	v_mfma_f32_16x16x32_bf16 v[66:69], v[174:177], v[236:239], v[66:69]
	v_mfma_f32_16x16x32_bf16 v[118:121], v[170:173], v[186:189], v[118:121]
	v_mfma_f32_16x16x32_bf16 v[114:117], v[178:181], v[186:189], v[114:117]
	v_mfma_f32_16x16x32_bf16 v[102:105], v[170:173], v[224:227], v[102:105]
	v_mfma_f32_16x16x32_bf16 v[98:101], v[178:181], v[224:227], v[98:101]
	v_mfma_f32_16x16x32_bf16 v[86:89], v[170:173], v[232:235], v[86:89]
	v_mfma_f32_16x16x32_bf16 v[82:85], v[178:181], v[232:235], v[82:85]
	v_mfma_f32_16x16x32_bf16 v[70:73], v[170:173], v[240:243], v[70:73]
	v_mfma_f32_16x16x32_bf16 v[66:69], v[178:181], v[240:243], v[66:69]
	s_barrier
	s_add_i32 s36, s63, s42
	v_lshl_add_u64 v[190:191], v[190:191], 0, s[72:73]
	s_mov_b32 m0, s36
	ds_read_b128 v[182:185], v141 offset:49152
	ds_read_b128 v[186:189], v141 offset:50176
	ds_read_b128 v[220:223], v141 offset:51200
	ds_read_b128 v[224:227], v141 offset:52224
	ds_read_b128 v[228:231], v141 offset:53248
	ds_read_b128 v[232:235], v141 offset:54272
	ds_read_b128 v[236:239], v141 offset:55296
	ds_read_b128 v[240:243], v141 offset:56320
	global_load_lds_dwordx4 v[190:191], off
	s_add_i32 m0, s36, 0x2000
	s_add_u32 s34, s34, 0x80080
	v_lshl_add_u64 v[190:191], v[244:245], 0, s[72:73]
	s_addc_u32 s35, s35, 0
	s_add_i32 s36, s78, s42
	global_load_lds_dwordx4 v[190:191], off
	v_lshl_add_u64 v[190:191], s[34:35], 0, v[0:1]
	s_mov_b32 m0, s36
	s_nop 0
	global_load_lds_dwordx4 v[190:191], off
	v_lshl_add_u64 v[190:191], s[34:35], 0, v[134:135]
	s_add_i32 m0, s36, 0x2000
	s_nop 0
	global_load_lds_dwordx4 v[190:191], off
	v_lshl_add_u64 v[190:191], v[246:247], 0, s[72:73]
	s_mov_b32 m0, s56
	s_nop 0
	global_load_lds_dwordx4 v[190:191], off
	v_lshl_add_u64 v[190:191], v[248:249], 0, s[72:73]
	s_mov_b32 m0, s57
	s_nop 0
	global_load_lds_dwordx4 v[190:191], off
	s_waitcnt vmcnt(8)
	s_waitcnt lgkmcnt(0)
	s_barrier
	s_waitcnt lgkmcnt(0)
	v_mfma_f32_16x16x32_bf16 v[62:65], v[142:145], v[182:185], v[62:65]
	v_mfma_f32_16x16x32_bf16 v[58:61], v[150:153], v[182:185], v[58:61]
	v_mfma_f32_16x16x32_bf16 v[46:49], v[142:145], v[220:223], v[46:49]
	v_mfma_f32_16x16x32_bf16 v[42:45], v[150:153], v[220:223], v[42:45]
	v_mfma_f32_16x16x32_bf16 v[30:33], v[142:145], v[228:231], v[30:33]
	v_mfma_f32_16x16x32_bf16 v[26:29], v[150:153], v[228:231], v[26:29]
	v_mfma_f32_16x16x32_bf16 v[14:17], v[142:145], v[236:239], v[14:17]
	v_mfma_f32_16x16x32_bf16 v[10:13], v[150:153], v[236:239], v[10:13]
	v_mfma_f32_16x16x32_bf16 v[62:65], v[146:149], v[186:189], v[62:65]
	v_mfma_f32_16x16x32_bf16 v[58:61], v[162:165], v[186:189], v[58:61]
	v_mfma_f32_16x16x32_bf16 v[46:49], v[146:149], v[224:227], v[46:49]
	v_mfma_f32_16x16x32_bf16 v[42:45], v[162:165], v[224:227], v[42:45]
	v_mfma_f32_16x16x32_bf16 v[30:33], v[146:149], v[232:235], v[30:33]
	v_mfma_f32_16x16x32_bf16 v[26:29], v[162:165], v[232:235], v[26:29]
	v_mfma_f32_16x16x32_bf16 v[14:17], v[146:149], v[240:243], v[14:17]
	v_mfma_f32_16x16x32_bf16 v[10:13], v[162:165], v[240:243], v[10:13]
	v_mfma_f32_16x16x32_bf16 v[54:57], v[166:169], v[182:185], v[54:57]
	v_mfma_f32_16x16x32_bf16 v[50:53], v[174:177], v[182:185], v[50:53]
	v_mfma_f32_16x16x32_bf16 v[38:41], v[166:169], v[220:223], v[38:41]
	v_mfma_f32_16x16x32_bf16 v[34:37], v[174:177], v[220:223], v[34:37]
	v_mfma_f32_16x16x32_bf16 v[22:25], v[166:169], v[228:231], v[22:25]
	v_mfma_f32_16x16x32_bf16 v[18:21], v[174:177], v[228:231], v[18:21]
	v_mfma_f32_16x16x32_bf16 v[6:9], v[166:169], v[236:239], v[6:9]
	v_mfma_f32_16x16x32_bf16 v[2:5], v[174:177], v[236:239], v[2:5]
	v_mfma_f32_16x16x32_bf16 v[54:57], v[170:173], v[186:189], v[54:57]
	v_mfma_f32_16x16x32_bf16 v[50:53], v[178:181], v[186:189], v[50:53]
	v_mfma_f32_16x16x32_bf16 v[38:41], v[170:173], v[224:227], v[38:41]
	v_mfma_f32_16x16x32_bf16 v[34:37], v[178:181], v[224:227], v[34:37]
	v_mfma_f32_16x16x32_bf16 v[22:25], v[170:173], v[232:235], v[22:25]
	v_mfma_f32_16x16x32_bf16 v[18:21], v[178:181], v[232:235], v[18:21]
	v_mfma_f32_16x16x32_bf16 v[6:9], v[170:173], v[240:243], v[6:9]
	v_mfma_f32_16x16x32_bf16 v[2:5], v[178:181], v[240:243], v[2:5]
	s_barrier
	s_add_u32 s30, s30, 0x100
	s_addc_u32 s31, s31, 0
	s_add_u32 s74, s74, 0x100
	s_addc_u32 s75, s75, 0
	s_cmp_ge_i32 s77, s48
	s_mov_b32 s34, s77
	s_cbranch_scc0 .LBB0_347
	v_readlane_b32 s84, v255, 34
	s_mov_b32 s63, 0x8000
	s_movk_i32 s71, 0x7fff

.LBB0_374:
	s_add_i32 s8, s30, 2
	s_add_u32 s28, s26, 0x100
	s_addc_u32 s29, s27, 0
	s_add_i32 s9, 0, 0x10000
	s_cmp_eq_u32 s58, s30
	s_cselect_b32 s35, s7, s29
	s_cselect_b32 s34, s6, s28
	v_add_u32_e32 v161, s9, v140
	s_cselect_b32 s31, s25, s78
	s_cselect_b32 s30, s24, s77
	s_add_i32 s62, 0, 0x14000
	ds_read_b128 v[142:145], v161
	ds_read_b128 v[146:149], v161 offset:1024
	ds_read_b128 v[150:153], v161 offset:2048
	ds_read_b128 v[162:165], v161 offset:3072
	v_add_u32_e32 v161, s62, v140
	ds_read_b128 v[166:169], v161
	ds_read_b128 v[170:173], v161 offset:1024
	ds_read_b128 v[174:177], v161 offset:2048
	ds_read_b128 v[178:181], v161 offset:3072
	v_lshl_add_u64 v[190:191], s[26:27], 0, v[136:137]
	s_add_i32 m0, s42, 0xc000
	ds_read_b128 v[182:185], v141
	ds_read_b128 v[186:189], v141 offset:1024
	ds_read_b128 v[220:223], v141 offset:2048
	ds_read_b128 v[224:227], v141 offset:3072
	ds_read_b128 v[228:231], v141 offset:4096
	ds_read_b128 v[232:235], v141 offset:5120
	ds_read_b128 v[236:239], v141 offset:6144
	ds_read_b128 v[240:243], v141 offset:7168
	global_load_lds_dwordx4 v[190:191], off
	v_lshl_add_u64 v[190:191], s[26:27], 0, v[138:139]
	s_add_i32 m0, s42, 0xe000
	s_nop 0
	global_load_lds_dwordx4 v[190:191], off
	s_waitcnt vmcnt(8)
	s_waitcnt lgkmcnt(0)
	s_barrier
	s_waitcnt lgkmcnt(0)
	v_mfma_f32_16x16x32_bf16 v[122:125], v[142:145], v[182:185], v[122:125]
	v_mfma_f32_16x16x32_bf16 v[126:129], v[150:153], v[182:185], v[126:129]
	v_mfma_f32_16x16x32_bf16 v[110:113], v[142:145], v[220:223], v[110:113]
	v_mfma_f32_16x16x32_bf16 v[106:109], v[150:153], v[220:223], v[106:109]
	v_mfma_f32_16x16x32_bf16 v[94:97], v[142:145], v[228:231], v[94:97]
	v_mfma_f32_16x16x32_bf16 v[90:93], v[150:153], v[228:231], v[90:93]
	v_mfma_f32_16x16x32_bf16 v[78:81], v[142:145], v[236:239], v[78:81]
	v_mfma_f32_16x16x32_bf16 v[74:77], v[150:153], v[236:239], v[74:77]
	v_mfma_f32_16x16x32_bf16 v[122:125], v[146:149], v[186:189], v[122:125]
	v_mfma_f32_16x16x32_bf16 v[126:129], v[162:165], v[186:189], v[126:129]
	v_mfma_f32_16x16x32_bf16 v[110:113], v[146:149], v[224:227], v[110:113]
	v_mfma_f32_16x16x32_bf16 v[106:109], v[162:165], v[224:227], v[106:109]
	v_mfma_f32_16x16x32_bf16 v[94:97], v[146:149], v[232:235], v[94:97]
	v_mfma_f32_16x16x32_bf16 v[90:93], v[162:165], v[232:235], v[90:93]
	v_mfma_f32_16x16x32_bf16 v[78:81], v[146:149], v[240:243], v[78:81]
	v_mfma_f32_16x16x32_bf16 v[74:77], v[162:165], v[240:243], v[74:77]
	v_mfma_f32_16x16x32_bf16 v[118:121], v[166:169], v[182:185], v[118:121]
	v_mfma_f32_16x16x32_bf16 v[114:117], v[174:177], v[182:185], v[114:117]
	v_mfma_f32_16x16x32_bf16 v[102:105], v[166:169], v[220:223], v[102:105]
	v_mfma_f32_16x16x32_bf16 v[98:101], v[174:177], v[220:223], v[98:101]
	v_mfma_f32_16x16x32_bf16 v[86:89], v[166:169], v[228:231], v[86:89]
	v_mfma_f32_16x16x32_bf16 v[82:85], v[174:177], v[228:231], v[82:85]
	v_mfma_f32_16x16x32_bf16 v[70:73], v[166:169], v[236:239], v[70:73]
	v_mfma_f32_16x16x32_bf16 v[66:69], v[174:177], v[236:239], v[66:69]
	v_mfma_f32_16x16x32_bf16 v[118:121], v[170:173], v[186:189], v[118:121]
	v_mfma_f32_16x16x32_bf16 v[114:117], v[178:181], v[186:189], v[114:117]
	v_mfma_f32_16x16x32_bf16 v[102:105], v[170:173], v[224:227], v[102:105]
	v_mfma_f32_16x16x32_bf16 v[98:101], v[178:181], v[224:227], v[98:101]
	v_mfma_f32_16x16x32_bf16 v[86:89], v[170:173], v[232:235], v[86:89]
	v_mfma_f32_16x16x32_bf16 v[82:85], v[178:181], v[232:235], v[82:85]
	v_mfma_f32_16x16x32_bf16 v[70:73], v[170:173], v[240:243], v[70:73]
	v_mfma_f32_16x16x32_bf16 v[66:69], v[178:181], v[240:243], v[66:69]
	s_barrier
	s_add_i32 s9, s9, s38
	v_lshl_add_u64 v[190:191], s[30:31], 0, v[0:1]
	s_mov_b32 m0, s9
	ds_read_b128 v[182:185], v141 offset:16384
	ds_read_b128 v[186:189], v141 offset:17408
	ds_read_b128 v[220:223], v141 offset:18432
	ds_read_b128 v[224:227], v141 offset:19456
	ds_read_b128 v[228:231], v141 offset:20480
	ds_read_b128 v[232:235], v141 offset:21504
	ds_read_b128 v[236:239], v141 offset:22528
	ds_read_b128 v[240:243], v141 offset:23552
	global_load_lds_dwordx4 v[190:191], off
	s_add_i32 m0, s9, 0x2000
	s_add_u32 s26, s30, 0x28000
	v_lshl_add_u64 v[244:245], s[30:31], 0, v[130:131]
	s_addc_u32 s27, s31, 0
	s_add_i32 s9, s62, s38
	global_load_lds_dwordx4 v[244:245], off
	v_lshl_add_u64 v[246:247], s[26:27], 0, v[0:1]
	s_mov_b32 m0, s9
	v_lshl_add_u64 v[248:249], s[34:35], 0, v[132:133]
	global_load_lds_dwordx4 v[246:247], off
	v_lshl_add_u64 v[246:247], s[26:27], 0, v[130:131]
	s_add_i32 m0, s9, 0x2000
	s_nop 0
	global_load_lds_dwordx4 v[246:247], off
	v_lshl_add_u64 v[246:247], s[34:35], 0, v[134:135]
	s_mov_b32 m0, s42
	s_nop 0
	global_load_lds_dwordx4 v[246:247], off
	s_mov_b32 m0, s43
	s_nop 0
	global_load_lds_dwordx4 v[248:249], off
	s_waitcnt vmcnt(8)
	s_waitcnt lgkmcnt(0)
	s_barrier
	s_waitcnt lgkmcnt(0)
	v_mfma_f32_16x16x32_bf16 v[62:65], v[142:145], v[182:185], v[62:65]
	v_mfma_f32_16x16x32_bf16 v[58:61], v[150:153], v[182:185], v[58:61]
	v_mfma_f32_16x16x32_bf16 v[46:49], v[142:145], v[220:223], v[46:49]
	v_mfma_f32_16x16x32_bf16 v[42:45], v[150:153], v[220:223], v[42:45]
	v_mfma_f32_16x16x32_bf16 v[30:33], v[142:145], v[228:231], v[30:33]
	v_mfma_f32_16x16x32_bf16 v[26:29], v[150:153], v[228:231], v[26:29]
	v_mfma_f32_16x16x32_bf16 v[14:17], v[142:145], v[236:239], v[14:17]
	v_mfma_f32_16x16x32_bf16 v[10:13], v[150:153], v[236:239], v[10:13]
	v_mfma_f32_16x16x32_bf16 v[62:65], v[146:149], v[186:189], v[62:65]
	v_mfma_f32_16x16x32_bf16 v[58:61], v[162:165], v[186:189], v[58:61]
	v_mfma_f32_16x16x32_bf16 v[46:49], v[146:149], v[224:227], v[46:49]
	v_mfma_f32_16x16x32_bf16 v[42:45], v[162:165], v[224:227], v[42:45]
	v_mfma_f32_16x16x32_bf16 v[30:33], v[146:149], v[232:235], v[30:33]
	v_mfma_f32_16x16x32_bf16 v[26:29], v[162:165], v[232:235], v[26:29]
	v_mfma_f32_16x16x32_bf16 v[14:17], v[146:149], v[240:243], v[14:17]
	v_mfma_f32_16x16x32_bf16 v[10:13], v[162:165], v[240:243], v[10:13]
	v_mfma_f32_16x16x32_bf16 v[54:57], v[166:169], v[182:185], v[54:57]
	v_mfma_f32_16x16x32_bf16 v[50:53], v[174:177], v[182:185], v[50:53]
	v_mfma_f32_16x16x32_bf16 v[38:41], v[166:169], v[220:223], v[38:41]
	v_mfma_f32_16x16x32_bf16 v[34:37], v[174:177], v[220:223], v[34:37]
	v_mfma_f32_16x16x32_bf16 v[22:25], v[166:169], v[228:231], v[22:25]
	v_mfma_f32_16x16x32_bf16 v[18:21], v[174:177], v[228:231], v[18:21]
	v_mfma_f32_16x16x32_bf16 v[6:9], v[166:169], v[236:239], v[6:9]
	v_mfma_f32_16x16x32_bf16 v[2:5], v[174:177], v[236:239], v[2:5]
	v_mfma_f32_16x16x32_bf16 v[54:57], v[170:173], v[186:189], v[54:57]
	v_mfma_f32_16x16x32_bf16 v[50:53], v[178:181], v[186:189], v[50:53]
	v_mfma_f32_16x16x32_bf16 v[38:41], v[170:173], v[224:227], v[38:41]
	v_mfma_f32_16x16x32_bf16 v[34:37], v[178:181], v[224:227], v[34:37]
	v_mfma_f32_16x16x32_bf16 v[22:25], v[170:173], v[232:235], v[22:25]
	v_mfma_f32_16x16x32_bf16 v[18:21], v[178:181], v[232:235], v[18:21]
	v_mfma_f32_16x16x32_bf16 v[6:9], v[170:173], v[240:243], v[6:9]
	v_mfma_f32_16x16x32_bf16 v[2:5], v[178:181], v[240:243], v[2:5]
	s_barrier
	s_add_i32 s9, 0, 0x18000
	v_add_u32_e32 v161, s9, v140
	s_add_i32 s62, 0, 0x1c000
	ds_read_b128 v[142:145], v161
	ds_read_b128 v[146:149], v161 offset:1024
	ds_read_b128 v[150:153], v161 offset:2048
	ds_read_b128 v[162:165], v161 offset:3072
	v_add_u32_e32 v161, s62, v140
	ds_read_b128 v[166:169], v161
	ds_read_b128 v[170:173], v161 offset:1024
	ds_read_b128 v[174:177], v161 offset:2048
	ds_read_b128 v[178:181], v161 offset:3072
	s_add_u32 s26, s34, 0x140000
	s_addc_u32 s27, s35, 0
	s_mov_b32 m0, s46
	v_lshl_add_u64 v[250:251], s[26:27], 0, v[134:135]
	ds_read_b128 v[182:185], v141 offset:32768
	ds_read_b128 v[186:189], v141 offset:33792
	ds_read_b128 v[220:223], v141 offset:34816
	ds_read_b128 v[224:227], v141 offset:35840
	ds_read_b128 v[228:231], v141 offset:36864
	ds_read_b128 v[232:235], v141 offset:37888
	ds_read_b128 v[236:239], v141 offset:38912
	ds_read_b128 v[240:243], v141 offset:39936
	global_load_lds_dwordx4 v[250:251], off
	v_lshl_add_u64 v[250:251], s[26:27], 0, v[132:133]
	s_mov_b32 m0, s47
	s_nop 0
	global_load_lds_dwordx4 v[250:251], off
	s_waitcnt vmcnt(8)
	s_waitcnt lgkmcnt(0)
	s_barrier
	s_waitcnt lgkmcnt(0)
	v_mfma_f32_16x16x32_bf16 v[122:125], v[142:145], v[182:185], v[122:125]
	v_mfma_f32_16x16x32_bf16 v[126:129], v[150:153], v[182:185], v[126:129]
	v_mfma_f32_16x16x32_bf16 v[110:113], v[142:145], v[220:223], v[110:113]
	v_mfma_f32_16x16x32_bf16 v[106:109], v[150:153], v[220:223], v[106:109]
	v_mfma_f32_16x16x32_bf16 v[94:97], v[142:145], v[228:231], v[94:97]
	v_mfma_f32_16x16x32_bf16 v[90:93], v[150:153], v[228:231], v[90:93]
	v_mfma_f32_16x16x32_bf16 v[78:81], v[142:145], v[236:239], v[78:81]
	v_mfma_f32_16x16x32_bf16 v[74:77], v[150:153], v[236:239], v[74:77]
	v_mfma_f32_16x16x32_bf16 v[122:125], v[146:149], v[186:189], v[122:125]
	v_mfma_f32_16x16x32_bf16 v[126:129], v[162:165], v[186:189], v[126:129]
	v_mfma_f32_16x16x32_bf16 v[110:113], v[146:149], v[224:227], v[110:113]
	v_mfma_f32_16x16x32_bf16 v[106:109], v[162:165], v[224:227], v[106:109]
	v_mfma_f32_16x16x32_bf16 v[94:97], v[146:149], v[232:235], v[94:97]
	v_mfma_f32_16x16x32_bf16 v[90:93], v[162:165], v[232:235], v[90:93]
	v_mfma_f32_16x16x32_bf16 v[78:81], v[146:149], v[240:243], v[78:81]
	v_mfma_f32_16x16x32_bf16 v[74:77], v[162:165], v[240:243], v[74:77]
	v_mfma_f32_16x16x32_bf16 v[118:121], v[166:169], v[182:185], v[118:121]
	v_mfma_f32_16x16x32_bf16 v[114:117], v[174:177], v[182:185], v[114:117]
	v_mfma_f32_16x16x32_bf16 v[102:105], v[166:169], v[220:223], v[102:105]
	v_mfma_f32_16x16x32_bf16 v[98:101], v[174:177], v[220:223], v[98:101]
	v_mfma_f32_16x16x32_bf16 v[86:89], v[166:169], v[228:231], v[86:89]
	v_mfma_f32_16x16x32_bf16 v[82:85], v[174:177], v[228:231], v[82:85]
	v_mfma_f32_16x16x32_bf16 v[70:73], v[166:169], v[236:239], v[70:73]
	v_mfma_f32_16x16x32_bf16 v[66:69], v[174:177], v[236:239], v[66:69]
	v_mfma_f32_16x16x32_bf16 v[118:121], v[170:173], v[186:189], v[118:121]
	v_mfma_f32_16x16x32_bf16 v[114:117], v[178:181], v[186:189], v[114:117]
	v_mfma_f32_16x16x32_bf16 v[102:105], v[170:173], v[224:227], v[102:105]
	v_mfma_f32_16x16x32_bf16 v[98:101], v[178:181], v[224:227], v[98:101]
	v_mfma_f32_16x16x32_bf16 v[86:89], v[170:173], v[232:235], v[86:89]
	v_mfma_f32_16x16x32_bf16 v[82:85], v[178:181], v[232:235], v[82:85]
	v_mfma_f32_16x16x32_bf16 v[70:73], v[170:173], v[240:243], v[70:73]
	v_mfma_f32_16x16x32_bf16 v[66:69], v[178:181], v[240:243], v[66:69]
	s_barrier
	s_add_i32 s9, s9, s38
	v_lshl_add_u64 v[190:191], v[190:191], 0, s[72:73]
	s_mov_b32 m0, s9
	ds_read_b128 v[182:185], v141 offset:49152
	ds_read_b128 v[186:189], v141 offset:50176
	ds_read_b128 v[220:223], v141 offset:51200
	ds_read_b128 v[224:227], v141 offset:52224
	ds_read_b128 v[228:231], v141 offset:53248
	ds_read_b128 v[232:235], v141 offset:54272
	ds_read_b128 v[236:239], v141 offset:55296
	ds_read_b128 v[240:243], v141 offset:56320
	global_load_lds_dwordx4 v[190:191], off
	s_add_i32 m0, s9, 0x2000
	s_add_u32 s26, s30, 0x28080
	v_lshl_add_u64 v[190:191], v[244:245], 0, s[72:73]
	s_addc_u32 s27, s31, 0
	s_add_i32 s9, s62, s38
	global_load_lds_dwordx4 v[190:191], off
	v_lshl_add_u64 v[190:191], s[26:27], 0, v[0:1]
	s_mov_b32 m0, s9
	s_nop 0
	global_load_lds_dwordx4 v[190:191], off
	v_lshl_add_u64 v[190:191], s[26:27], 0, v[130:131]
	s_add_i32 m0, s9, 0x2000
	s_nop 0
	global_load_lds_dwordx4 v[190:191], off
	v_lshl_add_u64 v[190:191], v[246:247], 0, s[72:73]
	s_mov_b32 m0, s56
	s_nop 0
	global_load_lds_dwordx4 v[190:191], off
	v_lshl_add_u64 v[190:191], v[248:249], 0, s[72:73]
	s_mov_b32 m0, s57
	s_nop 0
	global_load_lds_dwordx4 v[190:191], off
	s_waitcnt vmcnt(8)
	s_waitcnt lgkmcnt(0)
	s_barrier
	s_waitcnt lgkmcnt(0)
	v_mfma_f32_16x16x32_bf16 v[62:65], v[142:145], v[182:185], v[62:65]
	v_mfma_f32_16x16x32_bf16 v[58:61], v[150:153], v[182:185], v[58:61]
	v_mfma_f32_16x16x32_bf16 v[46:49], v[142:145], v[220:223], v[46:49]
	v_mfma_f32_16x16x32_bf16 v[42:45], v[150:153], v[220:223], v[42:45]
	v_mfma_f32_16x16x32_bf16 v[30:33], v[142:145], v[228:231], v[30:33]
	v_mfma_f32_16x16x32_bf16 v[26:29], v[150:153], v[228:231], v[26:29]
	v_mfma_f32_16x16x32_bf16 v[14:17], v[142:145], v[236:239], v[14:17]
	v_mfma_f32_16x16x32_bf16 v[10:13], v[150:153], v[236:239], v[10:13]
	v_mfma_f32_16x16x32_bf16 v[62:65], v[146:149], v[186:189], v[62:65]
	v_mfma_f32_16x16x32_bf16 v[58:61], v[162:165], v[186:189], v[58:61]
	v_mfma_f32_16x16x32_bf16 v[46:49], v[146:149], v[224:227], v[46:49]
	v_mfma_f32_16x16x32_bf16 v[42:45], v[162:165], v[224:227], v[42:45]
	v_mfma_f32_16x16x32_bf16 v[30:33], v[146:149], v[232:235], v[30:33]
	v_mfma_f32_16x16x32_bf16 v[26:29], v[162:165], v[232:235], v[26:29]
	v_mfma_f32_16x16x32_bf16 v[14:17], v[146:149], v[240:243], v[14:17]
	v_mfma_f32_16x16x32_bf16 v[10:13], v[162:165], v[240:243], v[10:13]
	v_mfma_f32_16x16x32_bf16 v[54:57], v[166:169], v[182:185], v[54:57]
	v_mfma_f32_16x16x32_bf16 v[50:53], v[174:177], v[182:185], v[50:53]
	v_mfma_f32_16x16x32_bf16 v[38:41], v[166:169], v[220:223], v[38:41]
	v_mfma_f32_16x16x32_bf16 v[34:37], v[174:177], v[220:223], v[34:37]
	v_mfma_f32_16x16x32_bf16 v[22:25], v[166:169], v[228:231], v[22:25]
	v_mfma_f32_16x16x32_bf16 v[18:21], v[174:177], v[228:231], v[18:21]
	v_mfma_f32_16x16x32_bf16 v[6:9], v[166:169], v[236:239], v[6:9]
	v_mfma_f32_16x16x32_bf16 v[2:5], v[174:177], v[236:239], v[2:5]
	v_mfma_f32_16x16x32_bf16 v[54:57], v[170:173], v[186:189], v[54:57]
	v_mfma_f32_16x16x32_bf16 v[50:53], v[178:181], v[186:189], v[50:53]
	v_mfma_f32_16x16x32_bf16 v[38:41], v[170:173], v[224:227], v[38:41]
	v_mfma_f32_16x16x32_bf16 v[34:37], v[178:181], v[224:227], v[34:37]
	v_mfma_f32_16x16x32_bf16 v[22:25], v[170:173], v[232:235], v[22:25]
	v_mfma_f32_16x16x32_bf16 v[18:21], v[178:181], v[232:235], v[18:21]
	v_mfma_f32_16x16x32_bf16 v[6:9], v[170:173], v[240:243], v[6:9]
	v_mfma_f32_16x16x32_bf16 v[2:5], v[178:181], v[240:243], v[2:5]
	s_barrier
	s_add_u32 s77, s77, 0x100
	s_addc_u32 s78, s78, 0
	s_cmp_ge_i32 s8, s48
	s_mov_b64 s[26:27], s[28:29]
	s_mov_b32 s30, s8
	s_cbranch_scc0 .LBB0_374

.LBB0_430:
	s_add_i32 s8, s36, 2
	s_add_u32 s9, s34, 0xfff80080
	s_addc_u32 s37, s35, -1
	s_add_i32 s62, 0, 0x10000
	s_cmp_eq_u32 s74, s36
	s_cselect_b32 s39, s25, s37
	s_cselect_b32 s38, s27, s9
	v_add_u32_e32 v161, s62, v148
	s_cselect_b32 s37, s79, vcc_hi
	s_cselect_b32 s36, s91, vcc_lo
	s_add_i32 s9, 0, 0x14000
	ds_read_b128 v[140:143], v161
	ds_read_b128 v[144:147], v161 offset:1024
	ds_read_b128 v[150:153], v161 offset:2048
	ds_read_b128 v[162:165], v161 offset:3072
	v_add_u32_e32 v161, s9, v148
	ds_read_b128 v[166:169], v161
	ds_read_b128 v[170:173], v161 offset:1024
	ds_read_b128 v[174:177], v161 offset:2048
	ds_read_b128 v[178:181], v161 offset:3072
	v_lshl_add_u64 v[190:191], s[34:35], 0, v[136:137]
	s_add_i32 m0, s23, 0xc000
	ds_read_b128 v[182:185], v149
	ds_read_b128 v[186:189], v149 offset:1024
	ds_read_b128 v[220:223], v149 offset:2048
	ds_read_b128 v[224:227], v149 offset:3072
	ds_read_b128 v[228:231], v149 offset:4096
	ds_read_b128 v[232:235], v149 offset:5120
	ds_read_b128 v[236:239], v149 offset:6144
	ds_read_b128 v[240:243], v149 offset:7168
	global_load_lds_dwordx4 v[190:191], off
	v_lshl_add_u64 v[190:191], s[34:35], 0, v[138:139]
	s_add_i32 m0, s23, 0xe000
	s_nop 0
	global_load_lds_dwordx4 v[190:191], off
	s_waitcnt vmcnt(8)
	s_waitcnt lgkmcnt(0)
	s_barrier
	s_waitcnt lgkmcnt(0)
	v_mfma_f32_16x16x32_bf16 v[126:129], v[140:143], v[182:185], v[126:129]
	v_mfma_f32_16x16x32_bf16 v[122:125], v[150:153], v[182:185], v[122:125]
	v_mfma_f32_16x16x32_bf16 v[118:121], v[140:143], v[220:223], v[118:121]
	v_mfma_f32_16x16x32_bf16 v[114:117], v[150:153], v[220:223], v[114:117]
	v_mfma_f32_16x16x32_bf16 v[106:109], v[140:143], v[228:231], v[106:109]
	v_mfma_f32_16x16x32_bf16 v[98:101], v[150:153], v[228:231], v[98:101]
	v_mfma_f32_16x16x32_bf16 v[90:93], v[140:143], v[236:239], v[90:93]
	v_mfma_f32_16x16x32_bf16 v[82:85], v[150:153], v[236:239], v[82:85]
	v_mfma_f32_16x16x32_bf16 v[126:129], v[144:147], v[186:189], v[126:129]
	v_mfma_f32_16x16x32_bf16 v[122:125], v[162:165], v[186:189], v[122:125]
	v_mfma_f32_16x16x32_bf16 v[118:121], v[144:147], v[224:227], v[118:121]
	v_mfma_f32_16x16x32_bf16 v[114:117], v[162:165], v[224:227], v[114:117]
	v_mfma_f32_16x16x32_bf16 v[106:109], v[144:147], v[232:235], v[106:109]
	v_mfma_f32_16x16x32_bf16 v[98:101], v[162:165], v[232:235], v[98:101]
	v_mfma_f32_16x16x32_bf16 v[90:93], v[144:147], v[240:243], v[90:93]
	v_mfma_f32_16x16x32_bf16 v[82:85], v[162:165], v[240:243], v[82:85]
	v_mfma_f32_16x16x32_bf16 v[110:113], v[166:169], v[182:185], v[110:113]
	v_mfma_f32_16x16x32_bf16 v[102:105], v[174:177], v[182:185], v[102:105]
	v_mfma_f32_16x16x32_bf16 v[94:97], v[166:169], v[220:223], v[94:97]
	v_mfma_f32_16x16x32_bf16 v[86:89], v[174:177], v[220:223], v[86:89]
	v_mfma_f32_16x16x32_bf16 v[78:81], v[166:169], v[228:231], v[78:81]
	v_mfma_f32_16x16x32_bf16 v[74:77], v[174:177], v[228:231], v[74:77]
	v_mfma_f32_16x16x32_bf16 v[70:73], v[166:169], v[236:239], v[70:73]
	v_mfma_f32_16x16x32_bf16 v[66:69], v[174:177], v[236:239], v[66:69]
	v_mfma_f32_16x16x32_bf16 v[110:113], v[170:173], v[186:189], v[110:113]
	v_mfma_f32_16x16x32_bf16 v[102:105], v[178:181], v[186:189], v[102:105]
	v_mfma_f32_16x16x32_bf16 v[94:97], v[170:173], v[224:227], v[94:97]
	v_mfma_f32_16x16x32_bf16 v[86:89], v[178:181], v[224:227], v[86:89]
	v_mfma_f32_16x16x32_bf16 v[78:81], v[170:173], v[232:235], v[78:81]
	v_mfma_f32_16x16x32_bf16 v[74:77], v[178:181], v[232:235], v[74:77]
	v_mfma_f32_16x16x32_bf16 v[70:73], v[170:173], v[240:243], v[70:73]
	v_mfma_f32_16x16x32_bf16 v[66:69], v[178:181], v[240:243], v[66:69]
	s_barrier
	s_add_i32 s62, s62, s46
	v_lshl_add_u64 v[190:191], s[36:37], 0, v[0:1]
	s_mov_b32 m0, s62
	ds_read_b128 v[182:185], v149 offset:16384
	ds_read_b128 v[186:189], v149 offset:17408
	ds_read_b128 v[220:223], v149 offset:18432
	ds_read_b128 v[224:227], v149 offset:19456
	ds_read_b128 v[228:231], v149 offset:20480
	ds_read_b128 v[232:235], v149 offset:21504
	ds_read_b128 v[236:239], v149 offset:22528
	ds_read_b128 v[240:243], v149 offset:23552
	global_load_lds_dwordx4 v[190:191], off
	s_add_i32 m0, s62, 0x2000
	s_add_u32 s62, s36, 0x8000
	v_lshl_add_u64 v[244:245], s[36:37], 0, v[130:131]
	s_addc_u32 s63, s37, 0
	s_add_i32 s9, s9, s46
	global_load_lds_dwordx4 v[244:245], off
	v_lshl_add_u64 v[246:247], s[62:63], 0, v[0:1]
	s_mov_b32 m0, s9
	v_lshl_add_u64 v[248:249], s[38:39], 0, v[132:133]
	global_load_lds_dwordx4 v[246:247], off
	v_lshl_add_u64 v[246:247], s[62:63], 0, v[130:131]
	s_add_i32 m0, s9, 0x2000
	s_nop 0
	global_load_lds_dwordx4 v[246:247], off
	v_lshl_add_u64 v[246:247], s[38:39], 0, v[134:135]
	s_mov_b32 m0, s23
	s_nop 0
	global_load_lds_dwordx4 v[246:247], off
	s_mov_b32 m0, s50
	s_nop 0
	global_load_lds_dwordx4 v[248:249], off
	s_waitcnt vmcnt(8)
	s_waitcnt lgkmcnt(0)
	s_barrier
	s_waitcnt lgkmcnt(0)
	v_mfma_f32_16x16x32_bf16 v[62:65], v[140:143], v[182:185], v[62:65]
	v_mfma_f32_16x16x32_bf16 v[58:61], v[150:153], v[182:185], v[58:61]
	v_mfma_f32_16x16x32_bf16 v[54:57], v[140:143], v[220:223], v[54:57]
	v_mfma_f32_16x16x32_bf16 v[50:53], v[150:153], v[220:223], v[50:53]
	v_mfma_f32_16x16x32_bf16 v[42:45], v[140:143], v[228:231], v[42:45]
	v_mfma_f32_16x16x32_bf16 v[34:37], v[150:153], v[228:231], v[34:37]
	v_mfma_f32_16x16x32_bf16 v[26:29], v[140:143], v[236:239], v[26:29]
	v_mfma_f32_16x16x32_bf16 v[18:21], v[150:153], v[236:239], v[18:21]
	v_mfma_f32_16x16x32_bf16 v[62:65], v[144:147], v[186:189], v[62:65]
	v_mfma_f32_16x16x32_bf16 v[58:61], v[162:165], v[186:189], v[58:61]
	v_mfma_f32_16x16x32_bf16 v[54:57], v[144:147], v[224:227], v[54:57]
	v_mfma_f32_16x16x32_bf16 v[50:53], v[162:165], v[224:227], v[50:53]
	v_mfma_f32_16x16x32_bf16 v[42:45], v[144:147], v[232:235], v[42:45]
	v_mfma_f32_16x16x32_bf16 v[34:37], v[162:165], v[232:235], v[34:37]
	v_mfma_f32_16x16x32_bf16 v[26:29], v[144:147], v[240:243], v[26:29]
	v_mfma_f32_16x16x32_bf16 v[18:21], v[162:165], v[240:243], v[18:21]
	v_mfma_f32_16x16x32_bf16 v[46:49], v[166:169], v[182:185], v[46:49]
	v_mfma_f32_16x16x32_bf16 v[38:41], v[174:177], v[182:185], v[38:41]
	v_mfma_f32_16x16x32_bf16 v[30:33], v[166:169], v[220:223], v[30:33]
	v_mfma_f32_16x16x32_bf16 v[22:25], v[174:177], v[220:223], v[22:25]
	v_mfma_f32_16x16x32_bf16 v[14:17], v[166:169], v[228:231], v[14:17]
	v_mfma_f32_16x16x32_bf16 v[10:13], v[174:177], v[228:231], v[10:13]
	v_mfma_f32_16x16x32_bf16 v[6:9], v[166:169], v[236:239], v[6:9]
	v_mfma_f32_16x16x32_bf16 v[2:5], v[174:177], v[236:239], v[2:5]
	v_mfma_f32_16x16x32_bf16 v[46:49], v[170:173], v[186:189], v[46:49]
	v_mfma_f32_16x16x32_bf16 v[38:41], v[178:181], v[186:189], v[38:41]
	v_mfma_f32_16x16x32_bf16 v[30:33], v[170:173], v[224:227], v[30:33]
	v_mfma_f32_16x16x32_bf16 v[22:25], v[178:181], v[224:227], v[22:25]
	v_mfma_f32_16x16x32_bf16 v[14:17], v[170:173], v[232:235], v[14:17]
	v_mfma_f32_16x16x32_bf16 v[10:13], v[178:181], v[232:235], v[10:13]
	v_mfma_f32_16x16x32_bf16 v[6:9], v[170:173], v[240:243], v[6:9]
	v_mfma_f32_16x16x32_bf16 v[2:5], v[178:181], v[240:243], v[2:5]
	s_barrier
	s_add_i32 s9, 0, 0x18000
	v_add_u32_e32 v161, s9, v148
	s_add_i32 s62, 0, 0x1c000
	ds_read_b128 v[140:143], v161
	ds_read_b128 v[144:147], v161 offset:1024
	ds_read_b128 v[150:153], v161 offset:2048
	ds_read_b128 v[162:165], v161 offset:3072
	v_add_u32_e32 v161, s62, v148
	ds_read_b128 v[166:169], v161
	ds_read_b128 v[170:173], v161 offset:1024
	ds_read_b128 v[174:177], v161 offset:2048
	ds_read_b128 v[178:181], v161 offset:3072
	s_add_u32 s38, s38, 0x80000
	s_addc_u32 s39, s39, 0
	s_mov_b32 m0, s56
	v_lshl_add_u64 v[250:251], s[38:39], 0, v[134:135]
	ds_read_b128 v[182:185], v149 offset:32768
	ds_read_b128 v[186:189], v149 offset:33792
	ds_read_b128 v[220:223], v149 offset:34816
	ds_read_b128 v[224:227], v149 offset:35840
	ds_read_b128 v[228:231], v149 offset:36864
	ds_read_b128 v[232:235], v149 offset:37888
	ds_read_b128 v[236:239], v149 offset:38912
	ds_read_b128 v[240:243], v149 offset:39936
	global_load_lds_dwordx4 v[250:251], off
	v_lshl_add_u64 v[250:251], s[38:39], 0, v[132:133]
	s_mov_b32 m0, s57
	s_nop 0
	global_load_lds_dwordx4 v[250:251], off
	s_waitcnt vmcnt(8)
	s_waitcnt lgkmcnt(0)
	s_barrier
	s_waitcnt lgkmcnt(0)
	v_mfma_f32_16x16x32_bf16 v[126:129], v[140:143], v[182:185], v[126:129]
	v_mfma_f32_16x16x32_bf16 v[122:125], v[150:153], v[182:185], v[122:125]
	v_mfma_f32_16x16x32_bf16 v[118:121], v[140:143], v[220:223], v[118:121]
	v_mfma_f32_16x16x32_bf16 v[114:117], v[150:153], v[220:223], v[114:117]
	v_mfma_f32_16x16x32_bf16 v[106:109], v[140:143], v[228:231], v[106:109]
	v_mfma_f32_16x16x32_bf16 v[98:101], v[150:153], v[228:231], v[98:101]
	v_mfma_f32_16x16x32_bf16 v[90:93], v[140:143], v[236:239], v[90:93]
	v_mfma_f32_16x16x32_bf16 v[82:85], v[150:153], v[236:239], v[82:85]
	v_mfma_f32_16x16x32_bf16 v[126:129], v[144:147], v[186:189], v[126:129]
	v_mfma_f32_16x16x32_bf16 v[122:125], v[162:165], v[186:189], v[122:125]
	v_mfma_f32_16x16x32_bf16 v[118:121], v[144:147], v[224:227], v[118:121]
	v_mfma_f32_16x16x32_bf16 v[114:117], v[162:165], v[224:227], v[114:117]
	v_mfma_f32_16x16x32_bf16 v[106:109], v[144:147], v[232:235], v[106:109]
	v_mfma_f32_16x16x32_bf16 v[98:101], v[162:165], v[232:235], v[98:101]
	v_mfma_f32_16x16x32_bf16 v[90:93], v[144:147], v[240:243], v[90:93]
	v_mfma_f32_16x16x32_bf16 v[82:85], v[162:165], v[240:243], v[82:85]
	v_mfma_f32_16x16x32_bf16 v[110:113], v[166:169], v[182:185], v[110:113]
	v_mfma_f32_16x16x32_bf16 v[102:105], v[174:177], v[182:185], v[102:105]
	v_mfma_f32_16x16x32_bf16 v[94:97], v[166:169], v[220:223], v[94:97]
	v_mfma_f32_16x16x32_bf16 v[86:89], v[174:177], v[220:223], v[86:89]
	v_mfma_f32_16x16x32_bf16 v[78:81], v[166:169], v[228:231], v[78:81]
	v_mfma_f32_16x16x32_bf16 v[74:77], v[174:177], v[228:231], v[74:77]
	v_mfma_f32_16x16x32_bf16 v[70:73], v[166:169], v[236:239], v[70:73]
	v_mfma_f32_16x16x32_bf16 v[66:69], v[174:177], v[236:239], v[66:69]
	v_mfma_f32_16x16x32_bf16 v[110:113], v[170:173], v[186:189], v[110:113]
	v_mfma_f32_16x16x32_bf16 v[102:105], v[178:181], v[186:189], v[102:105]
	v_mfma_f32_16x16x32_bf16 v[94:97], v[170:173], v[224:227], v[94:97]
	v_mfma_f32_16x16x32_bf16 v[86:89], v[178:181], v[224:227], v[86:89]
	v_mfma_f32_16x16x32_bf16 v[78:81], v[170:173], v[232:235], v[78:81]
	v_mfma_f32_16x16x32_bf16 v[74:77], v[178:181], v[232:235], v[74:77]
	v_mfma_f32_16x16x32_bf16 v[70:73], v[170:173], v[240:243], v[70:73]
	v_mfma_f32_16x16x32_bf16 v[66:69], v[178:181], v[240:243], v[66:69]
	s_barrier
	s_add_i32 s9, s9, s46
	v_lshl_add_u64 v[190:191], v[190:191], 0, s[72:73]
	s_mov_b32 m0, s9
	ds_read_b128 v[182:185], v149 offset:49152
	ds_read_b128 v[186:189], v149 offset:50176
	ds_read_b128 v[220:223], v149 offset:51200
	ds_read_b128 v[224:227], v149 offset:52224
	ds_read_b128 v[228:231], v149 offset:53248
	ds_read_b128 v[232:235], v149 offset:54272
	ds_read_b128 v[236:239], v149 offset:55296
	ds_read_b128 v[240:243], v149 offset:56320
	global_load_lds_dwordx4 v[190:191], off
	s_add_i32 m0, s9, 0x2000
	s_add_u32 s36, s36, 0x8080
	v_lshl_add_u64 v[190:191], v[244:245], 0, s[72:73]
	s_addc_u32 s37, s37, 0
	s_add_i32 s9, s62, s46
	global_load_lds_dwordx4 v[190:191], off
	v_lshl_add_u64 v[190:191], s[36:37], 0, v[0:1]
	s_mov_b32 m0, s9
	s_nop 0
	global_load_lds_dwordx4 v[190:191], off
	v_lshl_add_u64 v[190:191], s[36:37], 0, v[130:131]
	s_add_i32 m0, s9, 0x2000
	s_nop 0
	global_load_lds_dwordx4 v[190:191], off
	v_lshl_add_u64 v[190:191], v[246:247], 0, s[72:73]
	s_mov_b32 m0, s70
	s_nop 0
	global_load_lds_dwordx4 v[190:191], off
	v_lshl_add_u64 v[190:191], v[248:249], 0, s[72:73]
	s_mov_b32 m0, s71
	s_nop 0
	global_load_lds_dwordx4 v[190:191], off
	s_waitcnt vmcnt(8)
	s_waitcnt lgkmcnt(0)
	s_barrier
	s_waitcnt lgkmcnt(0)
	v_mfma_f32_16x16x32_bf16 v[62:65], v[140:143], v[182:185], v[62:65]
	v_mfma_f32_16x16x32_bf16 v[58:61], v[150:153], v[182:185], v[58:61]
	v_mfma_f32_16x16x32_bf16 v[54:57], v[140:143], v[220:223], v[54:57]
	v_mfma_f32_16x16x32_bf16 v[50:53], v[150:153], v[220:223], v[50:53]
	v_mfma_f32_16x16x32_bf16 v[42:45], v[140:143], v[228:231], v[42:45]
	v_mfma_f32_16x16x32_bf16 v[34:37], v[150:153], v[228:231], v[34:37]
	v_mfma_f32_16x16x32_bf16 v[26:29], v[140:143], v[236:239], v[26:29]
	v_mfma_f32_16x16x32_bf16 v[18:21], v[150:153], v[236:239], v[18:21]
	v_mfma_f32_16x16x32_bf16 v[62:65], v[144:147], v[186:189], v[62:65]
	v_mfma_f32_16x16x32_bf16 v[58:61], v[162:165], v[186:189], v[58:61]
	v_mfma_f32_16x16x32_bf16 v[54:57], v[144:147], v[224:227], v[54:57]
	v_mfma_f32_16x16x32_bf16 v[50:53], v[162:165], v[224:227], v[50:53]
	v_mfma_f32_16x16x32_bf16 v[42:45], v[144:147], v[232:235], v[42:45]
	v_mfma_f32_16x16x32_bf16 v[34:37], v[162:165], v[232:235], v[34:37]
	v_mfma_f32_16x16x32_bf16 v[26:29], v[144:147], v[240:243], v[26:29]
	v_mfma_f32_16x16x32_bf16 v[18:21], v[162:165], v[240:243], v[18:21]
	v_mfma_f32_16x16x32_bf16 v[46:49], v[166:169], v[182:185], v[46:49]
	v_mfma_f32_16x16x32_bf16 v[38:41], v[174:177], v[182:185], v[38:41]
	v_mfma_f32_16x16x32_bf16 v[30:33], v[166:169], v[220:223], v[30:33]
	v_mfma_f32_16x16x32_bf16 v[22:25], v[174:177], v[220:223], v[22:25]
	v_mfma_f32_16x16x32_bf16 v[14:17], v[166:169], v[228:231], v[14:17]
	v_mfma_f32_16x16x32_bf16 v[10:13], v[174:177], v[228:231], v[10:13]
	v_mfma_f32_16x16x32_bf16 v[6:9], v[166:169], v[236:239], v[6:9]
	v_mfma_f32_16x16x32_bf16 v[2:5], v[174:177], v[236:239], v[2:5]
	v_mfma_f32_16x16x32_bf16 v[46:49], v[170:173], v[186:189], v[46:49]
	v_mfma_f32_16x16x32_bf16 v[38:41], v[178:181], v[186:189], v[38:41]
	v_mfma_f32_16x16x32_bf16 v[30:33], v[170:173], v[224:227], v[30:33]
	v_mfma_f32_16x16x32_bf16 v[22:25], v[178:181], v[224:227], v[22:25]
	v_mfma_f32_16x16x32_bf16 v[14:17], v[170:173], v[232:235], v[14:17]
	v_mfma_f32_16x16x32_bf16 v[10:13], v[178:181], v[232:235], v[10:13]
	v_mfma_f32_16x16x32_bf16 v[6:9], v[170:173], v[240:243], v[6:9]
	v_mfma_f32_16x16x32_bf16 v[2:5], v[178:181], v[240:243], v[2:5]
	s_barrier
	s_add_u32 s34, s34, 0x100
	s_addc_u32 s35, s35, 0
	s_add_u32 vcc_lo, vcc_lo, 0x100
	s_addc_u32 vcc_hi, vcc_hi, 0
	s_cmp_ge_i32 s8, s58
	s_mov_b32 s36, s8
	s_cbranch_scc0 .LBB0_430
	s_mov_b32 s8, 0x3dd53b94
	v_pk_mul_f32 v[128:129], v[128:129], s[8:9] op_sel_hi:[1,0]
	v_pk_mul_f32 v[126:127], v[126:127], s[8:9] op_sel_hi:[1,0]
	v_pk_mul_f32 v[124:125], v[124:125], s[8:9] op_sel_hi:[1,0]
	v_pk_mul_f32 v[122:123], v[122:123], s[8:9] op_sel_hi:[1,0]
	v_pk_mul_f32 v[140:141], v[112:113], s[8:9] op_sel_hi:[1,0]
	v_pk_mul_f32 v[142:143], v[110:111], s[8:9] op_sel_hi:[1,0]
	v_pk_mul_f32 v[144:145], v[104:105], s[8:9] op_sel_hi:[1,0]
	v_pk_mul_f32 v[146:147], v[102:103], s[8:9] op_sel_hi:[1,0]
	v_pk_mul_f32 v[102:103], v[120:121], s[8:9] op_sel_hi:[1,0]
	v_pk_mul_f32 v[104:105], v[118:119], s[8:9] op_sel_hi:[1,0]
	v_pk_mul_f32 v[110:111], v[116:117], s[8:9] op_sel_hi:[1,0]
	v_pk_mul_f32 v[112:113], v[114:115], s[8:9] op_sel_hi:[1,0]
	v_pk_mul_f32 v[114:115], v[96:97], s[8:9] op_sel_hi:[1,0]
	v_pk_mul_f32 v[116:117], v[94:95], s[8:9] op_sel_hi:[1,0]
	v_pk_mul_f32 v[118:119], v[88:89], s[8:9] op_sel_hi:[1,0]
	v_pk_mul_f32 v[120:121], v[86:87], s[8:9] op_sel_hi:[1,0]
	v_pk_mul_f32 v[86:87], v[108:109], s[8:9] op_sel_hi:[1,0]
	v_pk_mul_f32 v[88:89], v[106:107], s[8:9] op_sel_hi:[1,0]
	v_pk_mul_f32 v[94:95], v[100:101], s[8:9] op_sel_hi:[1,0]
	v_pk_mul_f32 v[96:97], v[98:99], s[8:9] op_sel_hi:[1,0]
	v_pk_mul_f32 v[98:99], v[80:81], s[8:9] op_sel_hi:[1,0]
	v_pk_mul_f32 v[100:101], v[78:79], s[8:9] op_sel_hi:[1,0]
	v_pk_mul_f32 v[106:107], v[76:77], s[8:9] op_sel_hi:[1,0]
	v_pk_mul_f32 v[108:109], v[74:75], s[8:9] op_sel_hi:[1,0]
	v_pk_mul_f32 v[74:75], v[92:93], s[8:9] op_sel_hi:[1,0]
	v_pk_mul_f32 v[76:77], v[90:91], s[8:9] op_sel_hi:[1,0]
	v_pk_mul_f32 v[78:79], v[84:85], s[8:9] op_sel_hi:[1,0]
	v_pk_mul_f32 v[80:81], v[82:83], s[8:9] op_sel_hi:[1,0]
	v_pk_mul_f32 v[72:73], v[72:73], s[8:9] op_sel_hi:[1,0]
	v_pk_mul_f32 v[70:71], v[70:71], s[8:9] op_sel_hi:[1,0]
	v_pk_mul_f32 v[68:69], v[68:69], s[8:9] op_sel_hi:[1,0]
	v_pk_mul_f32 v[66:67], v[66:67], s[8:9] op_sel_hi:[1,0]
	v_pk_mul_f32 v[64:65], v[64:65], s[8:9] op_sel_hi:[1,0]
	v_pk_mul_f32 v[62:63], v[62:63], s[8:9] op_sel_hi:[1,0]
	v_pk_mul_f32 v[60:61], v[60:61], s[8:9] op_sel_hi:[1,0]
	v_pk_mul_f32 v[58:59], v[58:59], s[8:9] op_sel_hi:[1,0]
	v_pk_mul_f32 v[82:83], v[48:49], s[8:9] op_sel_hi:[1,0]
	v_pk_mul_f32 v[84:85], v[46:47], s[8:9] op_sel_hi:[1,0]
	v_pk_mul_f32 v[90:91], v[40:41], s[8:9] op_sel_hi:[1,0]
	v_pk_mul_f32 v[92:93], v[38:39], s[8:9] op_sel_hi:[1,0]
	v_pk_mul_f32 v[38:39], v[56:57], s[8:9] op_sel_hi:[1,0]
	v_pk_mul_f32 v[40:41], v[54:55], s[8:9] op_sel_hi:[1,0]
	v_pk_mul_f32 v[46:47], v[52:53], s[8:9] op_sel_hi:[1,0]
	v_pk_mul_f32 v[48:49], v[50:51], s[8:9] op_sel_hi:[1,0]
	v_pk_mul_f32 v[50:51], v[32:33], s[8:9] op_sel_hi:[1,0]
	v_pk_mul_f32 v[52:53], v[30:31], s[8:9] op_sel_hi:[1,0]
	v_pk_mul_f32 v[54:55], v[24:25], s[8:9] op_sel_hi:[1,0]
	v_pk_mul_f32 v[56:57], v[22:23], s[8:9] op_sel_hi:[1,0]
	v_pk_mul_f32 v[22:23], v[44:45], s[8:9] op_sel_hi:[1,0]
	v_pk_mul_f32 v[24:25], v[42:43], s[8:9] op_sel_hi:[1,0]
	v_pk_mul_f32 v[30:31], v[36:37], s[8:9] op_sel_hi:[1,0]
	v_pk_mul_f32 v[32:33], v[34:35], s[8:9] op_sel_hi:[1,0]
	v_pk_mul_f32 v[34:35], v[16:17], s[8:9] op_sel_hi:[1,0]
	v_pk_mul_f32 v[36:37], v[14:15], s[8:9] op_sel_hi:[1,0]
	v_pk_mul_f32 v[42:43], v[12:13], s[8:9] op_sel_hi:[1,0]
	v_pk_mul_f32 v[44:45], v[10:11], s[8:9] op_sel_hi:[1,0]
	v_pk_mul_f32 v[10:11], v[28:29], s[8:9] op_sel_hi:[1,0]
	v_pk_mul_f32 v[12:13], v[26:27], s[8:9] op_sel_hi:[1,0]
	v_pk_mul_f32 v[14:15], v[20:21], s[8:9] op_sel_hi:[1,0]
	v_pk_mul_f32 v[16:17], v[18:19], s[8:9] op_sel_hi:[1,0]
	v_pk_mul_f32 v[8:9], v[8:9], s[8:9] op_sel_hi:[1,0]
	v_pk_mul_f32 v[6:7], v[6:7], s[8:9] op_sel_hi:[1,0]
	v_pk_mul_f32 v[4:5], v[4:5], s[8:9] op_sel_hi:[1,0]
	v_pk_mul_f32 v[2:3], v[2:3], s[8:9] op_sel_hi:[1,0]
	v_readlane_b32 s91, v255, 35
	s_mov_b32 s63, 0x8000

.LBB0_460:
	s_add_i32 s8, s28, 2
	s_add_u32 s26, s24, 0x100
	s_addc_u32 s27, s25, 0
	s_add_i32 s9, 0, 0x10000
	s_cmp_eq_u32 s49, s28
	s_cselect_b32 s31, s7, s27
	s_cselect_b32 s30, s6, s26
	v_add_u32_e32 v0, s9, v146
	s_cselect_b32 s29, s23, s77
	s_cselect_b32 s28, s22, s75
	s_add_i32 s62, 0, 0x14000
	ds_read_b128 v[142:145], v0
	ds_read_b128 v[148:151], v0 offset:1024
	ds_read_b128 v[162:165], v0 offset:2048
	ds_read_b128 v[166:169], v0 offset:3072
	v_add_u32_e32 v0, s62, v146
	ds_read_b128 v[170:173], v0
	ds_read_b128 v[174:177], v0 offset:1024
	ds_read_b128 v[178:181], v0 offset:2048
	ds_read_b128 v[182:185], v0 offset:3072
	v_lshl_add_u64 v[152:153], s[24:25], 0, v[138:139]
	s_add_i32 m0, s37, 0xc000
	ds_read_b128 v[186:189], v147
	ds_read_b128 v[220:223], v147 offset:1024
	ds_read_b128 v[224:227], v147 offset:2048
	ds_read_b128 v[228:231], v147 offset:3072
	ds_read_b128 v[232:235], v147 offset:4096
	ds_read_b128 v[236:239], v147 offset:5120
	ds_read_b128 v[240:243], v147 offset:6144
	ds_read_b128 v[244:247], v147 offset:7168
	global_load_lds_dwordx4 v[152:153], off
	v_lshl_add_u64 v[152:153], s[24:25], 0, v[140:141]
	s_add_i32 m0, s37, 0xe000
	s_nop 0
	global_load_lds_dwordx4 v[152:153], off
	s_waitcnt vmcnt(8)
	s_waitcnt lgkmcnt(0)
	s_barrier
	s_waitcnt lgkmcnt(0)
	v_mfma_f32_16x16x32_bf16 v[122:125], v[142:145], v[186:189], v[122:125]
	v_mfma_f32_16x16x32_bf16 v[126:129], v[162:165], v[186:189], v[126:129]
	v_mfma_f32_16x16x32_bf16 v[118:121], v[142:145], v[224:227], v[118:121]
	v_mfma_f32_16x16x32_bf16 v[114:117], v[162:165], v[224:227], v[114:117]
	v_mfma_f32_16x16x32_bf16 v[110:113], v[142:145], v[232:235], v[110:113]
	v_mfma_f32_16x16x32_bf16 v[106:109], v[162:165], v[232:235], v[106:109]
	v_mfma_f32_16x16x32_bf16 v[102:105], v[142:145], v[240:243], v[102:105]
	v_mfma_f32_16x16x32_bf16 v[98:101], v[162:165], v[240:243], v[98:101]
	v_mfma_f32_16x16x32_bf16 v[122:125], v[148:151], v[220:223], v[122:125]
	v_mfma_f32_16x16x32_bf16 v[126:129], v[166:169], v[220:223], v[126:129]
	v_mfma_f32_16x16x32_bf16 v[118:121], v[148:151], v[228:231], v[118:121]
	v_mfma_f32_16x16x32_bf16 v[114:117], v[166:169], v[228:231], v[114:117]
	v_mfma_f32_16x16x32_bf16 v[110:113], v[148:151], v[236:239], v[110:113]
	v_mfma_f32_16x16x32_bf16 v[106:109], v[166:169], v[236:239], v[106:109]
	v_mfma_f32_16x16x32_bf16 v[102:105], v[148:151], v[244:247], v[102:105]
	v_mfma_f32_16x16x32_bf16 v[98:101], v[166:169], v[244:247], v[98:101]
	v_mfma_f32_16x16x32_bf16 v[62:65], v[170:173], v[186:189], v[62:65]
	v_mfma_f32_16x16x32_bf16 v[58:61], v[178:181], v[186:189], v[58:61]
	v_mfma_f32_16x16x32_bf16 v[54:57], v[170:173], v[224:227], v[54:57]
	v_mfma_f32_16x16x32_bf16 v[50:53], v[178:181], v[224:227], v[50:53]
	v_mfma_f32_16x16x32_bf16 v[46:49], v[170:173], v[232:235], v[46:49]
	v_mfma_f32_16x16x32_bf16 v[42:45], v[178:181], v[232:235], v[42:45]
	v_mfma_f32_16x16x32_bf16 v[38:41], v[170:173], v[240:243], v[38:41]
	v_mfma_f32_16x16x32_bf16 v[34:37], v[178:181], v[240:243], v[34:37]
	v_mfma_f32_16x16x32_bf16 v[62:65], v[174:177], v[220:223], v[62:65]
	v_mfma_f32_16x16x32_bf16 v[58:61], v[182:185], v[220:223], v[58:61]
	v_mfma_f32_16x16x32_bf16 v[54:57], v[174:177], v[228:231], v[54:57]
	v_mfma_f32_16x16x32_bf16 v[50:53], v[182:185], v[228:231], v[50:53]
	v_mfma_f32_16x16x32_bf16 v[46:49], v[174:177], v[236:239], v[46:49]
	v_mfma_f32_16x16x32_bf16 v[42:45], v[182:185], v[236:239], v[42:45]
	v_mfma_f32_16x16x32_bf16 v[38:41], v[174:177], v[244:247], v[38:41]
	v_mfma_f32_16x16x32_bf16 v[34:37], v[182:185], v[244:247], v[34:37]
	s_barrier
	s_add_i32 s9, s9, s34
	v_lshl_add_u64 v[152:153], s[28:29], 0, v[134:135]
	s_mov_b32 m0, s9
	ds_read_b128 v[186:189], v147 offset:16384
	ds_read_b128 v[220:223], v147 offset:17408
	ds_read_b128 v[224:227], v147 offset:18432
	ds_read_b128 v[228:231], v147 offset:19456
	ds_read_b128 v[232:235], v147 offset:20480
	ds_read_b128 v[236:239], v147 offset:21504
	ds_read_b128 v[240:243], v147 offset:22528
	ds_read_b128 v[244:247], v147 offset:23552
	global_load_lds_dwordx4 v[152:153], off
	s_add_i32 m0, s9, 0x2000
	s_add_u32 s24, s28, 0x18000
	v_lshl_add_u64 v[190:191], s[28:29], 0, v[130:131]
	s_addc_u32 s25, s29, 0
	s_add_i32 s9, s62, s34
	global_load_lds_dwordx4 v[190:191], off
	v_lshl_add_u64 v[248:249], s[24:25], 0, v[134:135]
	s_mov_b32 m0, s9
	v_lshl_add_u64 v[250:251], s[30:31], 0, v[132:133]
	global_load_lds_dwordx4 v[248:249], off
	v_lshl_add_u64 v[248:249], s[24:25], 0, v[130:131]
	s_add_i32 m0, s9, 0x2000
	s_nop 0
	global_load_lds_dwordx4 v[248:249], off
	v_lshl_add_u64 v[248:249], s[30:31], 0, v[136:137]
	s_mov_b32 m0, s37
	s_nop 0
	global_load_lds_dwordx4 v[248:249], off
	s_mov_b32 m0, s38
	s_nop 0
	global_load_lds_dwordx4 v[250:251], off
	s_waitcnt vmcnt(8)
	s_waitcnt lgkmcnt(0)
	s_barrier
	s_waitcnt lgkmcnt(0)
	v_mfma_f32_16x16x32_bf16 v[94:97], v[142:145], v[186:189], v[94:97]
	v_mfma_f32_16x16x32_bf16 v[90:93], v[162:165], v[186:189], v[90:93]
	v_mfma_f32_16x16x32_bf16 v[86:89], v[142:145], v[224:227], v[86:89]
	v_mfma_f32_16x16x32_bf16 v[82:85], v[162:165], v[224:227], v[82:85]
	v_mfma_f32_16x16x32_bf16 v[78:81], v[142:145], v[232:235], v[78:81]
	v_mfma_f32_16x16x32_bf16 v[74:77], v[162:165], v[232:235], v[74:77]
	v_mfma_f32_16x16x32_bf16 v[70:73], v[142:145], v[240:243], v[70:73]
	v_mfma_f32_16x16x32_bf16 v[66:69], v[162:165], v[240:243], v[66:69]
	v_mfma_f32_16x16x32_bf16 v[94:97], v[148:151], v[220:223], v[94:97]
	v_mfma_f32_16x16x32_bf16 v[90:93], v[166:169], v[220:223], v[90:93]
	v_mfma_f32_16x16x32_bf16 v[86:89], v[148:151], v[228:231], v[86:89]
	v_mfma_f32_16x16x32_bf16 v[82:85], v[166:169], v[228:231], v[82:85]
	v_mfma_f32_16x16x32_bf16 v[78:81], v[148:151], v[236:239], v[78:81]
	v_mfma_f32_16x16x32_bf16 v[74:77], v[166:169], v[236:239], v[74:77]
	v_mfma_f32_16x16x32_bf16 v[70:73], v[148:151], v[244:247], v[70:73]
	v_mfma_f32_16x16x32_bf16 v[66:69], v[166:169], v[244:247], v[66:69]
	v_mfma_f32_16x16x32_bf16 v[30:33], v[170:173], v[186:189], v[30:33]
	v_mfma_f32_16x16x32_bf16 v[26:29], v[178:181], v[186:189], v[26:29]
	v_mfma_f32_16x16x32_bf16 v[22:25], v[170:173], v[224:227], v[22:25]
	v_mfma_f32_16x16x32_bf16 v[18:21], v[178:181], v[224:227], v[18:21]
	v_mfma_f32_16x16x32_bf16 v[14:17], v[170:173], v[232:235], v[14:17]
	v_mfma_f32_16x16x32_bf16 v[10:13], v[178:181], v[232:235], v[10:13]
	v_mfma_f32_16x16x32_bf16 v[6:9], v[170:173], v[240:243], v[6:9]
	v_mfma_f32_16x16x32_bf16 v[2:5], v[178:181], v[240:243], v[2:5]
	v_mfma_f32_16x16x32_bf16 v[30:33], v[174:177], v[220:223], v[30:33]
	v_mfma_f32_16x16x32_bf16 v[26:29], v[182:185], v[220:223], v[26:29]
	v_mfma_f32_16x16x32_bf16 v[22:25], v[174:177], v[228:231], v[22:25]
	v_mfma_f32_16x16x32_bf16 v[18:21], v[182:185], v[228:231], v[18:21]
	v_mfma_f32_16x16x32_bf16 v[14:17], v[174:177], v[236:239], v[14:17]
	v_mfma_f32_16x16x32_bf16 v[10:13], v[182:185], v[236:239], v[10:13]
	v_mfma_f32_16x16x32_bf16 v[6:9], v[174:177], v[244:247], v[6:9]
	v_mfma_f32_16x16x32_bf16 v[2:5], v[182:185], v[244:247], v[2:5]
	s_barrier
	s_add_i32 s9, 0, 0x18000
	v_add_u32_e32 v0, s9, v146
	s_add_i32 s62, 0, 0x1c000
	ds_read_b128 v[142:145], v0
	ds_read_b128 v[148:151], v0 offset:1024
	ds_read_b128 v[162:165], v0 offset:2048
	ds_read_b128 v[166:169], v0 offset:3072
	v_add_u32_e32 v0, s62, v146
	ds_read_b128 v[170:173], v0
	ds_read_b128 v[174:177], v0 offset:1024
	ds_read_b128 v[178:181], v0 offset:2048
	ds_read_b128 v[182:185], v0 offset:3072
	s_add_u32 s24, s30, 0x18000
	s_addc_u32 s25, s31, 0
	s_mov_b32 m0, s39
	v_lshl_add_u64 v[252:253], s[24:25], 0, v[136:137]
	ds_read_b128 v[186:189], v147 offset:32768
	ds_read_b128 v[220:223], v147 offset:33792
	ds_read_b128 v[224:227], v147 offset:34816
	ds_read_b128 v[228:231], v147 offset:35840
	ds_read_b128 v[232:235], v147 offset:36864
	ds_read_b128 v[236:239], v147 offset:37888
	ds_read_b128 v[240:243], v147 offset:38912
	ds_read_b128 v[244:247], v147 offset:39936
	global_load_lds_dwordx4 v[252:253], off
	v_lshl_add_u64 v[252:253], s[24:25], 0, v[132:133]
	s_mov_b32 m0, s42
	s_nop 0
	global_load_lds_dwordx4 v[252:253], off
	s_waitcnt vmcnt(8)
	s_waitcnt lgkmcnt(0)
	s_barrier
	s_waitcnt lgkmcnt(0)
	v_mfma_f32_16x16x32_bf16 v[122:125], v[142:145], v[186:189], v[122:125]
	v_mfma_f32_16x16x32_bf16 v[126:129], v[162:165], v[186:189], v[126:129]
	v_mfma_f32_16x16x32_bf16 v[118:121], v[142:145], v[224:227], v[118:121]
	v_mfma_f32_16x16x32_bf16 v[114:117], v[162:165], v[224:227], v[114:117]
	v_mfma_f32_16x16x32_bf16 v[110:113], v[142:145], v[232:235], v[110:113]
	v_mfma_f32_16x16x32_bf16 v[106:109], v[162:165], v[232:235], v[106:109]
	v_mfma_f32_16x16x32_bf16 v[102:105], v[142:145], v[240:243], v[102:105]
	v_mfma_f32_16x16x32_bf16 v[98:101], v[162:165], v[240:243], v[98:101]
	v_mfma_f32_16x16x32_bf16 v[122:125], v[148:151], v[220:223], v[122:125]
	v_mfma_f32_16x16x32_bf16 v[126:129], v[166:169], v[220:223], v[126:129]
	v_mfma_f32_16x16x32_bf16 v[118:121], v[148:151], v[228:231], v[118:121]
	v_mfma_f32_16x16x32_bf16 v[114:117], v[166:169], v[228:231], v[114:117]
	v_mfma_f32_16x16x32_bf16 v[110:113], v[148:151], v[236:239], v[110:113]
	v_mfma_f32_16x16x32_bf16 v[106:109], v[166:169], v[236:239], v[106:109]
	v_mfma_f32_16x16x32_bf16 v[102:105], v[148:151], v[244:247], v[102:105]
	v_mfma_f32_16x16x32_bf16 v[98:101], v[166:169], v[244:247], v[98:101]
	v_mfma_f32_16x16x32_bf16 v[62:65], v[170:173], v[186:189], v[62:65]
	v_mfma_f32_16x16x32_bf16 v[58:61], v[178:181], v[186:189], v[58:61]
	v_mfma_f32_16x16x32_bf16 v[54:57], v[170:173], v[224:227], v[54:57]
	v_mfma_f32_16x16x32_bf16 v[50:53], v[178:181], v[224:227], v[50:53]
	v_mfma_f32_16x16x32_bf16 v[46:49], v[170:173], v[232:235], v[46:49]
	v_mfma_f32_16x16x32_bf16 v[42:45], v[178:181], v[232:235], v[42:45]
	v_mfma_f32_16x16x32_bf16 v[38:41], v[170:173], v[240:243], v[38:41]
	v_mfma_f32_16x16x32_bf16 v[34:37], v[178:181], v[240:243], v[34:37]
	v_mfma_f32_16x16x32_bf16 v[62:65], v[174:177], v[220:223], v[62:65]
	v_mfma_f32_16x16x32_bf16 v[58:61], v[182:185], v[220:223], v[58:61]
	v_mfma_f32_16x16x32_bf16 v[54:57], v[174:177], v[228:231], v[54:57]
	v_mfma_f32_16x16x32_bf16 v[50:53], v[182:185], v[228:231], v[50:53]
	v_mfma_f32_16x16x32_bf16 v[46:49], v[174:177], v[236:239], v[46:49]
	v_mfma_f32_16x16x32_bf16 v[42:45], v[182:185], v[236:239], v[42:45]
	v_mfma_f32_16x16x32_bf16 v[38:41], v[174:177], v[244:247], v[38:41]
	v_mfma_f32_16x16x32_bf16 v[34:37], v[182:185], v[244:247], v[34:37]
	s_barrier
	s_add_i32 s9, s9, s34
	v_lshl_add_u64 v[152:153], v[152:153], 0, s[72:73]
	s_mov_b32 m0, s9
	ds_read_b128 v[186:189], v147 offset:49152
	ds_read_b128 v[220:223], v147 offset:50176
	ds_read_b128 v[224:227], v147 offset:51200
	ds_read_b128 v[228:231], v147 offset:52224
	ds_read_b128 v[232:235], v147 offset:53248
	ds_read_b128 v[236:239], v147 offset:54272
	ds_read_b128 v[240:243], v147 offset:55296
	ds_read_b128 v[244:247], v147 offset:56320
	global_load_lds_dwordx4 v[152:153], off
	s_add_i32 m0, s9, 0x2000
	s_add_u32 s24, s28, 0x18080
	v_lshl_add_u64 v[152:153], v[190:191], 0, s[72:73]
	s_addc_u32 s25, s29, 0
	s_add_i32 s9, s62, s34
	global_load_lds_dwordx4 v[152:153], off
	v_lshl_add_u64 v[152:153], s[24:25], 0, v[134:135]
	s_mov_b32 m0, s9
	s_nop 0
	global_load_lds_dwordx4 v[152:153], off
	v_lshl_add_u64 v[152:153], s[24:25], 0, v[130:131]
	s_add_i32 m0, s9, 0x2000
	s_nop 0
	global_load_lds_dwordx4 v[152:153], off
	v_lshl_add_u64 v[152:153], v[248:249], 0, s[72:73]
	s_mov_b32 m0, s47
	s_nop 0
	global_load_lds_dwordx4 v[152:153], off
	v_lshl_add_u64 v[152:153], v[250:251], 0, s[72:73]
	s_mov_b32 m0, s48
	s_nop 0
	global_load_lds_dwordx4 v[152:153], off
	s_waitcnt vmcnt(8)
	s_waitcnt lgkmcnt(0)
	s_barrier
	s_waitcnt lgkmcnt(0)
	v_mfma_f32_16x16x32_bf16 v[94:97], v[142:145], v[186:189], v[94:97]
	v_mfma_f32_16x16x32_bf16 v[90:93], v[162:165], v[186:189], v[90:93]
	v_mfma_f32_16x16x32_bf16 v[86:89], v[142:145], v[224:227], v[86:89]
	v_mfma_f32_16x16x32_bf16 v[82:85], v[162:165], v[224:227], v[82:85]
	v_mfma_f32_16x16x32_bf16 v[78:81], v[142:145], v[232:235], v[78:81]
	v_mfma_f32_16x16x32_bf16 v[74:77], v[162:165], v[232:235], v[74:77]
	v_mfma_f32_16x16x32_bf16 v[70:73], v[142:145], v[240:243], v[70:73]
	v_mfma_f32_16x16x32_bf16 v[66:69], v[162:165], v[240:243], v[66:69]
	v_mfma_f32_16x16x32_bf16 v[94:97], v[148:151], v[220:223], v[94:97]
	v_mfma_f32_16x16x32_bf16 v[90:93], v[166:169], v[220:223], v[90:93]
	v_mfma_f32_16x16x32_bf16 v[86:89], v[148:151], v[228:231], v[86:89]
	v_mfma_f32_16x16x32_bf16 v[82:85], v[166:169], v[228:231], v[82:85]
	v_mfma_f32_16x16x32_bf16 v[78:81], v[148:151], v[236:239], v[78:81]
	v_mfma_f32_16x16x32_bf16 v[74:77], v[166:169], v[236:239], v[74:77]
	v_mfma_f32_16x16x32_bf16 v[70:73], v[148:151], v[244:247], v[70:73]
	v_mfma_f32_16x16x32_bf16 v[66:69], v[166:169], v[244:247], v[66:69]
	v_mfma_f32_16x16x32_bf16 v[30:33], v[170:173], v[186:189], v[30:33]
	v_mfma_f32_16x16x32_bf16 v[26:29], v[178:181], v[186:189], v[26:29]
	v_mfma_f32_16x16x32_bf16 v[22:25], v[170:173], v[224:227], v[22:25]
	v_mfma_f32_16x16x32_bf16 v[18:21], v[178:181], v[224:227], v[18:21]
	v_mfma_f32_16x16x32_bf16 v[14:17], v[170:173], v[232:235], v[14:17]
	v_mfma_f32_16x16x32_bf16 v[10:13], v[178:181], v[232:235], v[10:13]
	v_mfma_f32_16x16x32_bf16 v[6:9], v[170:173], v[240:243], v[6:9]
	v_mfma_f32_16x16x32_bf16 v[2:5], v[178:181], v[240:243], v[2:5]
	v_mfma_f32_16x16x32_bf16 v[30:33], v[174:177], v[220:223], v[30:33]
	v_mfma_f32_16x16x32_bf16 v[26:29], v[182:185], v[220:223], v[26:29]
	v_mfma_f32_16x16x32_bf16 v[22:25], v[174:177], v[228:231], v[22:25]
	v_mfma_f32_16x16x32_bf16 v[18:21], v[182:185], v[228:231], v[18:21]
	v_mfma_f32_16x16x32_bf16 v[14:17], v[174:177], v[236:239], v[14:17]
	v_mfma_f32_16x16x32_bf16 v[10:13], v[182:185], v[236:239], v[10:13]
	v_mfma_f32_16x16x32_bf16 v[6:9], v[174:177], v[244:247], v[6:9]
	v_mfma_f32_16x16x32_bf16 v[2:5], v[182:185], v[244:247], v[2:5]
	s_barrier
	s_add_u32 s75, s75, 0x100
	s_addc_u32 s77, s77, 0
	s_cmp_ge_i32 s8, s43
	s_mov_b64 s[24:25], s[26:27]
	s_mov_b32 s28, s8
	s_cbranch_scc0 .LBB0_460

.LBB0_503:
	s_add_i32 s77, s34, 2
	s_add_u32 s8, s30, 0xfffc0080
	s_addc_u32 s9, s31, -1
	s_add_i32 s62, 0, 0x10000
	s_cmp_eq_u32 s57, s34
	s_cselect_b32 s37, s21, s9
	s_cselect_b32 s36, s23, s8
	s_cselect_b32 s35, s70, s75
	s_cselect_b32 s34, s71, s74
	s_add_i32 s63, 0, 0x14000
	v_add_u32_e32 v150, s62, v136
	v_add_u32_e32 v161, s63, v136
	ds_read_b128 v[138:141], v150
	ds_read_b128 v[142:145], v150 offset:1024
	ds_read_b128 v[146:149], v150 offset:2048
	ds_read_b128 v[150:153], v150 offset:3072
	ds_read_b128 v[162:165], v161
	ds_read_b128 v[166:169], v161 offset:1024
	ds_read_b128 v[170:173], v161 offset:2048
	ds_read_b128 v[174:177], v161 offset:3072
	v_lshl_add_u64 v[190:191], s[30:31], 0, v[132:133]
	s_add_i32 m0, s25, 0xc000
	ds_read_b128 v[178:181], v137
	ds_read_b128 v[182:185], v137 offset:1024
	ds_read_b128 v[186:189], v137 offset:2048
	ds_read_b128 v[220:223], v137 offset:3072
	ds_read_b128 v[224:227], v137 offset:4096
	ds_read_b128 v[228:231], v137 offset:5120
	ds_read_b128 v[232:235], v137 offset:6144
	ds_read_b128 v[236:239], v137 offset:7168
	global_load_lds_dwordx4 v[190:191], off
	v_lshl_add_u64 v[190:191], s[30:31], 0, v[134:135]
	s_add_i32 m0, s25, 0xe000
	s_nop 0
	global_load_lds_dwordx4 v[190:191], off
	s_waitcnt vmcnt(8)
	s_waitcnt lgkmcnt(0)
	s_barrier
	s_waitcnt lgkmcnt(0)
	v_mfma_f32_16x16x32_bf16 v[126:129], v[138:141], v[178:181], v[126:129]
	v_mfma_f32_16x16x32_bf16 v[122:125], v[146:149], v[178:181], v[122:125]
	v_mfma_f32_16x16x32_bf16 v[110:113], v[138:141], v[186:189], v[110:113]
	v_mfma_f32_16x16x32_bf16 v[106:109], v[146:149], v[186:189], v[106:109]
	v_mfma_f32_16x16x32_bf16 v[94:97], v[138:141], v[224:227], v[94:97]
	v_mfma_f32_16x16x32_bf16 v[90:93], v[146:149], v[224:227], v[90:93]
	v_mfma_f32_16x16x32_bf16 v[78:81], v[138:141], v[232:235], v[78:81]
	v_mfma_f32_16x16x32_bf16 v[74:77], v[146:149], v[232:235], v[74:77]
	v_mfma_f32_16x16x32_bf16 v[126:129], v[142:145], v[182:185], v[126:129]
	v_mfma_f32_16x16x32_bf16 v[122:125], v[150:153], v[182:185], v[122:125]
	v_mfma_f32_16x16x32_bf16 v[110:113], v[142:145], v[220:223], v[110:113]
	v_mfma_f32_16x16x32_bf16 v[106:109], v[150:153], v[220:223], v[106:109]
	v_mfma_f32_16x16x32_bf16 v[94:97], v[142:145], v[228:231], v[94:97]
	v_mfma_f32_16x16x32_bf16 v[90:93], v[150:153], v[228:231], v[90:93]
	v_mfma_f32_16x16x32_bf16 v[78:81], v[142:145], v[236:239], v[78:81]
	v_mfma_f32_16x16x32_bf16 v[74:77], v[150:153], v[236:239], v[74:77]
	v_mfma_f32_16x16x32_bf16 v[118:121], v[162:165], v[178:181], v[118:121]
	v_mfma_f32_16x16x32_bf16 v[114:117], v[170:173], v[178:181], v[114:117]
	v_mfma_f32_16x16x32_bf16 v[102:105], v[162:165], v[186:189], v[102:105]
	v_mfma_f32_16x16x32_bf16 v[98:101], v[170:173], v[186:189], v[98:101]
	v_mfma_f32_16x16x32_bf16 v[86:89], v[162:165], v[224:227], v[86:89]
	v_mfma_f32_16x16x32_bf16 v[82:85], v[170:173], v[224:227], v[82:85]
	v_mfma_f32_16x16x32_bf16 v[70:73], v[162:165], v[232:235], v[70:73]
	v_mfma_f32_16x16x32_bf16 v[66:69], v[170:173], v[232:235], v[66:69]
	v_mfma_f32_16x16x32_bf16 v[118:121], v[166:169], v[182:185], v[118:121]
	v_mfma_f32_16x16x32_bf16 v[114:117], v[174:177], v[182:185], v[114:117]
	v_mfma_f32_16x16x32_bf16 v[102:105], v[166:169], v[220:223], v[102:105]
	v_mfma_f32_16x16x32_bf16 v[98:101], v[174:177], v[220:223], v[98:101]
	v_mfma_f32_16x16x32_bf16 v[86:89], v[166:169], v[228:231], v[86:89]
	v_mfma_f32_16x16x32_bf16 v[82:85], v[174:177], v[228:231], v[82:85]
	v_mfma_f32_16x16x32_bf16 v[70:73], v[166:169], v[236:239], v[70:73]
	v_mfma_f32_16x16x32_bf16 v[66:69], v[174:177], v[236:239], v[66:69]
	s_barrier
	s_add_i32 s8, s62, s38
	v_lshl_add_u64 v[190:191], s[34:35], 0, v[0:1]
	s_mov_b32 m0, s8
	ds_read_b128 v[178:181], v137 offset:16384
	ds_read_b128 v[182:185], v137 offset:17408
	ds_read_b128 v[186:189], v137 offset:18432
	ds_read_b128 v[220:223], v137 offset:19456
	ds_read_b128 v[224:227], v137 offset:20480
	ds_read_b128 v[228:231], v137 offset:21504
	ds_read_b128 v[232:235], v137 offset:22528
	ds_read_b128 v[236:239], v137 offset:23552
	global_load_lds_dwordx4 v[190:191], off
	s_add_i32 m0, s8, 0x2000
	s_add_u32 s8, s34, 0x40000
	v_lshl_add_u64 v[240:241], s[34:35], 0, v[130:131]
	s_addc_u32 s9, s35, 0
	s_add_i32 s62, s63, s38
	global_load_lds_dwordx4 v[240:241], off
	v_lshl_add_u64 v[242:243], s[8:9], 0, v[0:1]
	s_mov_b32 m0, s62
	v_lshl_add_u64 v[244:245], s[36:37], 0, v[130:131]
	global_load_lds_dwordx4 v[242:243], off
	v_lshl_add_u64 v[242:243], s[8:9], 0, v[130:131]
	s_add_i32 m0, s62, 0x2000
	s_nop 0
	global_load_lds_dwordx4 v[242:243], off
	v_lshl_add_u64 v[242:243], s[36:37], 0, v[0:1]
	s_mov_b32 m0, s25
	s_nop 0
	global_load_lds_dwordx4 v[242:243], off
	s_mov_b32 m0, s42
	s_nop 0
	global_load_lds_dwordx4 v[244:245], off
	s_waitcnt vmcnt(8)
	s_waitcnt lgkmcnt(0)
	s_barrier
	s_waitcnt lgkmcnt(0)
	v_mfma_f32_16x16x32_bf16 v[62:65], v[138:141], v[178:181], v[62:65]
	v_mfma_f32_16x16x32_bf16 v[58:61], v[146:149], v[178:181], v[58:61]
	v_mfma_f32_16x16x32_bf16 v[46:49], v[138:141], v[186:189], v[46:49]
	v_mfma_f32_16x16x32_bf16 v[42:45], v[146:149], v[186:189], v[42:45]
	v_mfma_f32_16x16x32_bf16 v[30:33], v[138:141], v[224:227], v[30:33]
	v_mfma_f32_16x16x32_bf16 v[26:29], v[146:149], v[224:227], v[26:29]
	v_mfma_f32_16x16x32_bf16 v[14:17], v[138:141], v[232:235], v[14:17]
	v_mfma_f32_16x16x32_bf16 v[10:13], v[146:149], v[232:235], v[10:13]
	v_mfma_f32_16x16x32_bf16 v[62:65], v[142:145], v[182:185], v[62:65]
	v_mfma_f32_16x16x32_bf16 v[58:61], v[150:153], v[182:185], v[58:61]
	v_mfma_f32_16x16x32_bf16 v[46:49], v[142:145], v[220:223], v[46:49]
	v_mfma_f32_16x16x32_bf16 v[42:45], v[150:153], v[220:223], v[42:45]
	v_mfma_f32_16x16x32_bf16 v[30:33], v[142:145], v[228:231], v[30:33]
	v_mfma_f32_16x16x32_bf16 v[26:29], v[150:153], v[228:231], v[26:29]
	v_mfma_f32_16x16x32_bf16 v[14:17], v[142:145], v[236:239], v[14:17]
	v_mfma_f32_16x16x32_bf16 v[10:13], v[150:153], v[236:239], v[10:13]
	v_mfma_f32_16x16x32_bf16 v[54:57], v[162:165], v[178:181], v[54:57]
	v_mfma_f32_16x16x32_bf16 v[50:53], v[170:173], v[178:181], v[50:53]
	v_mfma_f32_16x16x32_bf16 v[38:41], v[162:165], v[186:189], v[38:41]
	v_mfma_f32_16x16x32_bf16 v[34:37], v[170:173], v[186:189], v[34:37]
	v_mfma_f32_16x16x32_bf16 v[22:25], v[162:165], v[224:227], v[22:25]
	v_mfma_f32_16x16x32_bf16 v[18:21], v[170:173], v[224:227], v[18:21]
	v_mfma_f32_16x16x32_bf16 v[6:9], v[162:165], v[232:235], v[6:9]
	v_mfma_f32_16x16x32_bf16 v[2:5], v[170:173], v[232:235], v[2:5]
	v_mfma_f32_16x16x32_bf16 v[54:57], v[166:169], v[182:185], v[54:57]
	v_mfma_f32_16x16x32_bf16 v[50:53], v[174:177], v[182:185], v[50:53]
	v_mfma_f32_16x16x32_bf16 v[38:41], v[166:169], v[220:223], v[38:41]
	v_mfma_f32_16x16x32_bf16 v[34:37], v[174:177], v[220:223], v[34:37]
	v_mfma_f32_16x16x32_bf16 v[22:25], v[166:169], v[228:231], v[22:25]
	v_mfma_f32_16x16x32_bf16 v[18:21], v[174:177], v[228:231], v[18:21]
	v_mfma_f32_16x16x32_bf16 v[6:9], v[166:169], v[236:239], v[6:9]
	v_mfma_f32_16x16x32_bf16 v[2:5], v[174:177], v[236:239], v[2:5]
	s_barrier
	s_add_i32 s62, 0, 0x18000
	s_add_i32 s63, 0, 0x1c000
	v_add_u32_e32 v150, s62, v136
	v_add_u32_e32 v161, s63, v136
	ds_read_b128 v[138:141], v150
	ds_read_b128 v[142:145], v150 offset:1024
	ds_read_b128 v[146:149], v150 offset:2048
	ds_read_b128 v[150:153], v150 offset:3072
	ds_read_b128 v[162:165], v161
	ds_read_b128 v[166:169], v161 offset:1024
	ds_read_b128 v[170:173], v161 offset:2048
	ds_read_b128 v[174:177], v161 offset:3072
	s_add_u32 s8, s36, 0x40000
	s_addc_u32 s9, s37, 0
	s_mov_b32 m0, s43
	v_lshl_add_u64 v[246:247], s[8:9], 0, v[0:1]
	ds_read_b128 v[178:181], v137 offset:32768
	ds_read_b128 v[182:185], v137 offset:33792
	ds_read_b128 v[186:189], v137 offset:34816
	ds_read_b128 v[220:223], v137 offset:35840
	ds_read_b128 v[224:227], v137 offset:36864
	ds_read_b128 v[228:231], v137 offset:37888
	ds_read_b128 v[232:235], v137 offset:38912
	ds_read_b128 v[236:239], v137 offset:39936
	global_load_lds_dwordx4 v[246:247], off
	v_lshl_add_u64 v[246:247], s[8:9], 0, v[130:131]
	s_mov_b32 m0, s46
	s_nop 0
	global_load_lds_dwordx4 v[246:247], off
	s_waitcnt vmcnt(8)
	s_waitcnt lgkmcnt(0)
	s_barrier
	s_waitcnt lgkmcnt(0)
	v_mfma_f32_16x16x32_bf16 v[126:129], v[138:141], v[178:181], v[126:129]
	v_mfma_f32_16x16x32_bf16 v[122:125], v[146:149], v[178:181], v[122:125]
	v_mfma_f32_16x16x32_bf16 v[110:113], v[138:141], v[186:189], v[110:113]
	v_mfma_f32_16x16x32_bf16 v[106:109], v[146:149], v[186:189], v[106:109]
	v_mfma_f32_16x16x32_bf16 v[94:97], v[138:141], v[224:227], v[94:97]
	v_mfma_f32_16x16x32_bf16 v[90:93], v[146:149], v[224:227], v[90:93]
	v_mfma_f32_16x16x32_bf16 v[78:81], v[138:141], v[232:235], v[78:81]
	v_mfma_f32_16x16x32_bf16 v[74:77], v[146:149], v[232:235], v[74:77]
	v_mfma_f32_16x16x32_bf16 v[126:129], v[142:145], v[182:185], v[126:129]
	v_mfma_f32_16x16x32_bf16 v[122:125], v[150:153], v[182:185], v[122:125]
	v_mfma_f32_16x16x32_bf16 v[110:113], v[142:145], v[220:223], v[110:113]
	v_mfma_f32_16x16x32_bf16 v[106:109], v[150:153], v[220:223], v[106:109]
	v_mfma_f32_16x16x32_bf16 v[94:97], v[142:145], v[228:231], v[94:97]
	v_mfma_f32_16x16x32_bf16 v[90:93], v[150:153], v[228:231], v[90:93]
	v_mfma_f32_16x16x32_bf16 v[78:81], v[142:145], v[236:239], v[78:81]
	v_mfma_f32_16x16x32_bf16 v[74:77], v[150:153], v[236:239], v[74:77]
	v_mfma_f32_16x16x32_bf16 v[118:121], v[162:165], v[178:181], v[118:121]
	v_mfma_f32_16x16x32_bf16 v[114:117], v[170:173], v[178:181], v[114:117]
	v_mfma_f32_16x16x32_bf16 v[102:105], v[162:165], v[186:189], v[102:105]
	v_mfma_f32_16x16x32_bf16 v[98:101], v[170:173], v[186:189], v[98:101]
	v_mfma_f32_16x16x32_bf16 v[86:89], v[162:165], v[224:227], v[86:89]
	v_mfma_f32_16x16x32_bf16 v[82:85], v[170:173], v[224:227], v[82:85]
	v_mfma_f32_16x16x32_bf16 v[70:73], v[162:165], v[232:235], v[70:73]
	v_mfma_f32_16x16x32_bf16 v[66:69], v[170:173], v[232:235], v[66:69]
	v_mfma_f32_16x16x32_bf16 v[118:121], v[166:169], v[182:185], v[118:121]
	v_mfma_f32_16x16x32_bf16 v[114:117], v[174:177], v[182:185], v[114:117]
	v_mfma_f32_16x16x32_bf16 v[102:105], v[166:169], v[220:223], v[102:105]
	v_mfma_f32_16x16x32_bf16 v[98:101], v[174:177], v[220:223], v[98:101]
	v_mfma_f32_16x16x32_bf16 v[86:89], v[166:169], v[228:231], v[86:89]
	v_mfma_f32_16x16x32_bf16 v[82:85], v[174:177], v[228:231], v[82:85]
	v_mfma_f32_16x16x32_bf16 v[70:73], v[166:169], v[236:239], v[70:73]
	v_mfma_f32_16x16x32_bf16 v[66:69], v[174:177], v[236:239], v[66:69]
	s_barrier
	s_add_i32 s8, s62, s38
	v_lshl_add_u64 v[190:191], v[190:191], 0, s[72:73]
	s_mov_b32 m0, s8
	ds_read_b128 v[178:181], v137 offset:49152
	ds_read_b128 v[182:185], v137 offset:50176
	ds_read_b128 v[186:189], v137 offset:51200
	ds_read_b128 v[220:223], v137 offset:52224
	ds_read_b128 v[224:227], v137 offset:53248
	ds_read_b128 v[228:231], v137 offset:54272
	ds_read_b128 v[232:235], v137 offset:55296
	ds_read_b128 v[236:239], v137 offset:56320
	global_load_lds_dwordx4 v[190:191], off
	s_add_i32 m0, s8, 0x2000
	s_add_u32 s8, s34, 0x40080
	v_lshl_add_u64 v[190:191], v[240:241], 0, s[72:73]
	s_addc_u32 s9, s35, 0
	s_add_i32 s34, s63, s38
	global_load_lds_dwordx4 v[190:191], off
	v_lshl_add_u64 v[190:191], s[8:9], 0, v[0:1]
	s_mov_b32 m0, s34
	s_nop 0
	global_load_lds_dwordx4 v[190:191], off
	v_lshl_add_u64 v[190:191], s[8:9], 0, v[130:131]
	s_add_i32 m0, s34, 0x2000
	s_nop 0
	global_load_lds_dwordx4 v[190:191], off
	v_lshl_add_u64 v[190:191], v[242:243], 0, s[72:73]
	s_mov_b32 m0, s50
	s_nop 0
	global_load_lds_dwordx4 v[190:191], off
	v_lshl_add_u64 v[190:191], v[244:245], 0, s[72:73]
	s_mov_b32 m0, s56
	s_nop 0
	global_load_lds_dwordx4 v[190:191], off
	s_waitcnt vmcnt(8)
	s_waitcnt lgkmcnt(0)
	s_barrier
	s_waitcnt lgkmcnt(0)
	v_mfma_f32_16x16x32_bf16 v[62:65], v[138:141], v[178:181], v[62:65]
	v_mfma_f32_16x16x32_bf16 v[58:61], v[146:149], v[178:181], v[58:61]
	v_mfma_f32_16x16x32_bf16 v[46:49], v[138:141], v[186:189], v[46:49]
	v_mfma_f32_16x16x32_bf16 v[42:45], v[146:149], v[186:189], v[42:45]
	v_mfma_f32_16x16x32_bf16 v[30:33], v[138:141], v[224:227], v[30:33]
	v_mfma_f32_16x16x32_bf16 v[26:29], v[146:149], v[224:227], v[26:29]
	v_mfma_f32_16x16x32_bf16 v[14:17], v[138:141], v[232:235], v[14:17]
	v_mfma_f32_16x16x32_bf16 v[10:13], v[146:149], v[232:235], v[10:13]
	v_mfma_f32_16x16x32_bf16 v[62:65], v[142:145], v[182:185], v[62:65]
	v_mfma_f32_16x16x32_bf16 v[58:61], v[150:153], v[182:185], v[58:61]
	v_mfma_f32_16x16x32_bf16 v[46:49], v[142:145], v[220:223], v[46:49]
	v_mfma_f32_16x16x32_bf16 v[42:45], v[150:153], v[220:223], v[42:45]
	v_mfma_f32_16x16x32_bf16 v[30:33], v[142:145], v[228:231], v[30:33]
	v_mfma_f32_16x16x32_bf16 v[26:29], v[150:153], v[228:231], v[26:29]
	v_mfma_f32_16x16x32_bf16 v[14:17], v[142:145], v[236:239], v[14:17]
	v_mfma_f32_16x16x32_bf16 v[10:13], v[150:153], v[236:239], v[10:13]
	v_mfma_f32_16x16x32_bf16 v[54:57], v[162:165], v[178:181], v[54:57]
	v_mfma_f32_16x16x32_bf16 v[50:53], v[170:173], v[178:181], v[50:53]
	v_mfma_f32_16x16x32_bf16 v[38:41], v[162:165], v[186:189], v[38:41]
	v_mfma_f32_16x16x32_bf16 v[34:37], v[170:173], v[186:189], v[34:37]
	v_mfma_f32_16x16x32_bf16 v[22:25], v[162:165], v[224:227], v[22:25]
	v_mfma_f32_16x16x32_bf16 v[18:21], v[170:173], v[224:227], v[18:21]
	v_mfma_f32_16x16x32_bf16 v[6:9], v[162:165], v[232:235], v[6:9]
	v_mfma_f32_16x16x32_bf16 v[2:5], v[170:173], v[232:235], v[2:5]
	v_mfma_f32_16x16x32_bf16 v[54:57], v[166:169], v[182:185], v[54:57]
	v_mfma_f32_16x16x32_bf16 v[50:53], v[174:177], v[182:185], v[50:53]
	v_mfma_f32_16x16x32_bf16 v[38:41], v[166:169], v[220:223], v[38:41]
	v_mfma_f32_16x16x32_bf16 v[34:37], v[174:177], v[220:223], v[34:37]
	v_mfma_f32_16x16x32_bf16 v[22:25], v[166:169], v[228:231], v[22:25]
	v_mfma_f32_16x16x32_bf16 v[18:21], v[174:177], v[228:231], v[18:21]
	v_mfma_f32_16x16x32_bf16 v[6:9], v[166:169], v[236:239], v[6:9]
	v_mfma_f32_16x16x32_bf16 v[2:5], v[174:177], v[236:239], v[2:5]
	s_barrier
	s_add_u32 s30, s30, 0x100
	s_addc_u32 s31, s31, 0
	s_add_u32 s74, s74, 0x100
	s_addc_u32 s75, s75, 0
	s_cmp_ge_i32 s77, s47
	s_mov_b32 s34, s77
	s_cbranch_scc0 .LBB0_503
	s_mov_b32 s63, 0x8000

.LBB0_541:
	s_add_i32 s8, s26, 2
	s_add_u32 s24, s22, 0x100
	s_addc_u32 s25, s23, 0
	s_add_i32 s9, 0, 0x10000
	s_cmp_eq_u32 s48, s26
	s_cselect_b32 s29, s7, s25
	s_cselect_b32 s28, s6, s24
	v_add_u32_e32 v161, s9, v140
	s_cselect_b32 s27, s21, s67
	s_cselect_b32 s26, s20, s62
	s_add_i32 s63, 0, 0x14000
	ds_read_b128 v[142:145], v161
	ds_read_b128 v[146:149], v161 offset:1024
	ds_read_b128 v[150:153], v161 offset:2048
	ds_read_b128 v[162:165], v161 offset:3072
	v_add_u32_e32 v161, s63, v140
	ds_read_b128 v[166:169], v161
	ds_read_b128 v[170:173], v161 offset:1024
	ds_read_b128 v[174:177], v161 offset:2048
	ds_read_b128 v[178:181], v161 offset:3072
	v_lshl_add_u64 v[190:191], s[22:23], 0, v[136:137]
	s_add_i32 m0, s37, 0xc000
	ds_read_b128 v[182:185], v141
	ds_read_b128 v[186:189], v141 offset:1024
	ds_read_b128 v[220:223], v141 offset:2048
	ds_read_b128 v[224:227], v141 offset:3072
	ds_read_b128 v[228:231], v141 offset:4096
	ds_read_b128 v[232:235], v141 offset:5120
	ds_read_b128 v[236:239], v141 offset:6144
	ds_read_b128 v[240:243], v141 offset:7168
	global_load_lds_dwordx4 v[190:191], off
	v_lshl_add_u64 v[190:191], s[22:23], 0, v[138:139]
	s_add_i32 m0, s37, 0xe000
	s_nop 0
	global_load_lds_dwordx4 v[190:191], off
	s_waitcnt vmcnt(8)
	s_waitcnt lgkmcnt(0)
	s_barrier
	s_waitcnt lgkmcnt(0)
	v_mfma_f32_16x16x32_bf16 v[122:125], v[142:145], v[182:185], v[122:125]
	v_mfma_f32_16x16x32_bf16 v[126:129], v[150:153], v[182:185], v[126:129]
	v_mfma_f32_16x16x32_bf16 v[110:113], v[142:145], v[220:223], v[110:113]
	v_mfma_f32_16x16x32_bf16 v[106:109], v[150:153], v[220:223], v[106:109]
	v_mfma_f32_16x16x32_bf16 v[94:97], v[142:145], v[228:231], v[94:97]
	v_mfma_f32_16x16x32_bf16 v[90:93], v[150:153], v[228:231], v[90:93]
	v_mfma_f32_16x16x32_bf16 v[78:81], v[142:145], v[236:239], v[78:81]
	v_mfma_f32_16x16x32_bf16 v[74:77], v[150:153], v[236:239], v[74:77]
	v_mfma_f32_16x16x32_bf16 v[122:125], v[146:149], v[186:189], v[122:125]
	v_mfma_f32_16x16x32_bf16 v[126:129], v[162:165], v[186:189], v[126:129]
	v_mfma_f32_16x16x32_bf16 v[110:113], v[146:149], v[224:227], v[110:113]
	v_mfma_f32_16x16x32_bf16 v[106:109], v[162:165], v[224:227], v[106:109]
	v_mfma_f32_16x16x32_bf16 v[94:97], v[146:149], v[232:235], v[94:97]
	v_mfma_f32_16x16x32_bf16 v[90:93], v[162:165], v[232:235], v[90:93]
	v_mfma_f32_16x16x32_bf16 v[78:81], v[146:149], v[240:243], v[78:81]
	v_mfma_f32_16x16x32_bf16 v[74:77], v[162:165], v[240:243], v[74:77]
	v_mfma_f32_16x16x32_bf16 v[118:121], v[166:169], v[182:185], v[118:121]
	v_mfma_f32_16x16x32_bf16 v[114:117], v[174:177], v[182:185], v[114:117]
	v_mfma_f32_16x16x32_bf16 v[102:105], v[166:169], v[220:223], v[102:105]
	v_mfma_f32_16x16x32_bf16 v[98:101], v[174:177], v[220:223], v[98:101]
	v_mfma_f32_16x16x32_bf16 v[86:89], v[166:169], v[228:231], v[86:89]
	v_mfma_f32_16x16x32_bf16 v[82:85], v[174:177], v[228:231], v[82:85]
	v_mfma_f32_16x16x32_bf16 v[70:73], v[166:169], v[236:239], v[70:73]
	v_mfma_f32_16x16x32_bf16 v[66:69], v[174:177], v[236:239], v[66:69]
	v_mfma_f32_16x16x32_bf16 v[118:121], v[170:173], v[186:189], v[118:121]
	v_mfma_f32_16x16x32_bf16 v[114:117], v[178:181], v[186:189], v[114:117]
	v_mfma_f32_16x16x32_bf16 v[102:105], v[170:173], v[224:227], v[102:105]
	v_mfma_f32_16x16x32_bf16 v[98:101], v[178:181], v[224:227], v[98:101]
	v_mfma_f32_16x16x32_bf16 v[86:89], v[170:173], v[232:235], v[86:89]
	v_mfma_f32_16x16x32_bf16 v[82:85], v[178:181], v[232:235], v[82:85]
	v_mfma_f32_16x16x32_bf16 v[70:73], v[170:173], v[240:243], v[70:73]
	v_mfma_f32_16x16x32_bf16 v[66:69], v[178:181], v[240:243], v[66:69]
	s_barrier
	s_add_i32 s9, s9, s36
	v_lshl_add_u64 v[190:191], s[26:27], 0, v[0:1]
	s_mov_b32 m0, s9
	ds_read_b128 v[182:185], v141 offset:16384
	ds_read_b128 v[186:189], v141 offset:17408
	ds_read_b128 v[220:223], v141 offset:18432
	ds_read_b128 v[224:227], v141 offset:19456
	ds_read_b128 v[228:231], v141 offset:20480
	ds_read_b128 v[232:235], v141 offset:21504
	ds_read_b128 v[236:239], v141 offset:22528
	ds_read_b128 v[240:243], v141 offset:23552
	global_load_lds_dwordx4 v[190:191], off
	s_add_i32 m0, s9, 0x2000
	s_add_u32 s22, s26, 0xb0000
	v_lshl_add_u64 v[244:245], s[26:27], 0, v[134:135]
	s_addc_u32 s23, s27, 0
	s_add_i32 s9, s63, s36
	global_load_lds_dwordx4 v[244:245], off
	v_lshl_add_u64 v[246:247], s[22:23], 0, v[0:1]
	s_mov_b32 m0, s9
	v_lshl_add_u64 v[248:249], s[28:29], 0, v[132:133]
	global_load_lds_dwordx4 v[246:247], off
	v_lshl_add_u64 v[246:247], s[22:23], 0, v[134:135]
	s_add_i32 m0, s9, 0x2000
	s_nop 0
	global_load_lds_dwordx4 v[246:247], off
	v_lshl_add_u64 v[246:247], s[28:29], 0, v[130:131]
	s_mov_b32 m0, s37
	s_nop 0
	global_load_lds_dwordx4 v[246:247], off
	s_mov_b32 m0, s38
	s_nop 0
	global_load_lds_dwordx4 v[248:249], off
	s_waitcnt vmcnt(8)
	s_waitcnt lgkmcnt(0)
	s_barrier
	s_waitcnt lgkmcnt(0)
	v_mfma_f32_16x16x32_bf16 v[62:65], v[142:145], v[182:185], v[62:65]
	v_mfma_f32_16x16x32_bf16 v[58:61], v[150:153], v[182:185], v[58:61]
	v_mfma_f32_16x16x32_bf16 v[46:49], v[142:145], v[220:223], v[46:49]
	v_mfma_f32_16x16x32_bf16 v[42:45], v[150:153], v[220:223], v[42:45]
	v_mfma_f32_16x16x32_bf16 v[30:33], v[142:145], v[228:231], v[30:33]
	v_mfma_f32_16x16x32_bf16 v[26:29], v[150:153], v[228:231], v[26:29]
	v_mfma_f32_16x16x32_bf16 v[14:17], v[142:145], v[236:239], v[14:17]
	v_mfma_f32_16x16x32_bf16 v[10:13], v[150:153], v[236:239], v[10:13]
	v_mfma_f32_16x16x32_bf16 v[62:65], v[146:149], v[186:189], v[62:65]
	v_mfma_f32_16x16x32_bf16 v[58:61], v[162:165], v[186:189], v[58:61]
	v_mfma_f32_16x16x32_bf16 v[46:49], v[146:149], v[224:227], v[46:49]
	v_mfma_f32_16x16x32_bf16 v[42:45], v[162:165], v[224:227], v[42:45]
	v_mfma_f32_16x16x32_bf16 v[30:33], v[146:149], v[232:235], v[30:33]
	v_mfma_f32_16x16x32_bf16 v[26:29], v[162:165], v[232:235], v[26:29]
	v_mfma_f32_16x16x32_bf16 v[14:17], v[146:149], v[240:243], v[14:17]
	v_mfma_f32_16x16x32_bf16 v[10:13], v[162:165], v[240:243], v[10:13]
	v_mfma_f32_16x16x32_bf16 v[54:57], v[166:169], v[182:185], v[54:57]
	v_mfma_f32_16x16x32_bf16 v[50:53], v[174:177], v[182:185], v[50:53]
	v_mfma_f32_16x16x32_bf16 v[38:41], v[166:169], v[220:223], v[38:41]
	v_mfma_f32_16x16x32_bf16 v[34:37], v[174:177], v[220:223], v[34:37]
	v_mfma_f32_16x16x32_bf16 v[22:25], v[166:169], v[228:231], v[22:25]
	v_mfma_f32_16x16x32_bf16 v[18:21], v[174:177], v[228:231], v[18:21]
	v_mfma_f32_16x16x32_bf16 v[6:9], v[166:169], v[236:239], v[6:9]
	v_mfma_f32_16x16x32_bf16 v[2:5], v[174:177], v[236:239], v[2:5]
	v_mfma_f32_16x16x32_bf16 v[54:57], v[170:173], v[186:189], v[54:57]
	v_mfma_f32_16x16x32_bf16 v[50:53], v[178:181], v[186:189], v[50:53]
	v_mfma_f32_16x16x32_bf16 v[38:41], v[170:173], v[224:227], v[38:41]
	v_mfma_f32_16x16x32_bf16 v[34:37], v[178:181], v[224:227], v[34:37]
	v_mfma_f32_16x16x32_bf16 v[22:25], v[170:173], v[232:235], v[22:25]
	v_mfma_f32_16x16x32_bf16 v[18:21], v[178:181], v[232:235], v[18:21]
	v_mfma_f32_16x16x32_bf16 v[6:9], v[170:173], v[240:243], v[6:9]
	v_mfma_f32_16x16x32_bf16 v[2:5], v[178:181], v[240:243], v[2:5]
	s_barrier
	s_add_i32 s9, 0, 0x18000
	v_add_u32_e32 v161, s9, v140
	s_add_i32 s63, 0, 0x1c000
	ds_read_b128 v[142:145], v161
	ds_read_b128 v[146:149], v161 offset:1024
	ds_read_b128 v[150:153], v161 offset:2048
	ds_read_b128 v[162:165], v161 offset:3072
	v_add_u32_e32 v161, s63, v140
	ds_read_b128 v[166:169], v161
	ds_read_b128 v[170:173], v161 offset:1024
	ds_read_b128 v[174:177], v161 offset:2048
	ds_read_b128 v[178:181], v161 offset:3072
	s_add_u32 s22, s28, 0xb0000
	s_addc_u32 s23, s29, 0
	s_mov_b32 m0, s39
	v_lshl_add_u64 v[250:251], s[22:23], 0, v[130:131]
	ds_read_b128 v[182:185], v141 offset:32768
	ds_read_b128 v[186:189], v141 offset:33792
	ds_read_b128 v[220:223], v141 offset:34816
	ds_read_b128 v[224:227], v141 offset:35840
	ds_read_b128 v[228:231], v141 offset:36864
	ds_read_b128 v[232:235], v141 offset:37888
	ds_read_b128 v[236:239], v141 offset:38912
	ds_read_b128 v[240:243], v141 offset:39936
	global_load_lds_dwordx4 v[250:251], off
	v_lshl_add_u64 v[250:251], s[22:23], 0, v[132:133]
	s_mov_b32 m0, s40
	s_nop 0
	global_load_lds_dwordx4 v[250:251], off
	s_waitcnt vmcnt(8)
	s_waitcnt lgkmcnt(0)
	s_barrier
	s_waitcnt lgkmcnt(0)
	v_mfma_f32_16x16x32_bf16 v[122:125], v[142:145], v[182:185], v[122:125]
	v_mfma_f32_16x16x32_bf16 v[126:129], v[150:153], v[182:185], v[126:129]
	v_mfma_f32_16x16x32_bf16 v[110:113], v[142:145], v[220:223], v[110:113]
	v_mfma_f32_16x16x32_bf16 v[106:109], v[150:153], v[220:223], v[106:109]
	v_mfma_f32_16x16x32_bf16 v[94:97], v[142:145], v[228:231], v[94:97]
	v_mfma_f32_16x16x32_bf16 v[90:93], v[150:153], v[228:231], v[90:93]
	v_mfma_f32_16x16x32_bf16 v[78:81], v[142:145], v[236:239], v[78:81]
	v_mfma_f32_16x16x32_bf16 v[74:77], v[150:153], v[236:239], v[74:77]
	v_mfma_f32_16x16x32_bf16 v[122:125], v[146:149], v[186:189], v[122:125]
	v_mfma_f32_16x16x32_bf16 v[126:129], v[162:165], v[186:189], v[126:129]
	v_mfma_f32_16x16x32_bf16 v[110:113], v[146:149], v[224:227], v[110:113]
	v_mfma_f32_16x16x32_bf16 v[106:109], v[162:165], v[224:227], v[106:109]
	v_mfma_f32_16x16x32_bf16 v[94:97], v[146:149], v[232:235], v[94:97]
	v_mfma_f32_16x16x32_bf16 v[90:93], v[162:165], v[232:235], v[90:93]
	v_mfma_f32_16x16x32_bf16 v[78:81], v[146:149], v[240:243], v[78:81]
	v_mfma_f32_16x16x32_bf16 v[74:77], v[162:165], v[240:243], v[74:77]
	v_mfma_f32_16x16x32_bf16 v[118:121], v[166:169], v[182:185], v[118:121]
	v_mfma_f32_16x16x32_bf16 v[114:117], v[174:177], v[182:185], v[114:117]
	v_mfma_f32_16x16x32_bf16 v[102:105], v[166:169], v[220:223], v[102:105]
	v_mfma_f32_16x16x32_bf16 v[98:101], v[174:177], v[220:223], v[98:101]
	v_mfma_f32_16x16x32_bf16 v[86:89], v[166:169], v[228:231], v[86:89]
	v_mfma_f32_16x16x32_bf16 v[82:85], v[174:177], v[228:231], v[82:85]
	v_mfma_f32_16x16x32_bf16 v[70:73], v[166:169], v[236:239], v[70:73]
	v_mfma_f32_16x16x32_bf16 v[66:69], v[174:177], v[236:239], v[66:69]
	v_mfma_f32_16x16x32_bf16 v[118:121], v[170:173], v[186:189], v[118:121]
	v_mfma_f32_16x16x32_bf16 v[114:117], v[178:181], v[186:189], v[114:117]
	v_mfma_f32_16x16x32_bf16 v[102:105], v[170:173], v[224:227], v[102:105]
	v_mfma_f32_16x16x32_bf16 v[98:101], v[178:181], v[224:227], v[98:101]
	v_mfma_f32_16x16x32_bf16 v[86:89], v[170:173], v[232:235], v[86:89]
	v_mfma_f32_16x16x32_bf16 v[82:85], v[178:181], v[232:235], v[82:85]
	v_mfma_f32_16x16x32_bf16 v[70:73], v[170:173], v[240:243], v[70:73]
	v_mfma_f32_16x16x32_bf16 v[66:69], v[178:181], v[240:243], v[66:69]
	s_barrier
	s_add_i32 s9, s9, s36
	v_lshl_add_u64 v[190:191], v[190:191], 0, s[72:73]
	s_mov_b32 m0, s9
	ds_read_b128 v[182:185], v141 offset:49152
	ds_read_b128 v[186:189], v141 offset:50176
	ds_read_b128 v[220:223], v141 offset:51200
	ds_read_b128 v[224:227], v141 offset:52224
	ds_read_b128 v[228:231], v141 offset:53248
	ds_read_b128 v[232:235], v141 offset:54272
	ds_read_b128 v[236:239], v141 offset:55296
	ds_read_b128 v[240:243], v141 offset:56320
	global_load_lds_dwordx4 v[190:191], off
	s_add_i32 m0, s9, 0x2000
	s_add_u32 s22, s26, 0xb0080
	v_lshl_add_u64 v[190:191], v[244:245], 0, s[72:73]
	s_addc_u32 s23, s27, 0
	s_add_i32 s9, s63, s36
	global_load_lds_dwordx4 v[190:191], off
	v_lshl_add_u64 v[190:191], s[22:23], 0, v[0:1]
	s_mov_b32 m0, s9
	s_nop 0
	global_load_lds_dwordx4 v[190:191], off
	v_lshl_add_u64 v[190:191], s[22:23], 0, v[134:135]
	s_add_i32 m0, s9, 0x2000
	s_nop 0
	global_load_lds_dwordx4 v[190:191], off
	v_lshl_add_u64 v[190:191], v[246:247], 0, s[72:73]
	s_mov_b32 m0, s46
	s_nop 0
	global_load_lds_dwordx4 v[190:191], off
	v_lshl_add_u64 v[190:191], v[248:249], 0, s[72:73]
	s_mov_b32 m0, s47
	s_nop 0
	global_load_lds_dwordx4 v[190:191], off
	s_waitcnt vmcnt(8)
	s_waitcnt lgkmcnt(0)
	s_barrier
	s_waitcnt lgkmcnt(0)
	v_mfma_f32_16x16x32_bf16 v[62:65], v[142:145], v[182:185], v[62:65]
	v_mfma_f32_16x16x32_bf16 v[58:61], v[150:153], v[182:185], v[58:61]
	v_mfma_f32_16x16x32_bf16 v[46:49], v[142:145], v[220:223], v[46:49]
	v_mfma_f32_16x16x32_bf16 v[42:45], v[150:153], v[220:223], v[42:45]
	v_mfma_f32_16x16x32_bf16 v[30:33], v[142:145], v[228:231], v[30:33]
	v_mfma_f32_16x16x32_bf16 v[26:29], v[150:153], v[228:231], v[26:29]
	v_mfma_f32_16x16x32_bf16 v[14:17], v[142:145], v[236:239], v[14:17]
	v_mfma_f32_16x16x32_bf16 v[10:13], v[150:153], v[236:239], v[10:13]
	v_mfma_f32_16x16x32_bf16 v[62:65], v[146:149], v[186:189], v[62:65]
	v_mfma_f32_16x16x32_bf16 v[58:61], v[162:165], v[186:189], v[58:61]
	v_mfma_f32_16x16x32_bf16 v[46:49], v[146:149], v[224:227], v[46:49]
	v_mfma_f32_16x16x32_bf16 v[42:45], v[162:165], v[224:227], v[42:45]
	v_mfma_f32_16x16x32_bf16 v[30:33], v[146:149], v[232:235], v[30:33]
	v_mfma_f32_16x16x32_bf16 v[26:29], v[162:165], v[232:235], v[26:29]
	v_mfma_f32_16x16x32_bf16 v[14:17], v[146:149], v[240:243], v[14:17]
	v_mfma_f32_16x16x32_bf16 v[10:13], v[162:165], v[240:243], v[10:13]
	v_mfma_f32_16x16x32_bf16 v[54:57], v[166:169], v[182:185], v[54:57]
	v_mfma_f32_16x16x32_bf16 v[50:53], v[174:177], v[182:185], v[50:53]
	v_mfma_f32_16x16x32_bf16 v[38:41], v[166:169], v[220:223], v[38:41]
	v_mfma_f32_16x16x32_bf16 v[34:37], v[174:177], v[220:223], v[34:37]
	v_mfma_f32_16x16x32_bf16 v[22:25], v[166:169], v[228:231], v[22:25]
	v_mfma_f32_16x16x32_bf16 v[18:21], v[174:177], v[228:231], v[18:21]
	v_mfma_f32_16x16x32_bf16 v[6:9], v[166:169], v[236:239], v[6:9]
	v_mfma_f32_16x16x32_bf16 v[2:5], v[174:177], v[236:239], v[2:5]
	v_mfma_f32_16x16x32_bf16 v[54:57], v[170:173], v[186:189], v[54:57]
	v_mfma_f32_16x16x32_bf16 v[50:53], v[178:181], v[186:189], v[50:53]
	v_mfma_f32_16x16x32_bf16 v[38:41], v[170:173], v[224:227], v[38:41]
	v_mfma_f32_16x16x32_bf16 v[34:37], v[178:181], v[224:227], v[34:37]
	v_mfma_f32_16x16x32_bf16 v[22:25], v[170:173], v[232:235], v[22:25]
	v_mfma_f32_16x16x32_bf16 v[18:21], v[178:181], v[232:235], v[18:21]
	v_mfma_f32_16x16x32_bf16 v[6:9], v[170:173], v[240:243], v[6:9]
	v_mfma_f32_16x16x32_bf16 v[2:5], v[178:181], v[240:243], v[2:5]
	s_barrier
	s_add_u32 s62, s62, 0x100
	s_addc_u32 s67, s67, 0
	s_cmp_ge_i32 s8, s41
	s_mov_b64 s[22:23], s[24:25]
	s_mov_b32 s26, s8
	s_cbranch_scc0 .LBB0_541
	s_mov_b32 s63, 0x8000
	s_movk_i32 s67, 0x1800

.LBB0_577:
	s_add_i32 s75, s28, 2
	s_add_u32 s29, s26, 0xfffc0080
	s_addc_u32 s30, s27, -1
	s_add_i32 s62, 0, 0x10000
	s_cmp_eq_u32 s58, s28
	s_cselect_b32 s31, s7, s30
	s_cselect_b32 s30, s9, s29
	v_add_u32_e32 v140, s62, v142
	s_cselect_b32 s29, s19, s74
	s_cselect_b32 s28, s21, s71
	s_add_i32 s77, 0, 0x14000
	ds_read_b128 v[144:147], v140
	ds_read_b128 v[148:151], v140 offset:1024
	ds_read_b128 v[162:165], v140 offset:2048
	ds_read_b128 v[166:169], v140 offset:3072
	v_add_u32_e32 v140, s77, v142
	ds_read_b128 v[170:173], v140
	ds_read_b128 v[174:177], v140 offset:1024
	ds_read_b128 v[178:181], v140 offset:2048
	ds_read_b128 v[182:185], v140 offset:3072
	v_lshl_add_u64 v[140:141], s[26:27], 0, v[136:137]
	s_add_i32 m0, s37, 0xc000
	ds_read_b128 v[186:189], v143
	ds_read_b128 v[220:223], v143 offset:1024
	ds_read_b128 v[224:227], v143 offset:2048
	ds_read_b128 v[228:231], v143 offset:3072
	ds_read_b128 v[232:235], v143 offset:4096
	ds_read_b128 v[236:239], v143 offset:5120
	ds_read_b128 v[240:243], v143 offset:6144
	ds_read_b128 v[244:247], v143 offset:7168
	global_load_lds_dwordx4 v[140:141], off
	v_lshl_add_u64 v[140:141], s[26:27], 0, v[138:139]
	s_add_i32 m0, s37, 0xe000
	s_nop 0
	global_load_lds_dwordx4 v[140:141], off
	s_waitcnt vmcnt(8)
	s_waitcnt lgkmcnt(0)
	s_barrier
	s_waitcnt lgkmcnt(0)
	v_mfma_f32_16x16x32_bf16 v[126:129], v[144:147], v[186:189], v[126:129]
	v_mfma_f32_16x16x32_bf16 v[122:125], v[162:165], v[186:189], v[122:125]
	v_mfma_f32_16x16x32_bf16 v[110:113], v[144:147], v[224:227], v[110:113]
	v_mfma_f32_16x16x32_bf16 v[106:109], v[162:165], v[224:227], v[106:109]
	v_mfma_f32_16x16x32_bf16 v[94:97], v[144:147], v[232:235], v[94:97]
	v_mfma_f32_16x16x32_bf16 v[90:93], v[162:165], v[232:235], v[90:93]
	v_mfma_f32_16x16x32_bf16 v[78:81], v[144:147], v[240:243], v[78:81]
	v_mfma_f32_16x16x32_bf16 v[74:77], v[162:165], v[240:243], v[74:77]
	v_mfma_f32_16x16x32_bf16 v[126:129], v[148:151], v[220:223], v[126:129]
	v_mfma_f32_16x16x32_bf16 v[122:125], v[166:169], v[220:223], v[122:125]
	v_mfma_f32_16x16x32_bf16 v[110:113], v[148:151], v[228:231], v[110:113]
	v_mfma_f32_16x16x32_bf16 v[106:109], v[166:169], v[228:231], v[106:109]
	v_mfma_f32_16x16x32_bf16 v[94:97], v[148:151], v[236:239], v[94:97]
	v_mfma_f32_16x16x32_bf16 v[90:93], v[166:169], v[236:239], v[90:93]
	v_mfma_f32_16x16x32_bf16 v[78:81], v[148:151], v[244:247], v[78:81]
	v_mfma_f32_16x16x32_bf16 v[74:77], v[166:169], v[244:247], v[74:77]
	v_mfma_f32_16x16x32_bf16 v[118:121], v[170:173], v[186:189], v[118:121]
	v_mfma_f32_16x16x32_bf16 v[114:117], v[178:181], v[186:189], v[114:117]
	v_mfma_f32_16x16x32_bf16 v[102:105], v[170:173], v[224:227], v[102:105]
	v_mfma_f32_16x16x32_bf16 v[98:101], v[178:181], v[224:227], v[98:101]
	v_mfma_f32_16x16x32_bf16 v[86:89], v[170:173], v[232:235], v[86:89]
	v_mfma_f32_16x16x32_bf16 v[82:85], v[178:181], v[232:235], v[82:85]
	v_mfma_f32_16x16x32_bf16 v[70:73], v[170:173], v[240:243], v[70:73]
	v_mfma_f32_16x16x32_bf16 v[66:69], v[178:181], v[240:243], v[66:69]
	v_mfma_f32_16x16x32_bf16 v[118:121], v[174:177], v[220:223], v[118:121]
	v_mfma_f32_16x16x32_bf16 v[114:117], v[182:185], v[220:223], v[114:117]
	v_mfma_f32_16x16x32_bf16 v[102:105], v[174:177], v[228:231], v[102:105]
	v_mfma_f32_16x16x32_bf16 v[98:101], v[182:185], v[228:231], v[98:101]
	v_mfma_f32_16x16x32_bf16 v[86:89], v[174:177], v[236:239], v[86:89]
	v_mfma_f32_16x16x32_bf16 v[82:85], v[182:185], v[236:239], v[82:85]
	v_mfma_f32_16x16x32_bf16 v[70:73], v[174:177], v[244:247], v[70:73]
	v_mfma_f32_16x16x32_bf16 v[66:69], v[182:185], v[244:247], v[66:69]
	s_barrier
	s_add_i32 s62, s62, s36
	v_lshl_add_u64 v[140:141], s[28:29], 0, v[0:1]
	s_mov_b32 m0, s62
	ds_read_b128 v[186:189], v143 offset:16384
	ds_read_b128 v[220:223], v143 offset:17408
	ds_read_b128 v[224:227], v143 offset:18432
	ds_read_b128 v[228:231], v143 offset:19456
	ds_read_b128 v[232:235], v143 offset:20480
	ds_read_b128 v[236:239], v143 offset:21504
	ds_read_b128 v[240:243], v143 offset:22528
	ds_read_b128 v[244:247], v143 offset:23552
	global_load_lds_dwordx4 v[140:141], off
	s_add_i32 m0, s62, 0x2000
	s_add_u32 s62, s28, 0x40000
	v_lshl_add_u64 v[152:153], s[28:29], 0, v[134:135]
	s_addc_u32 s63, s29, 0
	s_add_i32 s77, s77, s36
	global_load_lds_dwordx4 v[152:153], off
	v_lshl_add_u64 v[190:191], s[62:63], 0, v[0:1]
	s_mov_b32 m0, s77
	v_lshl_add_u64 v[248:249], s[30:31], 0, v[132:133]
	global_load_lds_dwordx4 v[190:191], off
	v_lshl_add_u64 v[190:191], s[62:63], 0, v[134:135]
	s_add_i32 m0, s77, 0x2000
	s_nop 0
	global_load_lds_dwordx4 v[190:191], off
	v_lshl_add_u64 v[190:191], s[30:31], 0, v[130:131]
	s_mov_b32 m0, s37
	s_nop 0
	global_load_lds_dwordx4 v[190:191], off
	s_mov_b32 m0, s38
	s_nop 0
	global_load_lds_dwordx4 v[248:249], off
	s_waitcnt vmcnt(8)
	s_waitcnt lgkmcnt(0)
	s_barrier
	s_waitcnt lgkmcnt(0)
	v_mfma_f32_16x16x32_bf16 v[62:65], v[144:147], v[186:189], v[62:65]
	v_mfma_f32_16x16x32_bf16 v[58:61], v[162:165], v[186:189], v[58:61]
	v_mfma_f32_16x16x32_bf16 v[46:49], v[144:147], v[224:227], v[46:49]
	v_mfma_f32_16x16x32_bf16 v[42:45], v[162:165], v[224:227], v[42:45]
	v_mfma_f32_16x16x32_bf16 v[30:33], v[144:147], v[232:235], v[30:33]
	v_mfma_f32_16x16x32_bf16 v[26:29], v[162:165], v[232:235], v[26:29]
	v_mfma_f32_16x16x32_bf16 v[14:17], v[144:147], v[240:243], v[14:17]
	v_mfma_f32_16x16x32_bf16 v[10:13], v[162:165], v[240:243], v[10:13]
	v_mfma_f32_16x16x32_bf16 v[62:65], v[148:151], v[220:223], v[62:65]
	v_mfma_f32_16x16x32_bf16 v[58:61], v[166:169], v[220:223], v[58:61]
	v_mfma_f32_16x16x32_bf16 v[46:49], v[148:151], v[228:231], v[46:49]
	v_mfma_f32_16x16x32_bf16 v[42:45], v[166:169], v[228:231], v[42:45]
	v_mfma_f32_16x16x32_bf16 v[30:33], v[148:151], v[236:239], v[30:33]
	v_mfma_f32_16x16x32_bf16 v[26:29], v[166:169], v[236:239], v[26:29]
	v_mfma_f32_16x16x32_bf16 v[14:17], v[148:151], v[244:247], v[14:17]
	v_mfma_f32_16x16x32_bf16 v[10:13], v[166:169], v[244:247], v[10:13]
	v_mfma_f32_16x16x32_bf16 v[54:57], v[170:173], v[186:189], v[54:57]
	v_mfma_f32_16x16x32_bf16 v[50:53], v[178:181], v[186:189], v[50:53]
	v_mfma_f32_16x16x32_bf16 v[38:41], v[170:173], v[224:227], v[38:41]
	v_mfma_f32_16x16x32_bf16 v[34:37], v[178:181], v[224:227], v[34:37]
	v_mfma_f32_16x16x32_bf16 v[22:25], v[170:173], v[232:235], v[22:25]
	v_mfma_f32_16x16x32_bf16 v[18:21], v[178:181], v[232:235], v[18:21]
	v_mfma_f32_16x16x32_bf16 v[6:9], v[170:173], v[240:243], v[6:9]
	v_mfma_f32_16x16x32_bf16 v[2:5], v[178:181], v[240:243], v[2:5]
	v_mfma_f32_16x16x32_bf16 v[54:57], v[174:177], v[220:223], v[54:57]
	v_mfma_f32_16x16x32_bf16 v[50:53], v[182:185], v[220:223], v[50:53]
	v_mfma_f32_16x16x32_bf16 v[38:41], v[174:177], v[228:231], v[38:41]
	v_mfma_f32_16x16x32_bf16 v[34:37], v[182:185], v[228:231], v[34:37]
	v_mfma_f32_16x16x32_bf16 v[22:25], v[174:177], v[236:239], v[22:25]
	v_mfma_f32_16x16x32_bf16 v[18:21], v[182:185], v[236:239], v[18:21]
	v_mfma_f32_16x16x32_bf16 v[6:9], v[174:177], v[244:247], v[6:9]
	v_mfma_f32_16x16x32_bf16 v[2:5], v[182:185], v[244:247], v[2:5]
	s_barrier
	s_add_i32 s62, 0, 0x18000
	v_add_u32_e32 v161, s62, v142
	s_add_i32 s63, 0, 0x1c000
	ds_read_b128 v[144:147], v161
	ds_read_b128 v[148:151], v161 offset:1024
	ds_read_b128 v[162:165], v161 offset:2048
	ds_read_b128 v[166:169], v161 offset:3072
	v_add_u32_e32 v161, s63, v142
	ds_read_b128 v[170:173], v161
	ds_read_b128 v[174:177], v161 offset:1024
	ds_read_b128 v[178:181], v161 offset:2048
	ds_read_b128 v[182:185], v161 offset:3072
	s_add_u32 s30, s30, 0x40000
	s_addc_u32 s31, s31, 0
	s_mov_b32 m0, s39
	v_lshl_add_u64 v[250:251], s[30:31], 0, v[130:131]
	ds_read_b128 v[186:189], v143 offset:32768
	ds_read_b128 v[220:223], v143 offset:33792
	ds_read_b128 v[224:227], v143 offset:34816
	ds_read_b128 v[228:231], v143 offset:35840
	ds_read_b128 v[232:235], v143 offset:36864
	ds_read_b128 v[236:239], v143 offset:37888
	ds_read_b128 v[240:243], v143 offset:38912
	ds_read_b128 v[244:247], v143 offset:39936
	global_load_lds_dwordx4 v[250:251], off
	v_lshl_add_u64 v[250:251], s[30:31], 0, v[132:133]
	s_mov_b32 m0, s40
	s_nop 0
	global_load_lds_dwordx4 v[250:251], off
	s_waitcnt vmcnt(8)
	s_waitcnt lgkmcnt(0)
	s_barrier
	s_waitcnt lgkmcnt(0)
	v_mfma_f32_16x16x32_bf16 v[126:129], v[144:147], v[186:189], v[126:129]
	v_mfma_f32_16x16x32_bf16 v[122:125], v[162:165], v[186:189], v[122:125]
	v_mfma_f32_16x16x32_bf16 v[110:113], v[144:147], v[224:227], v[110:113]
	v_mfma_f32_16x16x32_bf16 v[106:109], v[162:165], v[224:227], v[106:109]
	v_mfma_f32_16x16x32_bf16 v[94:97], v[144:147], v[232:235], v[94:97]
	v_mfma_f32_16x16x32_bf16 v[90:93], v[162:165], v[232:235], v[90:93]
	v_mfma_f32_16x16x32_bf16 v[78:81], v[144:147], v[240:243], v[78:81]
	v_mfma_f32_16x16x32_bf16 v[74:77], v[162:165], v[240:243], v[74:77]
	v_mfma_f32_16x16x32_bf16 v[126:129], v[148:151], v[220:223], v[126:129]
	v_mfma_f32_16x16x32_bf16 v[122:125], v[166:169], v[220:223], v[122:125]
	v_mfma_f32_16x16x32_bf16 v[110:113], v[148:151], v[228:231], v[110:113]
	v_mfma_f32_16x16x32_bf16 v[106:109], v[166:169], v[228:231], v[106:109]
	v_mfma_f32_16x16x32_bf16 v[94:97], v[148:151], v[236:239], v[94:97]
	v_mfma_f32_16x16x32_bf16 v[90:93], v[166:169], v[236:239], v[90:93]
	v_mfma_f32_16x16x32_bf16 v[78:81], v[148:151], v[244:247], v[78:81]
	v_mfma_f32_16x16x32_bf16 v[74:77], v[166:169], v[244:247], v[74:77]
	v_mfma_f32_16x16x32_bf16 v[118:121], v[170:173], v[186:189], v[118:121]
	v_mfma_f32_16x16x32_bf16 v[114:117], v[178:181], v[186:189], v[114:117]
	v_mfma_f32_16x16x32_bf16 v[102:105], v[170:173], v[224:227], v[102:105]
	v_mfma_f32_16x16x32_bf16 v[98:101], v[178:181], v[224:227], v[98:101]
	v_mfma_f32_16x16x32_bf16 v[86:89], v[170:173], v[232:235], v[86:89]
	v_mfma_f32_16x16x32_bf16 v[82:85], v[178:181], v[232:235], v[82:85]
	v_mfma_f32_16x16x32_bf16 v[70:73], v[170:173], v[240:243], v[70:73]
	v_mfma_f32_16x16x32_bf16 v[66:69], v[178:181], v[240:243], v[66:69]
	v_mfma_f32_16x16x32_bf16 v[118:121], v[174:177], v[220:223], v[118:121]
	v_mfma_f32_16x16x32_bf16 v[114:117], v[182:185], v[220:223], v[114:117]
	v_mfma_f32_16x16x32_bf16 v[102:105], v[174:177], v[228:231], v[102:105]
	v_mfma_f32_16x16x32_bf16 v[98:101], v[182:185], v[228:231], v[98:101]
	v_mfma_f32_16x16x32_bf16 v[86:89], v[174:177], v[236:239], v[86:89]
	v_mfma_f32_16x16x32_bf16 v[82:85], v[182:185], v[236:239], v[82:85]
	v_mfma_f32_16x16x32_bf16 v[70:73], v[174:177], v[244:247], v[70:73]
	v_mfma_f32_16x16x32_bf16 v[66:69], v[182:185], v[244:247], v[66:69]
	s_barrier
	s_add_i32 s30, s62, s36
	v_lshl_add_u64 v[140:141], v[140:141], 0, s[72:73]
	s_mov_b32 m0, s30
	ds_read_b128 v[186:189], v143 offset:49152
	ds_read_b128 v[220:223], v143 offset:50176
	ds_read_b128 v[224:227], v143 offset:51200
	ds_read_b128 v[228:231], v143 offset:52224
	ds_read_b128 v[232:235], v143 offset:53248
	ds_read_b128 v[236:239], v143 offset:54272
	ds_read_b128 v[240:243], v143 offset:55296
	ds_read_b128 v[244:247], v143 offset:56320
	global_load_lds_dwordx4 v[140:141], off
	s_add_i32 m0, s30, 0x2000
	s_add_u32 s28, s28, 0x40080
	v_lshl_add_u64 v[140:141], v[152:153], 0, s[72:73]
	s_addc_u32 s29, s29, 0
	s_add_i32 s30, s63, s36
	global_load_lds_dwordx4 v[140:141], off
	v_lshl_add_u64 v[140:141], s[28:29], 0, v[0:1]
	s_mov_b32 m0, s30
	s_nop 0
	global_load_lds_dwordx4 v[140:141], off
	v_lshl_add_u64 v[140:141], s[28:29], 0, v[134:135]
	s_add_i32 m0, s30, 0x2000
	s_nop 0
	global_load_lds_dwordx4 v[140:141], off
	v_lshl_add_u64 v[140:141], v[190:191], 0, s[72:73]
	s_mov_b32 m0, s50
	s_nop 0
	global_load_lds_dwordx4 v[140:141], off
	v_lshl_add_u64 v[140:141], v[248:249], 0, s[72:73]
	s_mov_b32 m0, s56
	s_nop 0
	global_load_lds_dwordx4 v[140:141], off
	s_waitcnt vmcnt(8)
	s_waitcnt lgkmcnt(0)
	s_barrier
	s_waitcnt lgkmcnt(0)
	v_mfma_f32_16x16x32_bf16 v[62:65], v[144:147], v[186:189], v[62:65]
	v_mfma_f32_16x16x32_bf16 v[58:61], v[162:165], v[186:189], v[58:61]
	v_mfma_f32_16x16x32_bf16 v[46:49], v[144:147], v[224:227], v[46:49]
	v_mfma_f32_16x16x32_bf16 v[42:45], v[162:165], v[224:227], v[42:45]
	v_mfma_f32_16x16x32_bf16 v[30:33], v[144:147], v[232:235], v[30:33]
	v_mfma_f32_16x16x32_bf16 v[26:29], v[162:165], v[232:235], v[26:29]
	v_mfma_f32_16x16x32_bf16 v[14:17], v[144:147], v[240:243], v[14:17]
	v_mfma_f32_16x16x32_bf16 v[10:13], v[162:165], v[240:243], v[10:13]
	v_mfma_f32_16x16x32_bf16 v[62:65], v[148:151], v[220:223], v[62:65]
	v_mfma_f32_16x16x32_bf16 v[58:61], v[166:169], v[220:223], v[58:61]
	v_mfma_f32_16x16x32_bf16 v[46:49], v[148:151], v[228:231], v[46:49]
	v_mfma_f32_16x16x32_bf16 v[42:45], v[166:169], v[228:231], v[42:45]
	v_mfma_f32_16x16x32_bf16 v[30:33], v[148:151], v[236:239], v[30:33]
	v_mfma_f32_16x16x32_bf16 v[26:29], v[166:169], v[236:239], v[26:29]
	v_mfma_f32_16x16x32_bf16 v[14:17], v[148:151], v[244:247], v[14:17]
	v_mfma_f32_16x16x32_bf16 v[10:13], v[166:169], v[244:247], v[10:13]
	v_mfma_f32_16x16x32_bf16 v[54:57], v[170:173], v[186:189], v[54:57]
	v_mfma_f32_16x16x32_bf16 v[50:53], v[178:181], v[186:189], v[50:53]
	v_mfma_f32_16x16x32_bf16 v[38:41], v[170:173], v[224:227], v[38:41]
	v_mfma_f32_16x16x32_bf16 v[34:37], v[178:181], v[224:227], v[34:37]
	v_mfma_f32_16x16x32_bf16 v[22:25], v[170:173], v[232:235], v[22:25]
	v_mfma_f32_16x16x32_bf16 v[18:21], v[178:181], v[232:235], v[18:21]
	v_mfma_f32_16x16x32_bf16 v[6:9], v[170:173], v[240:243], v[6:9]
	v_mfma_f32_16x16x32_bf16 v[2:5], v[178:181], v[240:243], v[2:5]
	v_mfma_f32_16x16x32_bf16 v[54:57], v[174:177], v[220:223], v[54:57]
	v_mfma_f32_16x16x32_bf16 v[50:53], v[182:185], v[220:223], v[50:53]
	v_mfma_f32_16x16x32_bf16 v[38:41], v[174:177], v[228:231], v[38:41]
	v_mfma_f32_16x16x32_bf16 v[34:37], v[182:185], v[228:231], v[34:37]
	v_mfma_f32_16x16x32_bf16 v[22:25], v[174:177], v[236:239], v[22:25]
	v_mfma_f32_16x16x32_bf16 v[18:21], v[182:185], v[236:239], v[18:21]
	v_mfma_f32_16x16x32_bf16 v[6:9], v[174:177], v[244:247], v[6:9]
	v_mfma_f32_16x16x32_bf16 v[2:5], v[182:185], v[244:247], v[2:5]
	s_barrier
	s_add_u32 s26, s26, 0x100
	s_addc_u32 s27, s27, 0
	s_add_u32 s71, s71, 0x100
	s_addc_u32 s74, s74, 0
	s_cmp_ge_i32 s75, s47
	s_mov_b32 s28, s75
	s_cbranch_scc0 .LBB0_577
	s_mov_b32 s63, 0x8000
	s_movk_i32 s71, 0x2c00

.LBB0_916:
	s_add_i32 s58, s20, 2
	s_add_u32 s59, s18, 0x80
	s_addc_u32 s21, s19, 0
	s_add_i32 s62, 0, 0x10000
	s_cmp_eq_u32 s43, s20
	s_cselect_b32 s21, s7, s21
	s_cselect_b32 s20, s6, s59
	s_cselect_b32 s61, s17, s57
	s_cselect_b32 s60, s16, s56
	s_add_i32 s59, 0, 0x14000
	v_add_u32_e32 v150, s62, v136
	v_add_u32_e32 v158, s59, v136
	ds_read_b128 v[138:141], v150
	ds_read_b128 v[142:145], v150 offset:1024
	ds_read_b128 v[146:149], v150 offset:2048
	ds_read_b128 v[150:153], v150 offset:3072
	ds_read_b128 v[160:163], v158
	ds_read_b128 v[164:167], v158 offset:1024
	ds_read_b128 v[168:171], v158 offset:2048
	ds_read_b128 v[172:175], v158 offset:3072
	v_lshl_add_u64 v[188:189], s[18:19], 0, v[132:133]
	s_add_i32 m0, s30, 0xc000
	ds_read_b128 v[176:179], v137
	ds_read_b128 v[180:183], v137 offset:1024
	ds_read_b128 v[184:187], v137 offset:2048
	ds_read_b128 v[218:221], v137 offset:3072
	ds_read_b128 v[222:225], v137 offset:4096
	ds_read_b128 v[226:229], v137 offset:5120
	ds_read_b128 v[230:233], v137 offset:6144
	ds_read_b128 v[234:237], v137 offset:7168
	global_load_lds_dwordx4 v[188:189], off
	v_lshl_add_u64 v[188:189], s[18:19], 0, v[134:135]
	s_add_i32 m0, s30, 0xe000
	s_nop 0
	global_load_lds_dwordx4 v[188:189], off
	s_waitcnt vmcnt(8)
	s_waitcnt lgkmcnt(0)
	s_barrier
	s_waitcnt lgkmcnt(0)
	v_mfma_f32_16x16x32_bf16 v[126:129], v[138:141], v[176:179], v[126:129]
	v_mfma_f32_16x16x32_bf16 v[122:125], v[146:149], v[176:179], v[122:125]
	v_mfma_f32_16x16x32_bf16 v[110:113], v[138:141], v[184:187], v[110:113]
	v_mfma_f32_16x16x32_bf16 v[106:109], v[146:149], v[184:187], v[106:109]
	v_mfma_f32_16x16x32_bf16 v[94:97], v[138:141], v[222:225], v[94:97]
	v_mfma_f32_16x16x32_bf16 v[90:93], v[146:149], v[222:225], v[90:93]
	v_mfma_f32_16x16x32_bf16 v[78:81], v[138:141], v[230:233], v[78:81]
	v_mfma_f32_16x16x32_bf16 v[74:77], v[146:149], v[230:233], v[74:77]
	v_mfma_f32_16x16x32_bf16 v[126:129], v[142:145], v[180:183], v[126:129]
	v_mfma_f32_16x16x32_bf16 v[122:125], v[150:153], v[180:183], v[122:125]
	v_mfma_f32_16x16x32_bf16 v[110:113], v[142:145], v[218:221], v[110:113]
	v_mfma_f32_16x16x32_bf16 v[106:109], v[150:153], v[218:221], v[106:109]
	v_mfma_f32_16x16x32_bf16 v[94:97], v[142:145], v[226:229], v[94:97]
	v_mfma_f32_16x16x32_bf16 v[90:93], v[150:153], v[226:229], v[90:93]
	v_mfma_f32_16x16x32_bf16 v[78:81], v[142:145], v[234:237], v[78:81]
	v_mfma_f32_16x16x32_bf16 v[74:77], v[150:153], v[234:237], v[74:77]
	v_mfma_f32_16x16x32_bf16 v[118:121], v[160:163], v[176:179], v[118:121]
	v_mfma_f32_16x16x32_bf16 v[114:117], v[168:171], v[176:179], v[114:117]
	v_mfma_f32_16x16x32_bf16 v[102:105], v[160:163], v[184:187], v[102:105]
	v_mfma_f32_16x16x32_bf16 v[98:101], v[168:171], v[184:187], v[98:101]
	v_mfma_f32_16x16x32_bf16 v[86:89], v[160:163], v[222:225], v[86:89]
	v_mfma_f32_16x16x32_bf16 v[82:85], v[168:171], v[222:225], v[82:85]
	v_mfma_f32_16x16x32_bf16 v[70:73], v[160:163], v[230:233], v[70:73]
	v_mfma_f32_16x16x32_bf16 v[66:69], v[168:171], v[230:233], v[66:69]
	v_mfma_f32_16x16x32_bf16 v[118:121], v[164:167], v[180:183], v[118:121]
	v_mfma_f32_16x16x32_bf16 v[114:117], v[172:175], v[180:183], v[114:117]
	v_mfma_f32_16x16x32_bf16 v[102:105], v[164:167], v[218:221], v[102:105]
	v_mfma_f32_16x16x32_bf16 v[98:101], v[172:175], v[218:221], v[98:101]
	v_mfma_f32_16x16x32_bf16 v[86:89], v[164:167], v[226:229], v[86:89]
	v_mfma_f32_16x16x32_bf16 v[82:85], v[172:175], v[226:229], v[82:85]
	v_mfma_f32_16x16x32_bf16 v[70:73], v[164:167], v[234:237], v[70:73]
	v_mfma_f32_16x16x32_bf16 v[66:69], v[172:175], v[234:237], v[66:69]
	s_barrier
	s_add_i32 s62, s62, s27
	v_lshl_add_u64 v[188:189], s[60:61], 0, v[0:1]
	s_mov_b32 m0, s62
	ds_read_b128 v[176:179], v137 offset:16384
	ds_read_b128 v[180:183], v137 offset:17408
	ds_read_b128 v[184:187], v137 offset:18432
	ds_read_b128 v[218:221], v137 offset:19456
	ds_read_b128 v[222:225], v137 offset:20480
	ds_read_b128 v[226:229], v137 offset:21504
	ds_read_b128 v[230:233], v137 offset:22528
	ds_read_b128 v[234:237], v137 offset:23552
	global_load_lds_dwordx4 v[188:189], off
	s_add_i32 m0, s62, 0x2000
	v_lshl_add_u64 v[190:191], s[60:61], 0, v[130:131]
	s_add_u32 s60, s60, s88
	s_addc_u32 s61, s61, 0
	s_add_i32 s59, s59, s27
	global_load_lds_dwordx4 v[190:191], off
	v_lshl_add_u64 v[238:239], s[60:61], 0, v[0:1]
	s_mov_b32 m0, s59
	v_lshl_add_u64 v[240:241], s[60:61], 0, v[130:131]
	global_load_lds_dwordx4 v[238:239], off
	s_add_i32 m0, s59, 0x2000
	v_lshl_add_u64 v[242:243], s[20:21], 0, v[0:1]
	global_load_lds_dwordx4 v[240:241], off
	s_mov_b32 m0, s30
	v_lshl_add_u64 v[244:245], s[20:21], 0, v[130:131]
	global_load_lds_dwordx4 v[242:243], off
	s_mov_b32 m0, s31
	s_nop 0
	global_load_lds_dwordx4 v[244:245], off
	s_waitcnt vmcnt(8)
	s_waitcnt lgkmcnt(0)
	s_barrier
	s_waitcnt lgkmcnt(0)
	v_mfma_f32_16x16x32_bf16 v[62:65], v[138:141], v[176:179], v[62:65]
	v_mfma_f32_16x16x32_bf16 v[58:61], v[146:149], v[176:179], v[58:61]
	v_mfma_f32_16x16x32_bf16 v[46:49], v[138:141], v[184:187], v[46:49]
	v_mfma_f32_16x16x32_bf16 v[42:45], v[146:149], v[184:187], v[42:45]
	v_mfma_f32_16x16x32_bf16 v[30:33], v[138:141], v[222:225], v[30:33]
	v_mfma_f32_16x16x32_bf16 v[26:29], v[146:149], v[222:225], v[26:29]
	v_mfma_f32_16x16x32_bf16 v[14:17], v[138:141], v[230:233], v[14:17]
	v_mfma_f32_16x16x32_bf16 v[10:13], v[146:149], v[230:233], v[10:13]
	v_mfma_f32_16x16x32_bf16 v[62:65], v[142:145], v[180:183], v[62:65]
	v_mfma_f32_16x16x32_bf16 v[58:61], v[150:153], v[180:183], v[58:61]
	v_mfma_f32_16x16x32_bf16 v[46:49], v[142:145], v[218:221], v[46:49]
	v_mfma_f32_16x16x32_bf16 v[42:45], v[150:153], v[218:221], v[42:45]
	v_mfma_f32_16x16x32_bf16 v[30:33], v[142:145], v[226:229], v[30:33]
	v_mfma_f32_16x16x32_bf16 v[26:29], v[150:153], v[226:229], v[26:29]
	v_mfma_f32_16x16x32_bf16 v[14:17], v[142:145], v[234:237], v[14:17]
	v_mfma_f32_16x16x32_bf16 v[10:13], v[150:153], v[234:237], v[10:13]
	v_mfma_f32_16x16x32_bf16 v[54:57], v[160:163], v[176:179], v[54:57]
	v_mfma_f32_16x16x32_bf16 v[50:53], v[168:171], v[176:179], v[50:53]
	v_mfma_f32_16x16x32_bf16 v[38:41], v[160:163], v[184:187], v[38:41]
	v_mfma_f32_16x16x32_bf16 v[34:37], v[168:171], v[184:187], v[34:37]
	v_mfma_f32_16x16x32_bf16 v[22:25], v[160:163], v[222:225], v[22:25]
	v_mfma_f32_16x16x32_bf16 v[18:21], v[168:171], v[222:225], v[18:21]
	v_mfma_f32_16x16x32_bf16 v[6:9], v[160:163], v[230:233], v[6:9]
	v_mfma_f32_16x16x32_bf16 v[2:5], v[168:171], v[230:233], v[2:5]
	v_mfma_f32_16x16x32_bf16 v[54:57], v[164:167], v[180:183], v[54:57]
	v_mfma_f32_16x16x32_bf16 v[50:53], v[172:175], v[180:183], v[50:53]
	v_mfma_f32_16x16x32_bf16 v[38:41], v[164:167], v[218:221], v[38:41]
	v_mfma_f32_16x16x32_bf16 v[34:37], v[172:175], v[218:221], v[34:37]
	v_mfma_f32_16x16x32_bf16 v[22:25], v[164:167], v[226:229], v[22:25]
	v_mfma_f32_16x16x32_bf16 v[18:21], v[172:175], v[226:229], v[18:21]
	v_mfma_f32_16x16x32_bf16 v[6:9], v[164:167], v[234:237], v[6:9]
	v_mfma_f32_16x16x32_bf16 v[2:5], v[172:175], v[234:237], v[2:5]
	s_barrier
	s_add_i32 s59, 0, 0x18000
	s_add_i32 s60, 0, 0x1c000
	v_add_u32_e32 v150, s59, v136
	v_add_u32_e32 v158, s60, v136
	ds_read_b128 v[138:141], v150
	ds_read_b128 v[142:145], v150 offset:1024
	ds_read_b128 v[146:149], v150 offset:2048
	ds_read_b128 v[150:153], v150 offset:3072
	ds_read_b128 v[160:163], v158
	ds_read_b128 v[164:167], v158 offset:1024
	ds_read_b128 v[168:171], v158 offset:2048
	ds_read_b128 v[172:175], v158 offset:3072
	s_add_u32 s20, s20, s88
	s_addc_u32 s21, s21, 0
	s_mov_b32 m0, s34
	v_lshl_add_u64 v[246:247], s[20:21], 0, v[0:1]
	ds_read_b128 v[176:179], v137 offset:32768
	ds_read_b128 v[180:183], v137 offset:33792
	ds_read_b128 v[184:187], v137 offset:34816
	ds_read_b128 v[218:221], v137 offset:35840
	ds_read_b128 v[222:225], v137 offset:36864
	ds_read_b128 v[226:229], v137 offset:37888
	ds_read_b128 v[230:233], v137 offset:38912
	ds_read_b128 v[234:237], v137 offset:39936
	global_load_lds_dwordx4 v[246:247], off
	v_lshl_add_u64 v[246:247], s[20:21], 0, v[130:131]
	s_mov_b32 m0, s35
	s_nop 0
	global_load_lds_dwordx4 v[246:247], off
	s_waitcnt vmcnt(8)
	s_waitcnt lgkmcnt(0)
	s_barrier
	s_waitcnt lgkmcnt(0)
	v_mfma_f32_16x16x32_bf16 v[126:129], v[138:141], v[176:179], v[126:129]
	v_mfma_f32_16x16x32_bf16 v[122:125], v[146:149], v[176:179], v[122:125]
	v_mfma_f32_16x16x32_bf16 v[110:113], v[138:141], v[184:187], v[110:113]
	v_mfma_f32_16x16x32_bf16 v[106:109], v[146:149], v[184:187], v[106:109]
	v_mfma_f32_16x16x32_bf16 v[94:97], v[138:141], v[222:225], v[94:97]
	v_mfma_f32_16x16x32_bf16 v[90:93], v[146:149], v[222:225], v[90:93]
	v_mfma_f32_16x16x32_bf16 v[78:81], v[138:141], v[230:233], v[78:81]
	v_mfma_f32_16x16x32_bf16 v[74:77], v[146:149], v[230:233], v[74:77]
	v_mfma_f32_16x16x32_bf16 v[126:129], v[142:145], v[180:183], v[126:129]
	v_mfma_f32_16x16x32_bf16 v[122:125], v[150:153], v[180:183], v[122:125]
	v_mfma_f32_16x16x32_bf16 v[110:113], v[142:145], v[218:221], v[110:113]
	v_mfma_f32_16x16x32_bf16 v[106:109], v[150:153], v[218:221], v[106:109]
	v_mfma_f32_16x16x32_bf16 v[94:97], v[142:145], v[226:229], v[94:97]
	v_mfma_f32_16x16x32_bf16 v[90:93], v[150:153], v[226:229], v[90:93]
	v_mfma_f32_16x16x32_bf16 v[78:81], v[142:145], v[234:237], v[78:81]
	v_mfma_f32_16x16x32_bf16 v[74:77], v[150:153], v[234:237], v[74:77]
	v_mfma_f32_16x16x32_bf16 v[118:121], v[160:163], v[176:179], v[118:121]
	v_mfma_f32_16x16x32_bf16 v[114:117], v[168:171], v[176:179], v[114:117]
	v_mfma_f32_16x16x32_bf16 v[102:105], v[160:163], v[184:187], v[102:105]
	v_mfma_f32_16x16x32_bf16 v[98:101], v[168:171], v[184:187], v[98:101]
	v_mfma_f32_16x16x32_bf16 v[86:89], v[160:163], v[222:225], v[86:89]
	v_mfma_f32_16x16x32_bf16 v[82:85], v[168:171], v[222:225], v[82:85]
	v_mfma_f32_16x16x32_bf16 v[70:73], v[160:163], v[230:233], v[70:73]
	v_mfma_f32_16x16x32_bf16 v[66:69], v[168:171], v[230:233], v[66:69]
	v_mfma_f32_16x16x32_bf16 v[118:121], v[164:167], v[180:183], v[118:121]
	v_mfma_f32_16x16x32_bf16 v[114:117], v[172:175], v[180:183], v[114:117]
	v_mfma_f32_16x16x32_bf16 v[102:105], v[164:167], v[218:221], v[102:105]
	v_mfma_f32_16x16x32_bf16 v[98:101], v[172:175], v[218:221], v[98:101]
	v_mfma_f32_16x16x32_bf16 v[86:89], v[164:167], v[226:229], v[86:89]
	v_mfma_f32_16x16x32_bf16 v[82:85], v[172:175], v[226:229], v[82:85]
	v_mfma_f32_16x16x32_bf16 v[70:73], v[164:167], v[234:237], v[70:73]
	v_mfma_f32_16x16x32_bf16 v[66:69], v[172:175], v[234:237], v[66:69]
	s_barrier
	s_add_i32 s20, s59, s27
	v_lshl_add_u64 v[188:189], v[188:189], 0, s[72:73]
	s_mov_b32 m0, s20
	ds_read_b128 v[176:179], v137 offset:49152
	ds_read_b128 v[180:183], v137 offset:50176
	ds_read_b128 v[184:187], v137 offset:51200
	ds_read_b128 v[218:221], v137 offset:52224
	ds_read_b128 v[222:225], v137 offset:53248
	ds_read_b128 v[226:229], v137 offset:54272
	ds_read_b128 v[230:233], v137 offset:55296
	ds_read_b128 v[234:237], v137 offset:56320
	global_load_lds_dwordx4 v[188:189], off
	v_lshl_add_u64 v[188:189], v[190:191], 0, s[72:73]
	s_add_i32 m0, s20, 0x2000
	s_add_i32 s20, s60, s27
	global_load_lds_dwordx4 v[188:189], off
	v_lshl_add_u64 v[188:189], v[238:239], 0, s[72:73]
	s_mov_b32 m0, s20
	s_nop 0
	global_load_lds_dwordx4 v[188:189], off
	v_lshl_add_u64 v[188:189], v[240:241], 0, s[72:73]
	s_add_i32 m0, s20, 0x2000
	s_nop 0
	global_load_lds_dwordx4 v[188:189], off
	v_lshl_add_u64 v[188:189], v[242:243], 0, s[72:73]
	s_mov_b32 m0, s38
	s_nop 0
	global_load_lds_dwordx4 v[188:189], off
	v_lshl_add_u64 v[188:189], v[244:245], 0, s[72:73]
	s_mov_b32 m0, s39
	s_nop 0
	global_load_lds_dwordx4 v[188:189], off
	s_waitcnt vmcnt(8)
	s_waitcnt lgkmcnt(0)
	s_barrier
	s_waitcnt lgkmcnt(0)
	v_mfma_f32_16x16x32_bf16 v[62:65], v[138:141], v[176:179], v[62:65]
	v_mfma_f32_16x16x32_bf16 v[58:61], v[146:149], v[176:179], v[58:61]
	v_mfma_f32_16x16x32_bf16 v[46:49], v[138:141], v[184:187], v[46:49]
	v_mfma_f32_16x16x32_bf16 v[42:45], v[146:149], v[184:187], v[42:45]
	v_mfma_f32_16x16x32_bf16 v[30:33], v[138:141], v[222:225], v[30:33]
	v_mfma_f32_16x16x32_bf16 v[26:29], v[146:149], v[222:225], v[26:29]
	v_mfma_f32_16x16x32_bf16 v[14:17], v[138:141], v[230:233], v[14:17]
	v_mfma_f32_16x16x32_bf16 v[10:13], v[146:149], v[230:233], v[10:13]
	v_mfma_f32_16x16x32_bf16 v[62:65], v[142:145], v[180:183], v[62:65]
	v_mfma_f32_16x16x32_bf16 v[58:61], v[150:153], v[180:183], v[58:61]
	v_mfma_f32_16x16x32_bf16 v[46:49], v[142:145], v[218:221], v[46:49]
	v_mfma_f32_16x16x32_bf16 v[42:45], v[150:153], v[218:221], v[42:45]
	v_mfma_f32_16x16x32_bf16 v[30:33], v[142:145], v[226:229], v[30:33]
	v_mfma_f32_16x16x32_bf16 v[26:29], v[150:153], v[226:229], v[26:29]
	v_mfma_f32_16x16x32_bf16 v[14:17], v[142:145], v[234:237], v[14:17]
	v_mfma_f32_16x16x32_bf16 v[10:13], v[150:153], v[234:237], v[10:13]
	v_mfma_f32_16x16x32_bf16 v[54:57], v[160:163], v[176:179], v[54:57]
	v_mfma_f32_16x16x32_bf16 v[50:53], v[168:171], v[176:179], v[50:53]
	v_mfma_f32_16x16x32_bf16 v[38:41], v[160:163], v[184:187], v[38:41]
	v_mfma_f32_16x16x32_bf16 v[34:37], v[168:171], v[184:187], v[34:37]
	v_mfma_f32_16x16x32_bf16 v[22:25], v[160:163], v[222:225], v[22:25]
	v_mfma_f32_16x16x32_bf16 v[18:21], v[168:171], v[222:225], v[18:21]
	v_mfma_f32_16x16x32_bf16 v[6:9], v[160:163], v[230:233], v[6:9]
	v_mfma_f32_16x16x32_bf16 v[2:5], v[168:171], v[230:233], v[2:5]
	v_mfma_f32_16x16x32_bf16 v[54:57], v[164:167], v[180:183], v[54:57]
	v_mfma_f32_16x16x32_bf16 v[50:53], v[172:175], v[180:183], v[50:53]
	v_mfma_f32_16x16x32_bf16 v[38:41], v[164:167], v[218:221], v[38:41]
	v_mfma_f32_16x16x32_bf16 v[34:37], v[172:175], v[218:221], v[34:37]
	v_mfma_f32_16x16x32_bf16 v[22:25], v[164:167], v[226:229], v[22:25]
	v_mfma_f32_16x16x32_bf16 v[18:21], v[172:175], v[226:229], v[18:21]
	v_mfma_f32_16x16x32_bf16 v[6:9], v[164:167], v[234:237], v[6:9]
	v_mfma_f32_16x16x32_bf16 v[2:5], v[172:175], v[234:237], v[2:5]
	s_barrier
	s_add_u32 s18, s18, 0x100
	s_addc_u32 s19, s19, 0
	s_add_u32 s56, s56, 0x100
	s_addc_u32 s57, s57, 0
	s_cmp_ge_i32 s58, s40
	s_mov_b32 s20, s58
	s_cbranch_scc0 .LBB0_916
